# K-loop back edge rotated: loop-back barrier is the loop head, branch executes before the barrier, exit path has its own barrier copy
# baseline (speedup 1.0000x reference)
; #define PG8_STAGE(bufoff, gbase, voff) do { _Pragma("unroll") for (int _i = 0; _i < 2; ++_i) \
;         __builtin_amdgcn_global_load_lds((const unsigned*)((const char*)(gbase) + (voff)[_i]), (LAS unsigned*)(lds + (bufoff) + ldsw + _i * 8192), 16, 0, 0); } while (0)
; #define PG8_LDA(dst, b, h) do { _Pragma("unroll") for (int m = 0; m < 4; ++m) _Pragma("unroll") for (int k = 0; k < 2; ++k) dst[m][k] = *(const LAS bf16x8*)(lds + PG8_SA(b, h) + aoff + m * 2048 + k * 1024); } while (0)
; #define PG8_LDB(dst, b, h) do { _Pragma("unroll") for (int n = 0; n < 2; ++n) _Pragma("unroll") for (int k = 0; k < 2; ++k) dst[n][k] = *(const LAS bf16x8*)(lds + PG8_SB(b, h) + boff + n * 2048 + k * 1024); } while (0)
; #define PG8_WAIT_V(n) asm volatile("s_waitcnt vmcnt(" #n ")" ::: "memory")
; #define PG8_BAR __builtin_amdgcn_s_barrier()
; template <class Epi>
; __device__ __forceinline__ void gemm_phase(LAS unsigned char* lds, const Gemm g, const StaticOrder& S, const Epi& E) {
;     ...
;         const bool has_next = S.next(ui + 1, nxt);
;         const char* nA = has_next ? (const char*)g.A + (size_t)nxt.pm * tstepA : cA; const char* nB = has_next ? (const char*)g.Bt + (size_t)nxt.pn * tstepB : cB;
;         for (int t = 0; t < nt; t += 2) {
;             const bool last = (t == nt - 2);
;             const char* a1 = cA + (size_t)(t + 1) * kstep;
;             const char* a2 = last ? nA : cA + (size_t)(t + 2) * kstep; const char* b2 = last ? nB : cB + (size_t)(t + 2) * kstep;
;             const char* a3 = a2 + kstep; const char* b3 = b2 + kstep;
;             PG8_LDB(B0, 0, 0); PG8_SCHED; PG8_LDA(At, 0, 0); PG8_STAGE(PG8_SA(1, 1), a1 + hstepA, voffA);
;             PG8_WAIT_L(8); PG8_BAR; PG8_WAIT_L(0); PG8_MMA(0, 0, At, B0); PG8_BAR; PG8_SCHED;
;             PG8_LDB(B1, 0, 1); PG8_STAGE(PG8_SB(0, 0), b2, voffB);
;             PG8_BAR; PG8_WAIT_L(0); PG8_MMA(0, 1, At, B1); PG8_BAR;
;             PG8_LDA(At, 0, 1); PG8_STAGE(PG8_SA(0, 0), a2, voffA);
;             PG8_BAR; PG8_WAIT_L(0); PG8_MMA(1, 0, At, B0); PG8_BAR; PG8_SCHED;
;             PG8_STAGE(PG8_SB(0, 1), b2 + hstepB, voffB);
;             PG8_WAIT_V(6); PG8_BAR; PG8_MMA(1, 1, At, B1); PG8_BAR;
;             PG8_LDB(B0, 1, 0); PG8_SCHED; PG8_LDA(At, 1, 0); PG8_STAGE(PG8_SA(0, 1), a2 + hstepA, voffA);
;             PG8_WAIT_L(8); PG8_BAR; PG8_WAIT_L(0); PG8_MMA(0, 0, At, B0); PG8_BAR; PG8_SCHED;
.LBB0_140:
	v_mov_b64_e32 v[0:1], 0x800
	s_ashr_i32 s15, s14, 31
	v_cmp_lt_i64_e32 vcc, s[16:17], v[0:1]
	s_lshl_b64 s[16:17], s[14:15], 20
	v_readlane_b32 s18, v252, 53
	v_readlane_b32 s19, v252, 54
	s_add_u32 s16, s18, s16
	s_addc_u32 s17, s19, s17
	s_and_b64 s[18:19], vcc, exec
	s_cselect_b32 s15, s17, s23
	s_cselect_b32 s49, s16, s22
	s_ashr_i32 s5, s4, 31
	s_lshl_b64 s[18:19], s[4:5], 20
	s_add_u32 s18, s34, s18
	s_addc_u32 s19, s35, s19
	s_and_b64 s[26:27], vcc, exec
	s_cselect_b32 s5, s19, s25
	s_cselect_b32 s50, s18, s24
	s_add_u32 s22, s22, 0x84000
	s_addc_u32 s23, s23, 0
	s_add_u32 s51, s24, 0x8000
	s_addc_u32 s52, s25, 0
	s_mov_b32 s54, -2
	s_add_u32 s24, s22, 0xfff84000
	s_addc_u32 s25, s23, -1
	s_cmp_eq_u32 s54, 28
	s_cselect_b32 s28, s49, s24
	s_cselect_b32 s29, s15, s25
	s_cselect_b32 s24, s50, s51
	s_cselect_b32 s25, s5, s52
	s_add_u32 s26, s28, 0x4000
	s_addc_u32 s27, s29, 0
	s_add_i32 m0, s37, 0xc000
	v_lshl_add_u64 v[188:189], s[22:23], 0, v[128:129]
	global_load_lds_dwordx4 v[188:189], off
	s_add_i32 m0, s37, 0xe000
	v_lshl_add_u64 v[188:189], s[22:23], 0, v[130:131]
	global_load_lds_dwordx4 v[188:189], off
	s_mov_b32 s55, 0x10000
	v_add_u32_e32 v148, s55, v134
	ds_read_b128 v[136:139], v148
	ds_read_b128 v[144:147], v148 offset:2048
	ds_read_b128 v[140:143], v148 offset:1024
	ds_read_b128 v[148:151], v148 offset:3072
	ds_read_b128 v[156:159], v135
	ds_read_b128 v[164:167], v135 offset:2048
	ds_read_b128 v[172:175], v135 offset:4096
	ds_read_b128 v[180:183], v135 offset:6144
	ds_read_b128 v[160:163], v135 offset:1024
	ds_read_b128 v[168:171], v135 offset:3072
	ds_read_b128 v[176:179], v135 offset:5120
	ds_read_b128 v[184:187], v135 offset:7168
	s_mov_b32 s58, 0x14000
	s_add_i32 s55, s55, s36
	v_add_u32_e32 v152, s58, v134
	ds_read_b128 v[188:191], v152
	ds_read_b128 v[196:199], v152 offset:2048
	ds_read_b128 v[192:195], v152 offset:1024
	ds_read_b128 v[200:203], v152 offset:3072
	s_waitcnt lgkmcnt(0)
	s_barrier
	v_mfma_f32_16x16x32_bf16 v[124:127], v[136:139], v[156:159], 0
	s_setprio 1
	v_mfma_f32_16x16x32_bf16 v[120:123], v[144:147], v[156:159], 0
	v_mfma_f32_16x16x32_bf16 v[108:111], v[136:139], v[164:167], 0
	v_mfma_f32_16x16x32_bf16 v[104:107], v[144:147], v[164:167], 0
	v_mfma_f32_16x16x32_bf16 v[92:95], v[136:139], v[172:175], 0
	v_mfma_f32_16x16x32_bf16 v[88:91], v[144:147], v[172:175], 0
	v_mfma_f32_16x16x32_bf16 v[76:79], v[136:139], v[180:183], 0
	v_mfma_f32_16x16x32_bf16 v[72:75], v[144:147], v[180:183], 0
	v_mfma_f32_16x16x32_bf16 v[124:127], v[140:143], v[160:163], v[124:127]
	v_mfma_f32_16x16x32_bf16 v[120:123], v[148:151], v[160:163], v[120:123]
	v_mfma_f32_16x16x32_bf16 v[108:111], v[140:143], v[168:171], v[108:111]
	v_mfma_f32_16x16x32_bf16 v[104:107], v[148:151], v[168:171], v[104:107]
	v_mfma_f32_16x16x32_bf16 v[92:95], v[140:143], v[176:179], v[92:95]
	v_mfma_f32_16x16x32_bf16 v[88:91], v[148:151], v[176:179], v[88:91]
	v_mfma_f32_16x16x32_bf16 v[76:79], v[140:143], v[184:187], v[76:79]
	v_mfma_f32_16x16x32_bf16 v[72:75], v[148:151], v[184:187], v[72:75]
	v_mfma_f32_16x16x32_bf16 v[116:119], v[188:191], v[156:159], 0
	v_mfma_f32_16x16x32_bf16 v[112:115], v[196:199], v[156:159], 0
	v_mfma_f32_16x16x32_bf16 v[100:103], v[188:191], v[164:167], 0
	v_mfma_f32_16x16x32_bf16 v[96:99], v[196:199], v[164:167], 0
	v_mfma_f32_16x16x32_bf16 v[84:87], v[188:191], v[172:175], 0
	v_mfma_f32_16x16x32_bf16 v[80:83], v[196:199], v[172:175], 0
	v_mfma_f32_16x16x32_bf16 v[68:71], v[188:191], v[180:183], 0
	v_mfma_f32_16x16x32_bf16 v[64:67], v[196:199], v[180:183], 0
	v_mfma_f32_16x16x32_bf16 v[116:119], v[192:195], v[160:163], v[116:119]
	v_mfma_f32_16x16x32_bf16 v[112:115], v[200:203], v[160:163], v[112:115]
	v_mfma_f32_16x16x32_bf16 v[100:103], v[192:195], v[168:171], v[100:103]
	v_mfma_f32_16x16x32_bf16 v[96:99], v[200:203], v[168:171], v[96:99]
	v_mfma_f32_16x16x32_bf16 v[84:87], v[192:195], v[176:179], v[84:87]
	v_mfma_f32_16x16x32_bf16 v[80:83], v[200:203], v[176:179], v[80:83]
	v_mfma_f32_16x16x32_bf16 v[68:71], v[192:195], v[184:187], v[68:71]
	s_setprio 0
	v_mfma_f32_16x16x32_bf16 v[64:67], v[200:203], v[184:187], v[64:67]
	s_barrier
	s_mov_b32 m0, s55
	v_lshl_add_u64 v[204:205], s[24:25], 0, v[128:129]
	global_load_lds_dwordx4 v[204:205], off
	s_add_i32 m0, s55, 0x2000
	v_lshl_add_u64 v[204:205], s[24:25], 0, v[130:131]
	global_load_lds_dwordx4 v[204:205], off
	s_mov_b32 m0, s37
	v_lshl_add_u64 v[204:205], s[28:29], 0, v[128:129]
	global_load_lds_dwordx4 v[204:205], off
	s_mov_b32 m0, s38
	v_lshl_add_u64 v[204:205], s[28:29], 0, v[130:131]
	global_load_lds_dwordx4 v[204:205], off
	s_add_u32 s56, s24, 0x80000
	s_addc_u32 s57, s25, 0
	s_add_i32 s55, s58, s36
	s_mov_b32 m0, s55
	v_lshl_add_u64 v[204:205], s[56:57], 0, v[128:129]
	global_load_lds_dwordx4 v[204:205], off
	s_add_i32 m0, s55, 0x2000
	v_lshl_add_u64 v[204:205], s[56:57], 0, v[130:131]
	global_load_lds_dwordx4 v[204:205], off
	ds_read_b128 v[156:159], v135 offset:16384
	ds_read_b128 v[164:167], v135 offset:18432
	ds_read_b128 v[172:175], v135 offset:20480
	ds_read_b128 v[180:183], v135 offset:22528
	ds_read_b128 v[160:163], v135 offset:17408
	ds_read_b128 v[168:171], v135 offset:19456
	ds_read_b128 v[176:179], v135 offset:21504
	ds_read_b128 v[184:187], v135 offset:23552
	s_waitcnt vmcnt(6)
	s_waitcnt lgkmcnt(0)
	s_barrier
; #define PG8_STAGE(bufoff, gbase, voff) do { _Pragma("unroll") for (int _i = 0; _i < 2; ++_i) \
;         __builtin_amdgcn_global_load_lds((const unsigned*)((const char*)(gbase) + (voff)[_i]), (LAS unsigned*)(lds + (bufoff) + ldsw + _i * 8192), 16, 0, 0); } while (0)
; #define PG8_LDA(dst, b, h) do { _Pragma("unroll") for (int m = 0; m < 4; ++m) _Pragma("unroll") for (int k = 0; k < 2; ++k) dst[m][k] = *(const LAS bf16x8*)(lds + PG8_SA(b, h) + aoff + m * 2048 + k * 1024); } while (0)
; #define PG8_WAIT_V(n) asm volatile("s_waitcnt vmcnt(" #n ")" ::: "memory")
; #define PG8_WAIT_L(n) asm volatile("s_waitcnt lgkmcnt(" #n ")" ::: "memory")
; template <class Epi>
; __device__ __forceinline__ void gemm_phase(LAS unsigned char* lds, const Gemm g, const StaticOrder& S, const Epi& E) {
;     ...
;         for (int t = 0; t < nt; t += 2) {
;             const bool last = (t == nt - 2);
;             const char* a1 = cA + (size_t)(t + 1) * kstep;
;             const char* a2 = last ? nA : cA + (size_t)(t + 2) * kstep; const char* b2 = last ? nB : cB + (size_t)(t + 2) * kstep;
;             const char* a3 = a2 + kstep; const char* b3 = b2 + kstep;
;             PG8_LDB(B0, 0, 0); PG8_SCHED; PG8_LDA(At, 0, 0); PG8_STAGE(PG8_SA(1, 1), a1 + hstepA, voffA);
;             PG8_WAIT_L(8); PG8_BAR; PG8_WAIT_L(0); PG8_MMA(0, 0, At, B0); PG8_BAR; PG8_SCHED;
;             PG8_LDB(B1, 0, 1); PG8_STAGE(PG8_SB(0, 0), b2, voffB);
;             PG8_BAR; PG8_WAIT_L(0); PG8_MMA(0, 1, At, B1); PG8_BAR;
;             PG8_LDA(At, 0, 1); PG8_STAGE(PG8_SA(0, 0), a2, voffA);
;             PG8_BAR; PG8_WAIT_L(0); PG8_MMA(1, 0, At, B0); PG8_BAR; PG8_SCHED;
;             PG8_STAGE(PG8_SB(0, 1), b2 + hstepB, voffB);
;             PG8_WAIT_V(6); PG8_BAR; PG8_MMA(1, 1, At, B1); PG8_BAR;
;             PG8_LDB(B0, 1, 0); PG8_SCHED; PG8_LDA(At, 1, 0); PG8_STAGE(PG8_SA(0, 1), a2 + hstepA, voffA);
;             PG8_WAIT_L(8); PG8_BAR; PG8_WAIT_L(0); PG8_MMA(0, 0, At, B0); PG8_BAR; PG8_SCHED;
;             PG8_LDB(B1, 1, 1); PG8_STAGE(PG8_SB(1, 0), b3, voffB);
;             PG8_BAR; PG8_WAIT_L(0); PG8_MMA(0, 1, At, B1); PG8_BAR;
;             PG8_LDA(At, 1, 1); PG8_STAGE(PG8_SA(1, 0), a3, voffA);
;             PG8_BAR; PG8_WAIT_L(0); PG8_MMA(1, 0, At, B0); PG8_BAR; PG8_SCHED;
;             PG8_STAGE(PG8_SB(1, 1), b3 + hstepB, voffB);
;             PG8_WAIT_V(6); PG8_BAR; PG8_MMA(1, 1, At, B1); PG8_BAR;
	v_mfma_f32_16x16x32_bf16 v[60:63], v[136:139], v[156:159], 0
	s_setprio 1
	v_mfma_f32_16x16x32_bf16 v[56:59], v[144:147], v[156:159], 0
	v_mfma_f32_16x16x32_bf16 v[44:47], v[136:139], v[164:167], 0
	v_mfma_f32_16x16x32_bf16 v[40:43], v[144:147], v[164:167], 0
	v_mfma_f32_16x16x32_bf16 v[28:31], v[136:139], v[172:175], 0
	v_mfma_f32_16x16x32_bf16 v[24:27], v[144:147], v[172:175], 0
	v_mfma_f32_16x16x32_bf16 v[12:15], v[136:139], v[180:183], 0
	v_mfma_f32_16x16x32_bf16 v[8:11], v[144:147], v[180:183], 0
	v_mfma_f32_16x16x32_bf16 v[60:63], v[140:143], v[160:163], v[60:63]
	v_mfma_f32_16x16x32_bf16 v[56:59], v[148:151], v[160:163], v[56:59]
	v_mfma_f32_16x16x32_bf16 v[44:47], v[140:143], v[168:171], v[44:47]
	v_mfma_f32_16x16x32_bf16 v[40:43], v[148:151], v[168:171], v[40:43]
	v_mfma_f32_16x16x32_bf16 v[28:31], v[140:143], v[176:179], v[28:31]
	v_mfma_f32_16x16x32_bf16 v[24:27], v[148:151], v[176:179], v[24:27]
	v_mfma_f32_16x16x32_bf16 v[12:15], v[140:143], v[184:187], v[12:15]
	v_mfma_f32_16x16x32_bf16 v[8:11], v[148:151], v[184:187], v[8:11]
	v_mfma_f32_16x16x32_bf16 v[52:55], v[188:191], v[156:159], 0
	v_mfma_f32_16x16x32_bf16 v[48:51], v[196:199], v[156:159], 0
	s_add_i32 s55, 0, 0x18000
	v_add_u32_e32 v148, s55, v134
	v_mfma_f32_16x16x32_bf16 v[36:39], v[188:191], v[164:167], 0
	v_mfma_f32_16x16x32_bf16 v[32:35], v[196:199], v[164:167], 0
	v_mfma_f32_16x16x32_bf16 v[20:23], v[188:191], v[172:175], 0
	v_mfma_f32_16x16x32_bf16 v[16:19], v[196:199], v[172:175], 0
	v_mfma_f32_16x16x32_bf16 v[4:7], v[188:191], v[180:183], 0
	v_mfma_f32_16x16x32_bf16 v[0:3], v[196:199], v[180:183], 0
	v_mfma_f32_16x16x32_bf16 v[52:55], v[192:195], v[160:163], v[52:55]
	v_mfma_f32_16x16x32_bf16 v[48:51], v[200:203], v[160:163], v[48:51]
	v_mfma_f32_16x16x32_bf16 v[36:39], v[192:195], v[168:171], v[36:39]
	v_mfma_f32_16x16x32_bf16 v[32:35], v[200:203], v[168:171], v[32:35]
	v_mfma_f32_16x16x32_bf16 v[20:23], v[192:195], v[176:179], v[20:23]
	v_mfma_f32_16x16x32_bf16 v[16:19], v[200:203], v[176:179], v[16:19]
	v_mfma_f32_16x16x32_bf16 v[4:7], v[192:195], v[184:187], v[4:7]
	s_setprio 0
	v_mfma_f32_16x16x32_bf16 v[0:3], v[200:203], v[184:187], v[0:3]
	s_barrier
	s_add_u32 s28, s28, 0x80000
	s_addc_u32 s29, s29, 0
	s_mov_b32 m0, s39
	v_lshl_add_u64 v[188:189], s[28:29], 0, v[128:129]
	global_load_lds_dwordx4 v[188:189], off
	s_mov_b32 m0, s40
	v_lshl_add_u64 v[188:189], s[28:29], 0, v[130:131]
	global_load_lds_dwordx4 v[188:189], off
	ds_read_b128 v[136:139], v148
	ds_read_b128 v[144:147], v148 offset:2048
	ds_read_b128 v[140:143], v148 offset:1024
	ds_read_b128 v[148:151], v148 offset:3072
	ds_read_b128 v[156:159], v135 offset:32768
	ds_read_b128 v[164:167], v135 offset:34816
	ds_read_b128 v[172:175], v135 offset:36864
	ds_read_b128 v[180:183], v135 offset:38912
	ds_read_b128 v[160:163], v135 offset:33792
	ds_read_b128 v[168:171], v135 offset:35840
	ds_read_b128 v[176:179], v135 offset:37888
	ds_read_b128 v[184:187], v135 offset:39936
	s_mov_b32 s56, 0x1c000
	s_add_u32 s28, s24, 0x4000
	s_addc_u32 s29, s25, 0
	s_add_i32 s55, s55, s36
	v_add_u32_e32 v152, s56, v134
	ds_read_b128 v[188:191], v152
	ds_read_b128 v[196:199], v152 offset:2048
	ds_read_b128 v[192:195], v152 offset:1024
	ds_read_b128 v[200:203], v152 offset:3072
	s_waitcnt lgkmcnt(0)
	s_barrier
	v_mfma_f32_16x16x32_bf16 v[124:127], v[136:139], v[156:159], v[124:127]
	s_setprio 1
	v_mfma_f32_16x16x32_bf16 v[120:123], v[144:147], v[156:159], v[120:123]
	v_mfma_f32_16x16x32_bf16 v[108:111], v[136:139], v[164:167], v[108:111]
	v_mfma_f32_16x16x32_bf16 v[104:107], v[144:147], v[164:167], v[104:107]
	v_mfma_f32_16x16x32_bf16 v[92:95], v[136:139], v[172:175], v[92:95]
	v_mfma_f32_16x16x32_bf16 v[88:91], v[144:147], v[172:175], v[88:91]
	v_mfma_f32_16x16x32_bf16 v[76:79], v[136:139], v[180:183], v[76:79]
	v_mfma_f32_16x16x32_bf16 v[72:75], v[144:147], v[180:183], v[72:75]
	v_mfma_f32_16x16x32_bf16 v[124:127], v[140:143], v[160:163], v[124:127]
	v_mfma_f32_16x16x32_bf16 v[120:123], v[148:151], v[160:163], v[120:123]
	v_mfma_f32_16x16x32_bf16 v[108:111], v[140:143], v[168:171], v[108:111]
	v_mfma_f32_16x16x32_bf16 v[104:107], v[148:151], v[168:171], v[104:107]
	v_mfma_f32_16x16x32_bf16 v[92:95], v[140:143], v[176:179], v[92:95]
	v_mfma_f32_16x16x32_bf16 v[88:91], v[148:151], v[176:179], v[88:91]
	v_mfma_f32_16x16x32_bf16 v[76:79], v[140:143], v[184:187], v[76:79]
	v_mfma_f32_16x16x32_bf16 v[72:75], v[148:151], v[184:187], v[72:75]
	v_mfma_f32_16x16x32_bf16 v[116:119], v[188:191], v[156:159], v[116:119]
	v_mfma_f32_16x16x32_bf16 v[112:115], v[196:199], v[156:159], v[112:115]
	v_mfma_f32_16x16x32_bf16 v[100:103], v[188:191], v[164:167], v[100:103]
	v_mfma_f32_16x16x32_bf16 v[96:99], v[196:199], v[164:167], v[96:99]
	v_mfma_f32_16x16x32_bf16 v[84:87], v[188:191], v[172:175], v[84:87]
	v_mfma_f32_16x16x32_bf16 v[80:83], v[196:199], v[172:175], v[80:83]
	v_mfma_f32_16x16x32_bf16 v[68:71], v[188:191], v[180:183], v[68:71]
	v_mfma_f32_16x16x32_bf16 v[64:67], v[196:199], v[180:183], v[64:67]
	v_mfma_f32_16x16x32_bf16 v[116:119], v[192:195], v[160:163], v[116:119]
	v_mfma_f32_16x16x32_bf16 v[112:115], v[200:203], v[160:163], v[112:115]
	v_mfma_f32_16x16x32_bf16 v[100:103], v[192:195], v[168:171], v[100:103]
	v_mfma_f32_16x16x32_bf16 v[96:99], v[200:203], v[168:171], v[96:99]
	v_mfma_f32_16x16x32_bf16 v[84:87], v[192:195], v[176:179], v[84:87]
	v_mfma_f32_16x16x32_bf16 v[80:83], v[200:203], v[176:179], v[80:83]
	v_mfma_f32_16x16x32_bf16 v[68:71], v[192:195], v[184:187], v[68:71]
	s_setprio 0
	v_mfma_f32_16x16x32_bf16 v[64:67], v[200:203], v[184:187], v[64:67]
	s_barrier
; #define PG8_STAGE(bufoff, gbase, voff) do { _Pragma("unroll") for (int _i = 0; _i < 2; ++_i) \
;         __builtin_amdgcn_global_load_lds((const unsigned*)((const char*)(gbase) + (voff)[_i]), (LAS unsigned*)(lds + (bufoff) + ldsw + _i * 8192), 16, 0, 0); } while (0)
; #define PG8_LDA(dst, b, h) do { _Pragma("unroll") for (int m = 0; m < 4; ++m) _Pragma("unroll") for (int k = 0; k < 2; ++k) dst[m][k] = *(const LAS bf16x8*)(lds + PG8_SA(b, h) + aoff + m * 2048 + k * 1024); } while (0)
; #define PG8_WAIT_V(n) asm volatile("s_waitcnt vmcnt(" #n ")" ::: "memory")
; #define PG8_WAIT_L(n) asm volatile("s_waitcnt lgkmcnt(" #n ")" ::: "memory")
; template <class Epi>
; __device__ __forceinline__ void gemm_phase(LAS unsigned char* lds, const Gemm g, const StaticOrder& S, const Epi& E) {
;     ...
;         for (int t = 0; t < nt; t += 2) {
;             const bool last = (t == nt - 2);
;             const char* a1 = cA + (size_t)(t + 1) * kstep;
;             const char* a2 = last ? nA : cA + (size_t)(t + 2) * kstep; const char* b2 = last ? nB : cB + (size_t)(t + 2) * kstep;
;             const char* a3 = a2 + kstep; const char* b3 = b2 + kstep;
;             PG8_LDB(B0, 0, 0); PG8_SCHED; PG8_LDA(At, 0, 0); PG8_STAGE(PG8_SA(1, 1), a1 + hstepA, voffA);
;             PG8_WAIT_L(8); PG8_BAR; PG8_WAIT_L(0); PG8_MMA(0, 0, At, B0); PG8_BAR; PG8_SCHED;
;             PG8_LDB(B1, 0, 1); PG8_STAGE(PG8_SB(0, 0), b2, voffB);
;             PG8_BAR; PG8_WAIT_L(0); PG8_MMA(0, 1, At, B1); PG8_BAR;
;             PG8_LDA(At, 0, 1); PG8_STAGE(PG8_SA(0, 0), a2, voffA);
;             PG8_BAR; PG8_WAIT_L(0); PG8_MMA(1, 0, At, B0); PG8_BAR; PG8_SCHED;
;             PG8_STAGE(PG8_SB(0, 1), b2 + hstepB, voffB);
;             PG8_WAIT_V(6); PG8_BAR; PG8_MMA(1, 1, At, B1); PG8_BAR;
;             PG8_LDB(B0, 1, 0); PG8_SCHED; PG8_LDA(At, 1, 0); PG8_STAGE(PG8_SA(0, 1), a2 + hstepA, voffA);
;             PG8_WAIT_L(8); PG8_BAR; PG8_WAIT_L(0); PG8_MMA(0, 0, At, B0); PG8_BAR; PG8_SCHED;
;             PG8_LDB(B1, 1, 1); PG8_STAGE(PG8_SB(1, 0), b3, voffB);
;             PG8_BAR; PG8_WAIT_L(0); PG8_MMA(0, 1, At, B1); PG8_BAR;
;             PG8_LDA(At, 1, 1); PG8_STAGE(PG8_SA(1, 0), a3, voffA);
;             PG8_BAR; PG8_WAIT_L(0); PG8_MMA(1, 0, At, B0); PG8_BAR; PG8_SCHED;
;             PG8_STAGE(PG8_SB(1, 1), b3 + hstepB, voffB);
;             PG8_WAIT_V(6); PG8_BAR; PG8_MMA(1, 1, At, B1); PG8_BAR;
	s_mov_b32 m0, s55
	v_lshl_add_u64 v[204:205], s[28:29], 0, v[128:129]
	global_load_lds_dwordx4 v[204:205], off
	s_add_i32 m0, s55, 0x2000
	v_lshl_add_u64 v[204:205], s[28:29], 0, v[130:131]
	global_load_lds_dwordx4 v[204:205], off
	s_mov_b32 m0, s43
	v_lshl_add_u64 v[204:205], s[26:27], 0, v[128:129]
	global_load_lds_dwordx4 v[204:205], off
	s_mov_b32 m0, s44
	v_lshl_add_u64 v[204:205], s[26:27], 0, v[130:131]
	global_load_lds_dwordx4 v[204:205], off
	s_add_u32 s24, s24, 0x84000
	s_addc_u32 s25, s25, 0
	s_add_i32 s26, s56, s36
	s_mov_b32 m0, s26
	v_lshl_add_u64 v[204:205], s[24:25], 0, v[128:129]
	global_load_lds_dwordx4 v[204:205], off
	s_add_i32 m0, s26, 0x2000
	v_lshl_add_u64 v[204:205], s[24:25], 0, v[130:131]
	global_load_lds_dwordx4 v[204:205], off
	ds_read_b128 v[156:159], v135 offset:49152
	ds_read_b128 v[164:167], v135 offset:51200
	ds_read_b128 v[172:175], v135 offset:53248
	ds_read_b128 v[180:183], v135 offset:55296
	ds_read_b128 v[160:163], v135 offset:50176
	ds_read_b128 v[168:171], v135 offset:52224
	ds_read_b128 v[176:179], v135 offset:54272
	ds_read_b128 v[184:187], v135 offset:56320
	s_waitcnt vmcnt(6)
	s_waitcnt lgkmcnt(0)
	s_barrier
	v_mfma_f32_16x16x32_bf16 v[60:63], v[136:139], v[156:159], v[60:63]
	s_setprio 1
	v_mfma_f32_16x16x32_bf16 v[56:59], v[144:147], v[156:159], v[56:59]
	v_mfma_f32_16x16x32_bf16 v[44:47], v[136:139], v[164:167], v[44:47]
	v_mfma_f32_16x16x32_bf16 v[40:43], v[144:147], v[164:167], v[40:43]
	v_mfma_f32_16x16x32_bf16 v[28:31], v[136:139], v[172:175], v[28:31]
	v_mfma_f32_16x16x32_bf16 v[24:27], v[144:147], v[172:175], v[24:27]
	v_mfma_f32_16x16x32_bf16 v[12:15], v[136:139], v[180:183], v[12:15]
	v_mfma_f32_16x16x32_bf16 v[8:11], v[144:147], v[180:183], v[8:11]
	v_mfma_f32_16x16x32_bf16 v[60:63], v[140:143], v[160:163], v[60:63]
	v_mfma_f32_16x16x32_bf16 v[56:59], v[148:151], v[160:163], v[56:59]
	v_mfma_f32_16x16x32_bf16 v[44:47], v[140:143], v[168:171], v[44:47]
	v_mfma_f32_16x16x32_bf16 v[40:43], v[148:151], v[168:171], v[40:43]
	v_mfma_f32_16x16x32_bf16 v[28:31], v[140:143], v[176:179], v[28:31]
	v_mfma_f32_16x16x32_bf16 v[24:27], v[148:151], v[176:179], v[24:27]
	v_mfma_f32_16x16x32_bf16 v[12:15], v[140:143], v[184:187], v[12:15]
	v_mfma_f32_16x16x32_bf16 v[8:11], v[148:151], v[184:187], v[8:11]
	v_mfma_f32_16x16x32_bf16 v[52:55], v[188:191], v[156:159], v[52:55]
	v_mfma_f32_16x16x32_bf16 v[48:51], v[196:199], v[156:159], v[48:51]
	s_add_i32 s54, s54, 2
	s_add_u32 s22, s22, 0x8000
	s_addc_u32 s23, s23, 0
	s_add_u32 s51, s51, 0x8000
	s_addc_u32 s52, s52, 0
	v_mfma_f32_16x16x32_bf16 v[36:39], v[188:191], v[164:167], v[36:39]
	v_mfma_f32_16x16x32_bf16 v[32:35], v[196:199], v[164:167], v[32:35]
	v_mfma_f32_16x16x32_bf16 v[20:23], v[188:191], v[172:175], v[20:23]
	v_mfma_f32_16x16x32_bf16 v[16:19], v[196:199], v[172:175], v[16:19]
	v_mfma_f32_16x16x32_bf16 v[4:7], v[188:191], v[180:183], v[4:7]
	v_mfma_f32_16x16x32_bf16 v[0:3], v[196:199], v[180:183], v[0:3]
	v_mfma_f32_16x16x32_bf16 v[52:55], v[192:195], v[160:163], v[52:55]
	v_mfma_f32_16x16x32_bf16 v[48:51], v[200:203], v[160:163], v[48:51]
	v_mfma_f32_16x16x32_bf16 v[36:39], v[192:195], v[168:171], v[36:39]
	v_mfma_f32_16x16x32_bf16 v[32:35], v[200:203], v[168:171], v[32:35]
	v_mfma_f32_16x16x32_bf16 v[20:23], v[192:195], v[176:179], v[20:23]
	v_mfma_f32_16x16x32_bf16 v[16:19], v[200:203], v[176:179], v[16:19]
	v_mfma_f32_16x16x32_bf16 v[4:7], v[192:195], v[184:187], v[4:7]
	s_cmp_gt_u32 s54, 29
	s_setprio 0
	v_mfma_f32_16x16x32_bf16 v[0:3], v[200:203], v[184:187], v[0:3]
	s_cbranch_scc1 .Lrot_exit_141
.LBB0_141:
	s_barrier
	s_add_u32 s24, s22, 0xfff84000
	s_addc_u32 s25, s23, -1
	s_cmp_eq_u32 s54, 28
	s_cselect_b32 s28, s49, s24
	s_cselect_b32 s29, s15, s25
	s_cselect_b32 s24, s50, s51
	s_cselect_b32 s25, s5, s52
	s_add_u32 s26, s28, 0x4000
	s_addc_u32 s27, s29, 0
	s_add_i32 m0, s37, 0xc000
	v_lshl_add_u64 v[188:189], s[22:23], 0, v[128:129]
	global_load_lds_dwordx4 v[188:189], off
	s_add_i32 m0, s37, 0xe000
	v_lshl_add_u64 v[188:189], s[22:23], 0, v[130:131]
	global_load_lds_dwordx4 v[188:189], off
	s_mov_b32 s55, 0x10000
	v_add_u32_e32 v148, s55, v134
	ds_read_b128 v[136:139], v148
	ds_read_b128 v[144:147], v148 offset:2048
	ds_read_b128 v[140:143], v148 offset:1024
	ds_read_b128 v[148:151], v148 offset:3072
	ds_read_b128 v[156:159], v135
	ds_read_b128 v[164:167], v135 offset:2048
	ds_read_b128 v[172:175], v135 offset:4096
	ds_read_b128 v[180:183], v135 offset:6144
	ds_read_b128 v[160:163], v135 offset:1024
	ds_read_b128 v[168:171], v135 offset:3072
	ds_read_b128 v[176:179], v135 offset:5120
	ds_read_b128 v[184:187], v135 offset:7168
	s_mov_b32 s58, 0x14000
	s_add_i32 s55, s55, s36
	v_add_u32_e32 v152, s58, v134
	ds_read_b128 v[188:191], v152
	ds_read_b128 v[196:199], v152 offset:2048
	ds_read_b128 v[192:195], v152 offset:1024
	ds_read_b128 v[200:203], v152 offset:3072
	s_waitcnt lgkmcnt(0)
	s_barrier
; #define PG8_STAGE(bufoff, gbase, voff) do { _Pragma("unroll") for (int _i = 0; _i < 2; ++_i) \
;         __builtin_amdgcn_global_load_lds((const unsigned*)((const char*)(gbase) + (voff)[_i]), (LAS unsigned*)(lds + (bufoff) + ldsw + _i * 8192), 16, 0, 0); } while (0)
; #define PG8_LDA(dst, b, h) do { _Pragma("unroll") for (int m = 0; m < 4; ++m) _Pragma("unroll") for (int k = 0; k < 2; ++k) dst[m][k] = *(const LAS bf16x8*)(lds + PG8_SA(b, h) + aoff + m * 2048 + k * 1024); } while (0)
; #define PG8_WAIT_V(n) asm volatile("s_waitcnt vmcnt(" #n ")" ::: "memory")
; #define PG8_WAIT_L(n) asm volatile("s_waitcnt lgkmcnt(" #n ")" ::: "memory")
; template <class Epi>
; __device__ __forceinline__ void gemm_phase(LAS unsigned char* lds, const Gemm g, const StaticOrder& S, const Epi& E) {
;     ...
;         for (int t = 0; t < nt; t += 2) {
;             const bool last = (t == nt - 2);
;             const char* a1 = cA + (size_t)(t + 1) * kstep;
;             const char* a2 = last ? nA : cA + (size_t)(t + 2) * kstep; const char* b2 = last ? nB : cB + (size_t)(t + 2) * kstep;
;             const char* a3 = a2 + kstep; const char* b3 = b2 + kstep;
;             PG8_LDB(B0, 0, 0); PG8_SCHED; PG8_LDA(At, 0, 0); PG8_STAGE(PG8_SA(1, 1), a1 + hstepA, voffA);
;             PG8_WAIT_L(8); PG8_BAR; PG8_WAIT_L(0); PG8_MMA(0, 0, At, B0); PG8_BAR; PG8_SCHED;
;             PG8_LDB(B1, 0, 1); PG8_STAGE(PG8_SB(0, 0), b2, voffB);
;             PG8_BAR; PG8_WAIT_L(0); PG8_MMA(0, 1, At, B1); PG8_BAR;
;             PG8_LDA(At, 0, 1); PG8_STAGE(PG8_SA(0, 0), a2, voffA);
;             PG8_BAR; PG8_WAIT_L(0); PG8_MMA(1, 0, At, B0); PG8_BAR; PG8_SCHED;
;             PG8_STAGE(PG8_SB(0, 1), b2 + hstepB, voffB);
;             PG8_WAIT_V(6); PG8_BAR; PG8_MMA(1, 1, At, B1); PG8_BAR;
;             PG8_LDB(B0, 1, 0); PG8_SCHED; PG8_LDA(At, 1, 0); PG8_STAGE(PG8_SA(0, 1), a2 + hstepA, voffA);
;             PG8_WAIT_L(8); PG8_BAR; PG8_WAIT_L(0); PG8_MMA(0, 0, At, B0); PG8_BAR; PG8_SCHED;
;             PG8_LDB(B1, 1, 1); PG8_STAGE(PG8_SB(1, 0), b3, voffB);
;             PG8_BAR; PG8_WAIT_L(0); PG8_MMA(0, 1, At, B1); PG8_BAR;
;             PG8_LDA(At, 1, 1); PG8_STAGE(PG8_SA(1, 0), a3, voffA);
;             PG8_BAR; PG8_WAIT_L(0); PG8_MMA(1, 0, At, B0); PG8_BAR; PG8_SCHED;
;             PG8_STAGE(PG8_SB(1, 1), b3 + hstepB, voffB);
;             PG8_WAIT_V(6); PG8_BAR; PG8_MMA(1, 1, At, B1); PG8_BAR;
	v_mfma_f32_16x16x32_bf16 v[124:127], v[136:139], v[156:159], v[124:127]
	s_setprio 1
	v_mfma_f32_16x16x32_bf16 v[120:123], v[144:147], v[156:159], v[120:123]
	v_mfma_f32_16x16x32_bf16 v[108:111], v[136:139], v[164:167], v[108:111]
	v_mfma_f32_16x16x32_bf16 v[104:107], v[144:147], v[164:167], v[104:107]
	v_mfma_f32_16x16x32_bf16 v[92:95], v[136:139], v[172:175], v[92:95]
	v_mfma_f32_16x16x32_bf16 v[88:91], v[144:147], v[172:175], v[88:91]
	v_mfma_f32_16x16x32_bf16 v[76:79], v[136:139], v[180:183], v[76:79]
	v_mfma_f32_16x16x32_bf16 v[72:75], v[144:147], v[180:183], v[72:75]
	v_mfma_f32_16x16x32_bf16 v[124:127], v[140:143], v[160:163], v[124:127]
	v_mfma_f32_16x16x32_bf16 v[120:123], v[148:151], v[160:163], v[120:123]
	v_mfma_f32_16x16x32_bf16 v[108:111], v[140:143], v[168:171], v[108:111]
	v_mfma_f32_16x16x32_bf16 v[104:107], v[148:151], v[168:171], v[104:107]
	v_mfma_f32_16x16x32_bf16 v[92:95], v[140:143], v[176:179], v[92:95]
	v_mfma_f32_16x16x32_bf16 v[88:91], v[148:151], v[176:179], v[88:91]
	v_mfma_f32_16x16x32_bf16 v[76:79], v[140:143], v[184:187], v[76:79]
	v_mfma_f32_16x16x32_bf16 v[72:75], v[148:151], v[184:187], v[72:75]
	v_mfma_f32_16x16x32_bf16 v[116:119], v[188:191], v[156:159], v[116:119]
	v_mfma_f32_16x16x32_bf16 v[112:115], v[196:199], v[156:159], v[112:115]
	v_mfma_f32_16x16x32_bf16 v[100:103], v[188:191], v[164:167], v[100:103]
	v_mfma_f32_16x16x32_bf16 v[96:99], v[196:199], v[164:167], v[96:99]
	v_mfma_f32_16x16x32_bf16 v[84:87], v[188:191], v[172:175], v[84:87]
	v_mfma_f32_16x16x32_bf16 v[80:83], v[196:199], v[172:175], v[80:83]
	v_mfma_f32_16x16x32_bf16 v[68:71], v[188:191], v[180:183], v[68:71]
	v_mfma_f32_16x16x32_bf16 v[64:67], v[196:199], v[180:183], v[64:67]
	v_mfma_f32_16x16x32_bf16 v[116:119], v[192:195], v[160:163], v[116:119]
	v_mfma_f32_16x16x32_bf16 v[112:115], v[200:203], v[160:163], v[112:115]
	v_mfma_f32_16x16x32_bf16 v[100:103], v[192:195], v[168:171], v[100:103]
	v_mfma_f32_16x16x32_bf16 v[96:99], v[200:203], v[168:171], v[96:99]
	v_mfma_f32_16x16x32_bf16 v[84:87], v[192:195], v[176:179], v[84:87]
	v_mfma_f32_16x16x32_bf16 v[80:83], v[200:203], v[176:179], v[80:83]
	v_mfma_f32_16x16x32_bf16 v[68:71], v[192:195], v[184:187], v[68:71]
	s_setprio 0
	v_mfma_f32_16x16x32_bf16 v[64:67], v[200:203], v[184:187], v[64:67]
	s_barrier
	s_mov_b32 m0, s55
	v_lshl_add_u64 v[204:205], s[24:25], 0, v[128:129]
	global_load_lds_dwordx4 v[204:205], off
	s_add_i32 m0, s55, 0x2000
	v_lshl_add_u64 v[204:205], s[24:25], 0, v[130:131]
	global_load_lds_dwordx4 v[204:205], off
	s_mov_b32 m0, s37
	v_lshl_add_u64 v[204:205], s[28:29], 0, v[128:129]
	global_load_lds_dwordx4 v[204:205], off
	s_mov_b32 m0, s38
	v_lshl_add_u64 v[204:205], s[28:29], 0, v[130:131]
	global_load_lds_dwordx4 v[204:205], off
	s_add_u32 s56, s24, 0x80000
	s_addc_u32 s57, s25, 0
	s_add_i32 s55, s58, s36
	s_mov_b32 m0, s55
	v_lshl_add_u64 v[204:205], s[56:57], 0, v[128:129]
	global_load_lds_dwordx4 v[204:205], off
	s_add_i32 m0, s55, 0x2000
	v_lshl_add_u64 v[204:205], s[56:57], 0, v[130:131]
	global_load_lds_dwordx4 v[204:205], off
	ds_read_b128 v[156:159], v135 offset:16384
	ds_read_b128 v[164:167], v135 offset:18432
	ds_read_b128 v[172:175], v135 offset:20480
	ds_read_b128 v[180:183], v135 offset:22528
	ds_read_b128 v[160:163], v135 offset:17408
	ds_read_b128 v[168:171], v135 offset:19456
	ds_read_b128 v[176:179], v135 offset:21504
	ds_read_b128 v[184:187], v135 offset:23552
	s_waitcnt vmcnt(6)
	s_waitcnt lgkmcnt(0)
	s_barrier
	v_mfma_f32_16x16x32_bf16 v[60:63], v[136:139], v[156:159], v[60:63]
	s_setprio 1
	v_mfma_f32_16x16x32_bf16 v[56:59], v[144:147], v[156:159], v[56:59]
	v_mfma_f32_16x16x32_bf16 v[44:47], v[136:139], v[164:167], v[44:47]
	v_mfma_f32_16x16x32_bf16 v[40:43], v[144:147], v[164:167], v[40:43]
	v_mfma_f32_16x16x32_bf16 v[28:31], v[136:139], v[172:175], v[28:31]
	v_mfma_f32_16x16x32_bf16 v[24:27], v[144:147], v[172:175], v[24:27]
	v_mfma_f32_16x16x32_bf16 v[12:15], v[136:139], v[180:183], v[12:15]
	v_mfma_f32_16x16x32_bf16 v[8:11], v[144:147], v[180:183], v[8:11]
	v_mfma_f32_16x16x32_bf16 v[60:63], v[140:143], v[160:163], v[60:63]
	v_mfma_f32_16x16x32_bf16 v[56:59], v[148:151], v[160:163], v[56:59]
	v_mfma_f32_16x16x32_bf16 v[44:47], v[140:143], v[168:171], v[44:47]
	v_mfma_f32_16x16x32_bf16 v[40:43], v[148:151], v[168:171], v[40:43]
	v_mfma_f32_16x16x32_bf16 v[28:31], v[140:143], v[176:179], v[28:31]
	v_mfma_f32_16x16x32_bf16 v[24:27], v[148:151], v[176:179], v[24:27]
	v_mfma_f32_16x16x32_bf16 v[12:15], v[140:143], v[184:187], v[12:15]
	v_mfma_f32_16x16x32_bf16 v[8:11], v[148:151], v[184:187], v[8:11]
	v_mfma_f32_16x16x32_bf16 v[52:55], v[188:191], v[156:159], v[52:55]
	v_mfma_f32_16x16x32_bf16 v[48:51], v[196:199], v[156:159], v[48:51]
	s_add_i32 s55, 0, 0x18000
	v_add_u32_e32 v148, s55, v134
	v_mfma_f32_16x16x32_bf16 v[36:39], v[188:191], v[164:167], v[36:39]
	v_mfma_f32_16x16x32_bf16 v[32:35], v[196:199], v[164:167], v[32:35]
	v_mfma_f32_16x16x32_bf16 v[20:23], v[188:191], v[172:175], v[20:23]
	v_mfma_f32_16x16x32_bf16 v[16:19], v[196:199], v[172:175], v[16:19]
	v_mfma_f32_16x16x32_bf16 v[4:7], v[188:191], v[180:183], v[4:7]
	v_mfma_f32_16x16x32_bf16 v[0:3], v[196:199], v[180:183], v[0:3]
	v_mfma_f32_16x16x32_bf16 v[52:55], v[192:195], v[160:163], v[52:55]
	v_mfma_f32_16x16x32_bf16 v[48:51], v[200:203], v[160:163], v[48:51]
	v_mfma_f32_16x16x32_bf16 v[36:39], v[192:195], v[168:171], v[36:39]
	v_mfma_f32_16x16x32_bf16 v[32:35], v[200:203], v[168:171], v[32:35]
	v_mfma_f32_16x16x32_bf16 v[20:23], v[192:195], v[176:179], v[20:23]
	v_mfma_f32_16x16x32_bf16 v[16:19], v[200:203], v[176:179], v[16:19]
	v_mfma_f32_16x16x32_bf16 v[4:7], v[192:195], v[184:187], v[4:7]
	s_setprio 0
	v_mfma_f32_16x16x32_bf16 v[0:3], v[200:203], v[184:187], v[0:3]
	s_barrier
; #define PG8_STAGE(bufoff, gbase, voff) do { _Pragma("unroll") for (int _i = 0; _i < 2; ++_i) \
;         __builtin_amdgcn_global_load_lds((const unsigned*)((const char*)(gbase) + (voff)[_i]), (LAS unsigned*)(lds + (bufoff) + ldsw + _i * 8192), 16, 0, 0); } while (0)
; #define PG8_LDA(dst, b, h) do { _Pragma("unroll") for (int m = 0; m < 4; ++m) _Pragma("unroll") for (int k = 0; k < 2; ++k) dst[m][k] = *(const LAS bf16x8*)(lds + PG8_SA(b, h) + aoff + m * 2048 + k * 1024); } while (0)
; #define PG8_WAIT_V(n) asm volatile("s_waitcnt vmcnt(" #n ")" ::: "memory")
; #define PG8_WAIT_L(n) asm volatile("s_waitcnt lgkmcnt(" #n ")" ::: "memory")
; template <class Epi>
; __device__ __forceinline__ void gemm_phase(LAS unsigned char* lds, const Gemm g, const StaticOrder& S, const Epi& E) {
;     ...
;         for (int t = 0; t < nt; t += 2) {
;             const bool last = (t == nt - 2);
;             const char* a1 = cA + (size_t)(t + 1) * kstep;
;             const char* a2 = last ? nA : cA + (size_t)(t + 2) * kstep; const char* b2 = last ? nB : cB + (size_t)(t + 2) * kstep;
;             const char* a3 = a2 + kstep; const char* b3 = b2 + kstep;
;             PG8_LDB(B0, 0, 0); PG8_SCHED; PG8_LDA(At, 0, 0); PG8_STAGE(PG8_SA(1, 1), a1 + hstepA, voffA);
;             PG8_WAIT_L(8); PG8_BAR; PG8_WAIT_L(0); PG8_MMA(0, 0, At, B0); PG8_BAR; PG8_SCHED;
;             PG8_LDB(B1, 0, 1); PG8_STAGE(PG8_SB(0, 0), b2, voffB);
;             PG8_BAR; PG8_WAIT_L(0); PG8_MMA(0, 1, At, B1); PG8_BAR;
;             PG8_LDA(At, 0, 1); PG8_STAGE(PG8_SA(0, 0), a2, voffA);
;             PG8_BAR; PG8_WAIT_L(0); PG8_MMA(1, 0, At, B0); PG8_BAR; PG8_SCHED;
;             PG8_STAGE(PG8_SB(0, 1), b2 + hstepB, voffB);
;             PG8_WAIT_V(6); PG8_BAR; PG8_MMA(1, 1, At, B1); PG8_BAR;
;             PG8_LDB(B0, 1, 0); PG8_SCHED; PG8_LDA(At, 1, 0); PG8_STAGE(PG8_SA(0, 1), a2 + hstepA, voffA);
;             PG8_WAIT_L(8); PG8_BAR; PG8_WAIT_L(0); PG8_MMA(0, 0, At, B0); PG8_BAR; PG8_SCHED;
;             PG8_LDB(B1, 1, 1); PG8_STAGE(PG8_SB(1, 0), b3, voffB);
;             PG8_BAR; PG8_WAIT_L(0); PG8_MMA(0, 1, At, B1); PG8_BAR;
;             PG8_LDA(At, 1, 1); PG8_STAGE(PG8_SA(1, 0), a3, voffA);
;             PG8_BAR; PG8_WAIT_L(0); PG8_MMA(1, 0, At, B0); PG8_BAR; PG8_SCHED;
;             PG8_STAGE(PG8_SB(1, 1), b3 + hstepB, voffB);
;             PG8_WAIT_V(6); PG8_BAR; PG8_MMA(1, 1, At, B1); PG8_BAR;
	s_add_u32 s28, s28, 0x80000
	s_addc_u32 s29, s29, 0
	s_mov_b32 m0, s39
	v_lshl_add_u64 v[188:189], s[28:29], 0, v[128:129]
	global_load_lds_dwordx4 v[188:189], off
	s_mov_b32 m0, s40
	v_lshl_add_u64 v[188:189], s[28:29], 0, v[130:131]
	global_load_lds_dwordx4 v[188:189], off
	ds_read_b128 v[136:139], v148
	ds_read_b128 v[144:147], v148 offset:2048
	ds_read_b128 v[140:143], v148 offset:1024
	ds_read_b128 v[148:151], v148 offset:3072
	ds_read_b128 v[156:159], v135 offset:32768
	ds_read_b128 v[164:167], v135 offset:34816
	ds_read_b128 v[172:175], v135 offset:36864
	ds_read_b128 v[180:183], v135 offset:38912
	ds_read_b128 v[160:163], v135 offset:33792
	ds_read_b128 v[168:171], v135 offset:35840
	ds_read_b128 v[176:179], v135 offset:37888
	ds_read_b128 v[184:187], v135 offset:39936
	s_mov_b32 s56, 0x1c000
	s_add_u32 s28, s24, 0x4000
	s_addc_u32 s29, s25, 0
	s_add_i32 s55, s55, s36
	v_add_u32_e32 v152, s56, v134
	ds_read_b128 v[188:191], v152
	ds_read_b128 v[196:199], v152 offset:2048
	ds_read_b128 v[192:195], v152 offset:1024
	ds_read_b128 v[200:203], v152 offset:3072
	s_waitcnt lgkmcnt(0)
	s_barrier
	v_mfma_f32_16x16x32_bf16 v[124:127], v[136:139], v[156:159], v[124:127]
	s_setprio 1
	v_mfma_f32_16x16x32_bf16 v[120:123], v[144:147], v[156:159], v[120:123]
	v_mfma_f32_16x16x32_bf16 v[108:111], v[136:139], v[164:167], v[108:111]
	v_mfma_f32_16x16x32_bf16 v[104:107], v[144:147], v[164:167], v[104:107]
	v_mfma_f32_16x16x32_bf16 v[92:95], v[136:139], v[172:175], v[92:95]
	v_mfma_f32_16x16x32_bf16 v[88:91], v[144:147], v[172:175], v[88:91]
	v_mfma_f32_16x16x32_bf16 v[76:79], v[136:139], v[180:183], v[76:79]
	v_mfma_f32_16x16x32_bf16 v[72:75], v[144:147], v[180:183], v[72:75]
	v_mfma_f32_16x16x32_bf16 v[124:127], v[140:143], v[160:163], v[124:127]
	v_mfma_f32_16x16x32_bf16 v[120:123], v[148:151], v[160:163], v[120:123]
	v_mfma_f32_16x16x32_bf16 v[108:111], v[140:143], v[168:171], v[108:111]
	v_mfma_f32_16x16x32_bf16 v[104:107], v[148:151], v[168:171], v[104:107]
	v_mfma_f32_16x16x32_bf16 v[92:95], v[140:143], v[176:179], v[92:95]
	v_mfma_f32_16x16x32_bf16 v[88:91], v[148:151], v[176:179], v[88:91]
	v_mfma_f32_16x16x32_bf16 v[76:79], v[140:143], v[184:187], v[76:79]
	v_mfma_f32_16x16x32_bf16 v[72:75], v[148:151], v[184:187], v[72:75]
	v_mfma_f32_16x16x32_bf16 v[116:119], v[188:191], v[156:159], v[116:119]
	v_mfma_f32_16x16x32_bf16 v[112:115], v[196:199], v[156:159], v[112:115]
	v_mfma_f32_16x16x32_bf16 v[100:103], v[188:191], v[164:167], v[100:103]
	v_mfma_f32_16x16x32_bf16 v[96:99], v[196:199], v[164:167], v[96:99]
	v_mfma_f32_16x16x32_bf16 v[84:87], v[188:191], v[172:175], v[84:87]
	v_mfma_f32_16x16x32_bf16 v[80:83], v[196:199], v[172:175], v[80:83]
	v_mfma_f32_16x16x32_bf16 v[68:71], v[188:191], v[180:183], v[68:71]
	v_mfma_f32_16x16x32_bf16 v[64:67], v[196:199], v[180:183], v[64:67]
	v_mfma_f32_16x16x32_bf16 v[116:119], v[192:195], v[160:163], v[116:119]
	v_mfma_f32_16x16x32_bf16 v[112:115], v[200:203], v[160:163], v[112:115]
	v_mfma_f32_16x16x32_bf16 v[100:103], v[192:195], v[168:171], v[100:103]
	v_mfma_f32_16x16x32_bf16 v[96:99], v[200:203], v[168:171], v[96:99]
	v_mfma_f32_16x16x32_bf16 v[84:87], v[192:195], v[176:179], v[84:87]
	v_mfma_f32_16x16x32_bf16 v[80:83], v[200:203], v[176:179], v[80:83]
	v_mfma_f32_16x16x32_bf16 v[68:71], v[192:195], v[184:187], v[68:71]
	s_setprio 0
	v_mfma_f32_16x16x32_bf16 v[64:67], v[200:203], v[184:187], v[64:67]
	s_barrier
	s_mov_b32 m0, s55
	v_lshl_add_u64 v[204:205], s[28:29], 0, v[128:129]
	global_load_lds_dwordx4 v[204:205], off
	s_add_i32 m0, s55, 0x2000
	v_lshl_add_u64 v[204:205], s[28:29], 0, v[130:131]
	global_load_lds_dwordx4 v[204:205], off
	s_mov_b32 m0, s43
	v_lshl_add_u64 v[204:205], s[26:27], 0, v[128:129]
	global_load_lds_dwordx4 v[204:205], off
	s_mov_b32 m0, s44
	v_lshl_add_u64 v[204:205], s[26:27], 0, v[130:131]
	global_load_lds_dwordx4 v[204:205], off
	s_add_u32 s24, s24, 0x84000
	s_addc_u32 s25, s25, 0
	s_add_i32 s26, s56, s36
	s_mov_b32 m0, s26
	v_lshl_add_u64 v[204:205], s[24:25], 0, v[128:129]
	global_load_lds_dwordx4 v[204:205], off
	s_add_i32 m0, s26, 0x2000
	v_lshl_add_u64 v[204:205], s[24:25], 0, v[130:131]
	global_load_lds_dwordx4 v[204:205], off
	ds_read_b128 v[156:159], v135 offset:49152
	ds_read_b128 v[164:167], v135 offset:51200
	ds_read_b128 v[172:175], v135 offset:53248
	ds_read_b128 v[180:183], v135 offset:55296
	ds_read_b128 v[160:163], v135 offset:50176
	ds_read_b128 v[168:171], v135 offset:52224
	ds_read_b128 v[176:179], v135 offset:54272
	ds_read_b128 v[184:187], v135 offset:56320
	s_waitcnt vmcnt(6)
	s_waitcnt lgkmcnt(0)
	s_barrier
	v_mfma_f32_16x16x32_bf16 v[60:63], v[136:139], v[156:159], v[60:63]
	s_setprio 1
	v_mfma_f32_16x16x32_bf16 v[56:59], v[144:147], v[156:159], v[56:59]
	v_mfma_f32_16x16x32_bf16 v[44:47], v[136:139], v[164:167], v[44:47]
	v_mfma_f32_16x16x32_bf16 v[40:43], v[144:147], v[164:167], v[40:43]
	v_mfma_f32_16x16x32_bf16 v[28:31], v[136:139], v[172:175], v[28:31]
	v_mfma_f32_16x16x32_bf16 v[24:27], v[144:147], v[172:175], v[24:27]
	v_mfma_f32_16x16x32_bf16 v[12:15], v[136:139], v[180:183], v[12:15]
	v_mfma_f32_16x16x32_bf16 v[8:11], v[144:147], v[180:183], v[8:11]
	v_mfma_f32_16x16x32_bf16 v[60:63], v[140:143], v[160:163], v[60:63]
	v_mfma_f32_16x16x32_bf16 v[56:59], v[148:151], v[160:163], v[56:59]
	v_mfma_f32_16x16x32_bf16 v[44:47], v[140:143], v[168:171], v[44:47]
	v_mfma_f32_16x16x32_bf16 v[40:43], v[148:151], v[168:171], v[40:43]
	v_mfma_f32_16x16x32_bf16 v[28:31], v[140:143], v[176:179], v[28:31]
	v_mfma_f32_16x16x32_bf16 v[24:27], v[148:151], v[176:179], v[24:27]
	v_mfma_f32_16x16x32_bf16 v[12:15], v[140:143], v[184:187], v[12:15]
	v_mfma_f32_16x16x32_bf16 v[8:11], v[148:151], v[184:187], v[8:11]
	v_mfma_f32_16x16x32_bf16 v[52:55], v[188:191], v[156:159], v[52:55]
	v_mfma_f32_16x16x32_bf16 v[48:51], v[196:199], v[156:159], v[48:51]
	s_add_i32 s54, s54, 2
	s_add_u32 s22, s22, 0x8000
	s_addc_u32 s23, s23, 0
	s_add_u32 s51, s51, 0x8000
	s_addc_u32 s52, s52, 0
	v_mfma_f32_16x16x32_bf16 v[36:39], v[188:191], v[164:167], v[36:39]
	v_mfma_f32_16x16x32_bf16 v[32:35], v[196:199], v[164:167], v[32:35]
	v_mfma_f32_16x16x32_bf16 v[20:23], v[188:191], v[172:175], v[20:23]
	v_mfma_f32_16x16x32_bf16 v[16:19], v[196:199], v[172:175], v[16:19]
	v_mfma_f32_16x16x32_bf16 v[4:7], v[188:191], v[180:183], v[4:7]
	v_mfma_f32_16x16x32_bf16 v[0:3], v[196:199], v[180:183], v[0:3]
	v_mfma_f32_16x16x32_bf16 v[52:55], v[192:195], v[160:163], v[52:55]
	v_mfma_f32_16x16x32_bf16 v[48:51], v[200:203], v[160:163], v[48:51]
	v_mfma_f32_16x16x32_bf16 v[36:39], v[192:195], v[168:171], v[36:39]
	v_mfma_f32_16x16x32_bf16 v[32:35], v[200:203], v[168:171], v[32:35]
	v_mfma_f32_16x16x32_bf16 v[20:23], v[192:195], v[176:179], v[20:23]
	v_mfma_f32_16x16x32_bf16 v[16:19], v[200:203], v[176:179], v[16:19]
	v_mfma_f32_16x16x32_bf16 v[4:7], v[192:195], v[184:187], v[4:7]
	s_cmp_gt_u32 s54, 29
	s_setprio 0
	v_mfma_f32_16x16x32_bf16 v[0:3], v[200:203], v[184:187], v[0:3]
	s_cbranch_scc0 .LBB0_141
; __device__ __forceinline__ unsigned cvt_pk_bf16(float lo, float hi) { unsigned r; asm volatile("v_cvt_pk_bf16_f32 %0, %1, %2" : "=v"(r) : "v"(lo), "v"(hi)); return r; }
;     __device__ __forceinline__ void operator()(const f32x4 (&acc)[2][2][4][2], const Unit& u, int wr, int wc, int fr, int fq) const {
;         const int row0 = u.pm * BM + wr * 64 + fr, col0 = u.pn * BM + wc * 32 + 8 * fq;
; #pragma unroll
;         for (int ai = 0; ai < 2; ++ai)
; #pragma unroll
;             for (int m = 0; m < 4; ++m) {
;                 const int rowi = row0 + ai * HALF + m * 16;
; #pragma unroll
;                 for (int bj = 0; bj < 2; ++bj) {
;                     f32x4 v0 = acc[ai][bj][m][0], v1 = acc[ai][bj][m][1];
; #pragma unroll
;                     for (int j = 0; j < 4; ++j) { const float a = fmaxf(v0[j], 0.f), b = fmaxf(v1[j], 0.f); v0[j] = a * a; v1[j] = b * b; }
;                     u32x4 w; w.x = cvt_pk_bf16(v0[0], v0[1]); w.y = cvt_pk_bf16(v0[2], v0[3]); w.z = cvt_pk_bf16(v1[0], v1[1]); w.w = cvt_pk_bf16(v1[2], v1[3]);
;                     *(u32x4*)(O + tiled_off(rowi, col0 + bj * HALF, DFF / 64)) = w;
;                 }
.Lrot_exit_141:
	s_barrier
.Lpeel_done_141:
	s_lshl_b32 s24, s20, 8
	s_lshl_b32 s5, s21, 8
	s_add_i32 s24, s24, s41
	s_or_b32 s5, s5, s42
	s_and_b32 s22, s24, 0xffffff80
	s_ashr_i32 s5, s5, 6
	s_add_i32 s20, s22, s5
	s_ashr_i32 s21, s20, 31
	v_max_f32_e32 v120, 0, v120
	s_lshl_b64 s[20:21], s[20:21], 14
	v_readlane_b32 s26, v252, 57
	v_or_b32_e32 v136, s24, v132
	v_mul_f32_e32 v140, v120, v120
	v_max_f32_e32 v121, 0, v121
	v_max_f32_e32 v122, 0, v122
	v_readlane_b32 s27, v252, 58
	s_add_u32 s20, s26, s20
	v_lshlrev_b32_e32 v137, 6, v136
	s_movk_i32 s28, 0x3c0
	v_lshlrev_b32_e32 v138, 2, v136
	v_max_f32_e32 v120, 0, v125
	v_mul_f32_e32 v125, v121, v121
	v_max_f32_e32 v121, v126, v126
	v_mul_f32_e32 v126, v122, v122
	s_addc_u32 s21, s27, s21
	s_or_b32 s15, s5, 2
	v_and_or_b32 v137, v137, s28, v133
	v_and_b32_e32 v138, 32, v138
	v_max_f32_e32 v124, 0, v124
	v_mul_f32_e32 v120, v120, v120
	v_max_f32_e32 v121, 0, v121
	v_max_f32_e32 v122, 0, v127
	v_max_f32_e32 v123, 0, v123
	s_add_i32 s22, s15, s22
	v_bitop3_b32 v139, v137, s46, v138 bitop3:0xde
	v_mul_f32_e32 v124, v124, v124
	v_mul_f32_e32 v121, v121, v121
	v_mul_f32_e32 v122, v122, v122
	v_mul_f32_e32 v123, v123, v123
	v_cvt_pk_bf16_f32 v120, v124, v120
	v_max_f32_e32 v112, 0, v112
	v_max_f32_e32 v113, 0, v113
	s_ashr_i32 s23, s22, 31
	v_cvt_pk_bf16_f32 v121, v121, v122
	v_cvt_pk_bf16_f32 v122, v140, v125
	v_cvt_pk_bf16_f32 v123, v126, v123
	global_store_dwordx4 v139, v[120:123], s[20:21] nt
	v_max_f32_e32 v114, 0, v114
	s_lshl_b64 s[22:23], s[22:23], 14
	v_mul_f32_e32 v120, v112, v112
	v_max_f32_e32 v112, v117, v117
	v_mul_f32_e32 v117, v113, v113
	v_max_f32_e32 v112, 0, v112
	v_max_f32_e32 v113, 0, v118
	v_mul_f32_e32 v118, v114, v114
	s_add_u32 s22, s26, s22
	v_max_f32_e32 v116, 0, v116
	v_mul_f32_e32 v112, v112, v112
	v_mul_f32_e32 v113, v113, v113
	v_max_f32_e32 v114, 0, v119
	v_max_f32_e32 v115, 0, v115
	s_addc_u32 s23, s27, s23
	s_or_b32 s25, s24, 16
	v_mul_f32_e32 v116, v116, v116
	v_mul_f32_e32 v114, v114, v114
	v_mul_f32_e32 v115, v115, v115
	v_cvt_pk_bf16_f32 v112, v116, v112
	v_cvt_pk_bf16_f32 v113, v113, v114
	s_lshr_b32 s25, s25, 3
	v_max_f32_e32 v104, 0, v104
	v_cvt_pk_bf16_f32 v114, v120, v117
	v_cvt_pk_bf16_f32 v115, v118, v115
	global_store_dwordx4 v139, v[112:115], s[22:23] nt
	s_and_b32 s25, s25, 10
	v_max_f32_e32 v105, 0, v105
	v_mul_f32_e32 v113, v104, v104
	v_max_f32_e32 v106, 0, v106
	s_or_b32 s25, s25, s45
	v_max_f32_e32 v104, 0, v109
	v_mul_f32_e32 v109, v105, v105
	v_max_f32_e32 v105, v110, v110
	v_mul_f32_e32 v110, v106, v106
	s_lshl_b32 s25, s25, 10
	v_max_f32_e32 v108, 0, v108
	v_mul_f32_e32 v104, v104, v104
	v_max_f32_e32 v105, 0, v105
	v_max_f32_e32 v106, 0, v111
	v_max_f32_e32 v107, 0, v107
	v_bitop3_b32 v112, v137, s25, v138 bitop3:0xde
	v_mul_f32_e32 v108, v108, v108
	v_mul_f32_e32 v105, v105, v105
	v_mul_f32_e32 v106, v106, v106
	v_mul_f32_e32 v107, v107, v107
	v_cvt_pk_bf16_f32 v104, v108, v104
	v_max_f32_e32 v96, 0, v96
	v_max_f32_e32 v97, 0, v97
	v_cvt_pk_bf16_f32 v105, v105, v106
	v_cvt_pk_bf16_f32 v106, v113, v109
	v_cvt_pk_bf16_f32 v107, v110, v107
	global_store_dwordx4 v112, v[104:107], s[20:21] nt
	s_nop 0
	v_max_f32_e32 v98, 0, v98
	v_mul_f32_e32 v104, v96, v96
	v_max_f32_e32 v96, v101, v101
	v_mul_f32_e32 v101, v97, v97
	v_max_f32_e32 v96, 0, v96
	v_max_f32_e32 v97, 0, v102
	v_mul_f32_e32 v102, v98, v98
	v_max_f32_e32 v100, 0, v100
	v_mul_f32_e32 v96, v96, v96
	v_mul_f32_e32 v97, v97, v97
	v_max_f32_e32 v98, 0, v103
	v_max_f32_e32 v99, 0, v99
	s_or_b32 s25, s24, 32
	v_mul_f32_e32 v100, v100, v100
	v_mul_f32_e32 v98, v98, v98
	v_mul_f32_e32 v99, v99, v99
	v_cvt_pk_bf16_f32 v96, v100, v96
	v_cvt_pk_bf16_f32 v97, v97, v98
	s_lshr_b32 s25, s25, 3
	v_max_f32_e32 v88, 0, v88
	v_cvt_pk_bf16_f32 v98, v104, v101
	v_cvt_pk_bf16_f32 v99, v102, v99
	global_store_dwordx4 v112, v[96:99], s[22:23] nt
	s_and_b32 s25, s25, 12
	v_max_f32_e32 v89, 0, v89
	v_mul_f32_e32 v97, v88, v88
	v_max_f32_e32 v90, 0, v90
	s_or_b32 s25, s25, s45
	v_max_f32_e32 v88, 0, v93
	v_mul_f32_e32 v93, v89, v89
	v_max_f32_e32 v89, v94, v94
	v_mul_f32_e32 v94, v90, v90
	s_lshl_b32 s25, s25, 10
	v_max_f32_e32 v92, 0, v92
	v_mul_f32_e32 v88, v88, v88
	v_max_f32_e32 v89, 0, v89
	v_max_f32_e32 v90, 0, v95
	v_max_f32_e32 v91, 0, v91
	v_bitop3_b32 v96, v137, s25, v138 bitop3:0xde
	v_mul_f32_e32 v92, v92, v92
	v_mul_f32_e32 v89, v89, v89
	v_mul_f32_e32 v90, v90, v90
	v_mul_f32_e32 v91, v91, v91
	v_cvt_pk_bf16_f32 v88, v92, v88
	v_max_f32_e32 v80, 0, v80
	v_max_f32_e32 v81, 0, v81
	v_cvt_pk_bf16_f32 v89, v89, v90
	v_cvt_pk_bf16_f32 v90, v97, v93
	v_cvt_pk_bf16_f32 v91, v94, v91
	global_store_dwordx4 v96, v[88:91], s[20:21] nt
	s_nop 0
	v_max_f32_e32 v82, 0, v82
	v_mul_f32_e32 v88, v80, v80
	v_max_f32_e32 v80, v85, v85
	v_mul_f32_e32 v85, v81, v81
	v_max_f32_e32 v80, 0, v80
	v_max_f32_e32 v81, 0, v86
	v_mul_f32_e32 v86, v82, v82
	v_max_f32_e32 v84, 0, v84
	v_mul_f32_e32 v80, v80, v80
	v_mul_f32_e32 v81, v81, v81
	v_max_f32_e32 v82, 0, v87
	v_max_f32_e32 v83, 0, v83
	s_or_b32 s24, s24, 48
	v_mul_f32_e32 v84, v84, v84
	v_mul_f32_e32 v82, v82, v82
	v_mul_f32_e32 v83, v83, v83
	v_cvt_pk_bf16_f32 v80, v84, v80
	v_cvt_pk_bf16_f32 v81, v81, v82
	s_lshr_b32 s24, s24, 3
	v_max_f32_e32 v72, 0, v72
	v_cvt_pk_bf16_f32 v82, v88, v85
	v_cvt_pk_bf16_f32 v83, v86, v83
	global_store_dwordx4 v96, v[80:83], s[22:23] nt
	s_and_b32 s24, s24, 14
	v_max_f32_e32 v73, 0, v73
	v_mul_f32_e32 v81, v72, v72
	v_max_f32_e32 v74, 0, v74
	s_or_b32 s24, s24, s45
	v_max_f32_e32 v72, 0, v77
	v_mul_f32_e32 v77, v73, v73
	v_max_f32_e32 v73, v78, v78
	v_mul_f32_e32 v78, v74, v74
	s_lshl_b32 s24, s24, 10
	v_max_f32_e32 v76, 0, v76
; __device__ __forceinline__ unsigned cvt_pk_bf16(float lo, float hi) { unsigned r; asm volatile("v_cvt_pk_bf16_f32 %0, %1, %2" : "=v"(r) : "v"(lo), "v"(hi)); return r; }
;     __device__ __forceinline__ void operator()(const f32x4 (&acc)[2][2][4][2], const Unit& u, int wr, int wc, int fr, int fq) const {
;         const int row0 = u.pm * BM + wr * 64 + fr, col0 = u.pn * BM + wc * 32 + 8 * fq;
; #pragma unroll
;         for (int ai = 0; ai < 2; ++ai)
; #pragma unroll
;             for (int m = 0; m < 4; ++m) {
;                 const int rowi = row0 + ai * HALF + m * 16;
; #pragma unroll
;                 for (int bj = 0; bj < 2; ++bj) {
;                     f32x4 v0 = acc[ai][bj][m][0], v1 = acc[ai][bj][m][1];
; #pragma unroll
;                     for (int j = 0; j < 4; ++j) { const float a = fmaxf(v0[j], 0.f), b = fmaxf(v1[j], 0.f); v0[j] = a * a; v1[j] = b * b; }
;                     u32x4 w; w.x = cvt_pk_bf16(v0[0], v0[1]); w.y = cvt_pk_bf16(v0[2], v0[3]); w.z = cvt_pk_bf16(v1[0], v1[1]); w.w = cvt_pk_bf16(v1[2], v1[3]);
;                     *(u32x4*)(O + tiled_off(rowi, col0 + bj * HALF, DFF / 64)) = w;
;                 }
	v_mul_f32_e32 v72, v72, v72
	v_max_f32_e32 v73, 0, v73
	v_max_f32_e32 v74, 0, v79
	v_max_f32_e32 v75, 0, v75
	v_bitop3_b32 v80, v137, s24, v138 bitop3:0xde
	v_mul_f32_e32 v76, v76, v76
	v_mul_f32_e32 v73, v73, v73
	v_mul_f32_e32 v74, v74, v74
	v_mul_f32_e32 v75, v75, v75
	v_cvt_pk_bf16_f32 v72, v76, v72
	v_max_f32_e32 v64, 0, v64
	v_cvt_pk_bf16_f32 v73, v73, v74
	v_cvt_pk_bf16_f32 v74, v81, v77
	v_cvt_pk_bf16_f32 v75, v78, v75
	global_store_dwordx4 v80, v[72:75], s[20:21] nt
	v_max_f32_e32 v65, 0, v65
	v_max_f32_e32 v66, 0, v66
	v_mul_f32_e32 v72, v64, v64
	v_max_f32_e32 v64, 0, v69
	v_mul_f32_e32 v69, v65, v65
	v_max_f32_e32 v65, v70, v70
	v_mul_f32_e32 v70, v66, v66
	v_max_f32_e32 v68, 0, v68
	v_mul_f32_e32 v64, v64, v64
	v_max_f32_e32 v65, 0, v65
	v_max_f32_e32 v66, 0, v71
	v_max_f32_e32 v67, 0, v67
	v_mul_f32_e32 v68, v68, v68
	v_mul_f32_e32 v65, v65, v65
	v_mul_f32_e32 v66, v66, v66
	v_mul_f32_e32 v67, v67, v67
	v_cvt_pk_bf16_f32 v64, v68, v64
	v_cvt_pk_bf16_f32 v65, v65, v66
	v_cvt_pk_bf16_f32 v66, v72, v69
	v_cvt_pk_bf16_f32 v67, v70, v67
	global_store_dwordx4 v80, v[64:67], s[22:23] nt
	s_nop 0
	v_max_f32_e32 v56, 0, v56
	v_add_u32_e32 v64, 0x80, v136
	v_and_b32_e32 v65, 0xffffff80, v64
	v_lshlrev_b32_e32 v66, 6, v64
	v_lshlrev_b32_e32 v64, 2, v64
	v_and_or_b32 v66, v66, s28, v133
	v_and_b32_e32 v64, 32, v64
	v_bitop3_b32 v152, v66, s46, v64 bitop3:0xde
	v_mul_f32_e32 v64, v56, v56
	v_max_f32_e32 v57, 0, v57
	v_max_f32_e32 v58, 0, v58
	v_max_f32_e32 v60, 0, v60
	v_max_f32_e32 v56, 0, v61
	v_mul_f32_e32 v61, v57, v57
	v_max_f32_e32 v57, v62, v62
	v_mul_f32_e32 v62, v58, v58
	v_mul_f32_e32 v60, v60, v60
	v_mul_f32_e32 v56, v56, v56
	v_max_f32_e32 v57, 0, v57
	v_max_f32_e32 v58, 0, v63
	v_mul_f32_e32 v57, v57, v57
	v_mul_f32_e32 v58, v58, v58
	v_cvt_pk_bf16_f32 v56, v60, v56
	v_add_u32_e32 v60, s5, v65
	v_cvt_pk_bf16_f32 v57, v57, v58
	v_cvt_pk_bf16_f32 v58, v64, v61
	v_ashrrev_i32_e32 v61, 31, v60
	v_max_f32_e32 v59, 0, v59
	v_lshlrev_b64 v[60:61], 14, v[60:61]
	v_mul_f32_e32 v59, v59, v59
	v_lshl_add_u64 v[60:61], s[26:27], 0, v[60:61]
	v_cvt_pk_bf16_f32 v59, v62, v59
	v_lshl_add_u64 v[62:63], v[60:61], 0, v[152:153]
	v_max_f32_e32 v48, 0, v48
	global_store_dwordx4 v[62:63], v[56:59], off nt
	s_nop 0
	v_max_f32_e32 v49, 0, v49
	v_mul_f32_e32 v56, v48, v48
	v_max_f32_e32 v50, 0, v50
	v_max_f32_e32 v52, 0, v52
	v_max_f32_e32 v48, 0, v53
	v_mul_f32_e32 v53, v49, v49
	v_max_f32_e32 v49, v54, v54
	v_mul_f32_e32 v54, v50, v50
	v_mul_f32_e32 v52, v52, v52
	v_mul_f32_e32 v48, v48, v48
	v_max_f32_e32 v49, 0, v49
	v_max_f32_e32 v50, 0, v55
	v_mul_f32_e32 v49, v49, v49
	v_mul_f32_e32 v50, v50, v50
	v_cvt_pk_bf16_f32 v48, v52, v48
	v_add_u32_e32 v52, s15, v65
	v_cvt_pk_bf16_f32 v49, v49, v50
	v_cvt_pk_bf16_f32 v50, v56, v53
	v_ashrrev_i32_e32 v53, 31, v52
	v_max_f32_e32 v51, 0, v51
	v_lshlrev_b64 v[52:53], 14, v[52:53]
	v_mul_f32_e32 v51, v51, v51
	v_lshl_add_u64 v[52:53], s[26:27], 0, v[52:53]
	v_cvt_pk_bf16_f32 v51, v54, v51
	v_lshl_add_u64 v[54:55], v[52:53], 0, v[152:153]
	global_store_dwordx4 v[54:55], v[48:51], off nt
	s_nop 1
	v_add_u32_e32 v48, 0x90, v136
	v_lshrrev_b32_e32 v49, 3, v48
	v_and_or_b32 v49, v49, 10, s45
	v_lshlrev_b32_e32 v50, 6, v48
	v_lshlrev_b32_e32 v48, 2, v48
	v_and_or_b32 v50, v50, s28, v133
	v_lshlrev_b32_e32 v49, 10, v49
	v_and_b32_e32 v48, 32, v48
	v_max_f32_e32 v40, 0, v40
	v_max_f32_e32 v41, 0, v41
	v_max_f32_e32 v42, 0, v42
	v_bitop3_b32 v152, v50, v49, v48 bitop3:0xde
	v_mul_f32_e32 v48, v40, v40
	v_max_f32_e32 v40, v45, v45
	v_mul_f32_e32 v45, v41, v41
	v_max_f32_e32 v41, v46, v46
	v_mul_f32_e32 v46, v42, v42
	v_max_f32_e32 v44, 0, v44
	v_max_f32_e32 v40, 0, v40
	v_max_f32_e32 v41, 0, v41
	v_max_f32_e32 v42, 0, v47
	v_mul_f32_e32 v44, v44, v44
	v_mul_f32_e32 v40, v40, v40
	v_mul_f32_e32 v41, v41, v41
	v_max_f32_e32 v43, 0, v43
	v_mul_f32_e32 v42, v42, v42
	v_mul_f32_e32 v43, v43, v43
	v_cvt_pk_bf16_f32 v40, v44, v40
	v_cvt_pk_bf16_f32 v41, v41, v42
	v_cvt_pk_bf16_f32 v42, v48, v45
	v_lshl_add_u64 v[44:45], v[60:61], 0, v[152:153]
	v_max_f32_e32 v32, 0, v32
	v_max_f32_e32 v33, 0, v33
	v_max_f32_e32 v34, 0, v34
	v_cvt_pk_bf16_f32 v43, v46, v43
	global_store_dwordx4 v[44:45], v[40:43], off nt
	s_nop 0
	v_max_f32_e32 v36, 0, v36
	v_mul_f32_e32 v40, v32, v32
	v_max_f32_e32 v32, v37, v37
	v_mul_f32_e32 v37, v33, v33
; __device__ __forceinline__ unsigned cvt_pk_bf16(float lo, float hi) { unsigned r; asm volatile("v_cvt_pk_bf16_f32 %0, %1, %2" : "=v"(r) : "v"(lo), "v"(hi)); return r; }
; #define PG8_WAIT_V(n) asm volatile("s_waitcnt vmcnt(" #n ")" ::: "memory")
; #define PG8_BAR __builtin_amdgcn_s_barrier()
; template <class Epi>
; __device__ __forceinline__ void gemm_phase(LAS unsigned char* lds, const Gemm g, const StaticOrder& S, const Epi& E) {
;     ...
;         if (!has_next) break;
; #pragma unroll
;         for (int a = 0; a < 2; ++a)
; #pragma unroll
;             for (int b = 0; b < 2; ++b)
; #pragma unroll
;                 for (int m = 0; m < 4; ++m)
; #pragma unroll
;                     for (int n = 0; n < 2; ++n) acc[a][b][m][n] = (f32x4){0.f, 0.f, 0.f, 0.f};
;         cur = nxt; cA = nA; cB = nB; ++ui;
;     }
;     PG8_WAIT_V(0);
;     if (wr == 0) PG8_BAR;
;     __device__ __forceinline__ void operator()(const f32x4 (&acc)[2][2][4][2], const Unit& u, int wr, int wc, int fr, int fq) const {
;         const int row0 = u.pm * BM + wr * 64 + fr, col0 = u.pn * BM + wc * 32 + 8 * fq;
; #pragma unroll
;         for (int ai = 0; ai < 2; ++ai)
; #pragma unroll
;             for (int m = 0; m < 4; ++m) {
;                 const int rowi = row0 + ai * HALF + m * 16;
; #pragma unroll
;                 for (int bj = 0; bj < 2; ++bj) {
;                     f32x4 v0 = acc[ai][bj][m][0], v1 = acc[ai][bj][m][1];
; #pragma unroll
;                     for (int j = 0; j < 4; ++j) { const float a = fmaxf(v0[j], 0.f), b = fmaxf(v1[j], 0.f); v0[j] = a * a; v1[j] = b * b; }
;                     u32x4 w; w.x = cvt_pk_bf16(v0[0], v0[1]); w.y = cvt_pk_bf16(v0[2], v0[3]); w.z = cvt_pk_bf16(v1[0], v1[1]); w.w = cvt_pk_bf16(v1[2], v1[3]);
;                     *(u32x4*)(O + tiled_off(rowi, col0 + bj * HALF, DFF / 64)) = w;
;                 }
	v_max_f32_e32 v33, v38, v38
	v_mul_f32_e32 v38, v34, v34
	v_max_f32_e32 v32, 0, v32
	v_max_f32_e32 v33, 0, v33
	v_max_f32_e32 v34, 0, v39
	v_mul_f32_e32 v36, v36, v36
	v_mul_f32_e32 v32, v32, v32
	v_mul_f32_e32 v33, v33, v33
	v_max_f32_e32 v35, 0, v35
	v_mul_f32_e32 v34, v34, v34
	v_mul_f32_e32 v35, v35, v35
	v_cvt_pk_bf16_f32 v32, v36, v32
	v_cvt_pk_bf16_f32 v33, v33, v34
	v_cvt_pk_bf16_f32 v34, v40, v37
	v_lshl_add_u64 v[36:37], v[52:53], 0, v[152:153]
	v_cvt_pk_bf16_f32 v35, v38, v35
	global_store_dwordx4 v[36:37], v[32:35], off nt
	s_nop 1
	v_add_u32_e32 v32, 0xa0, v136
	v_lshrrev_b32_e32 v33, 3, v32
	v_and_or_b32 v33, v33, 12, s45
	v_lshlrev_b32_e32 v34, 6, v32
	v_lshlrev_b32_e32 v32, 2, v32
	v_and_or_b32 v34, v34, s28, v133
	v_lshlrev_b32_e32 v33, 10, v33
	v_and_b32_e32 v32, 32, v32
	v_max_f32_e32 v24, 0, v24
	v_max_f32_e32 v25, 0, v25
	v_max_f32_e32 v26, 0, v26
	v_bitop3_b32 v152, v34, v33, v32 bitop3:0xde
	v_mul_f32_e32 v32, v24, v24
	v_max_f32_e32 v24, v29, v29
	v_mul_f32_e32 v29, v25, v25
	v_max_f32_e32 v25, v30, v30
	v_mul_f32_e32 v30, v26, v26
	v_max_f32_e32 v28, 0, v28
	v_max_f32_e32 v24, 0, v24
	v_max_f32_e32 v25, 0, v25
	v_max_f32_e32 v26, 0, v31
	v_mul_f32_e32 v28, v28, v28
	v_mul_f32_e32 v24, v24, v24
	v_mul_f32_e32 v25, v25, v25
	v_max_f32_e32 v27, 0, v27
	v_mul_f32_e32 v26, v26, v26
	v_mul_f32_e32 v27, v27, v27
	v_cvt_pk_bf16_f32 v24, v28, v24
	v_cvt_pk_bf16_f32 v25, v25, v26
	v_cvt_pk_bf16_f32 v26, v32, v29
	v_lshl_add_u64 v[28:29], v[60:61], 0, v[152:153]
	v_max_f32_e32 v16, 0, v16
	v_max_f32_e32 v17, 0, v17
	v_max_f32_e32 v18, 0, v18
	v_cvt_pk_bf16_f32 v27, v30, v27
	global_store_dwordx4 v[28:29], v[24:27], off nt
	s_nop 0
	v_max_f32_e32 v20, 0, v20
	v_mul_f32_e32 v24, v16, v16
	v_max_f32_e32 v16, v21, v21
	v_mul_f32_e32 v21, v17, v17
	v_max_f32_e32 v17, v22, v22
	v_mul_f32_e32 v22, v18, v18
	v_max_f32_e32 v16, 0, v16
	v_max_f32_e32 v17, 0, v17
	v_max_f32_e32 v18, 0, v23
	v_mul_f32_e32 v20, v20, v20
	v_mul_f32_e32 v16, v16, v16
	v_mul_f32_e32 v17, v17, v17
	v_max_f32_e32 v19, 0, v19
	v_mul_f32_e32 v18, v18, v18
	v_mul_f32_e32 v19, v19, v19
	v_cvt_pk_bf16_f32 v16, v20, v16
	v_cvt_pk_bf16_f32 v17, v17, v18
	v_cvt_pk_bf16_f32 v18, v24, v21
	v_lshl_add_u64 v[20:21], v[52:53], 0, v[152:153]
	v_cvt_pk_bf16_f32 v19, v22, v19
	global_store_dwordx4 v[20:21], v[16:19], off nt
	s_nop 1
	v_add_u32_e32 v16, 0xb0, v136
	v_lshrrev_b32_e32 v17, 3, v16
	v_and_or_b32 v17, v17, 14, s45
	v_lshlrev_b32_e32 v18, 6, v16
	v_lshlrev_b32_e32 v16, 2, v16
	v_and_or_b32 v18, v18, s28, v133
	v_lshlrev_b32_e32 v17, 10, v17
	v_and_b32_e32 v16, 32, v16
	v_max_f32_e32 v8, 0, v8
	v_max_f32_e32 v9, 0, v9
	v_max_f32_e32 v10, 0, v10
	v_bitop3_b32 v152, v18, v17, v16 bitop3:0xde
	v_mul_f32_e32 v16, v8, v8
	v_max_f32_e32 v8, v13, v13
	v_mul_f32_e32 v13, v9, v9
	v_max_f32_e32 v9, v14, v14
	v_mul_f32_e32 v14, v10, v10
	v_max_f32_e32 v12, 0, v12
	v_max_f32_e32 v8, 0, v8
	v_max_f32_e32 v9, 0, v9
	v_max_f32_e32 v10, 0, v15
	v_mul_f32_e32 v12, v12, v12
	v_mul_f32_e32 v8, v8, v8
	v_mul_f32_e32 v9, v9, v9
	v_max_f32_e32 v11, 0, v11
	v_mul_f32_e32 v10, v10, v10
	v_mul_f32_e32 v11, v11, v11
	v_cvt_pk_bf16_f32 v8, v12, v8
	v_cvt_pk_bf16_f32 v9, v9, v10
	v_cvt_pk_bf16_f32 v10, v16, v13
	v_lshl_add_u64 v[12:13], v[60:61], 0, v[152:153]
	v_max_f32_e32 v0, 0, v0
	v_max_f32_e32 v1, 0, v1
	v_max_f32_e32 v2, 0, v2
	v_cvt_pk_bf16_f32 v11, v14, v11
	global_store_dwordx4 v[12:13], v[8:11], off nt
	s_nop 0
	v_max_f32_e32 v4, 0, v4
	v_mul_f32_e32 v8, v0, v0
	v_max_f32_e32 v0, v5, v5
	v_mul_f32_e32 v5, v1, v1
	v_max_f32_e32 v1, v6, v6
	v_mul_f32_e32 v6, v2, v2
	v_max_f32_e32 v0, 0, v0
	v_max_f32_e32 v1, 0, v1
	v_max_f32_e32 v2, 0, v7
	v_mul_f32_e32 v4, v4, v4
	v_mul_f32_e32 v0, v0, v0
	v_mul_f32_e32 v1, v1, v1
	v_max_f32_e32 v3, 0, v3
	v_mul_f32_e32 v2, v2, v2
	s_mov_b32 s54, 0xd00ab22c
	v_mul_f32_e32 v3, v3, v3
	v_cvt_pk_bf16_f32 v0, v4, v0
	v_cvt_pk_bf16_f32 v1, v1, v2
	v_cvt_pk_bf16_f32 v2, v8, v5
	v_lshl_add_u64 v[4:5], v[52:53], 0, v[152:153]
	s_and_b64 vcc, exec, s[0:1]
	s_mov_b32 s21, s4
	s_mov_b32 s20, s14
	s_mov_b64 s[24:25], s[18:19]
	s_mov_b64 s[22:23], s[16:17]
	s_mov_b32 s55, 0x3febb5fa
	v_cvt_pk_bf16_f32 v3, v6, v3
	global_store_dwordx4 v[4:5], v[0:3], off nt
	s_cbranch_vccz .LBB0_134
	s_waitcnt vmcnt(0)
	s_cmpk_gt_u32 s31, 0xff
	s_cbranch_scc1 .LBB0_145
	s_barrier

; #define PG8_STAGE(bufoff, gbase, voff) do { _Pragma("unroll") for (int _i = 0; _i < 2; ++_i) \
;         __builtin_amdgcn_global_load_lds((const unsigned*)((const char*)(gbase) + (voff)[_i]), (LAS unsigned*)(lds + (bufoff) + ldsw + _i * 8192), 16, 0, 0); } while (0)
; #define PG8_WAIT_V(n) asm volatile("s_waitcnt vmcnt(" #n ")" ::: "memory")
; #define PG8_WAIT_L(n) asm volatile("s_waitcnt lgkmcnt(" #n ")" ::: "memory")
; template <class Epi>
; __device__ __forceinline__ void gemm_phase(LAS unsigned char* lds, const Gemm g, const StaticOrder& S, const Epi& E) {
;     ...
;         const bool has_next = S.next(ui + 1, nxt);
;         const char* nA = has_next ? (const char*)g.A + (size_t)nxt.pm * tstepA : cA; const char* nB = has_next ? (const char*)g.Bt + (size_t)nxt.pn * tstepB : cB;
;         for (int t = 0; t < nt; t += 2) {
;             const bool last = (t == nt - 2);
;             const char* a1 = cA + (size_t)(t + 1) * kstep;
;             const char* a2 = last ? nA : cA + (size_t)(t + 2) * kstep; const char* b2 = last ? nB : cB + (size_t)(t + 2) * kstep;
;             const char* a3 = a2 + kstep; const char* b3 = b2 + kstep;
;             PG8_LDB(B0, 0, 0); PG8_SCHED; PG8_LDA(At, 0, 0); PG8_STAGE(PG8_SA(1, 1), a1 + hstepA, voffA);
;             PG8_WAIT_L(8); PG8_BAR; PG8_WAIT_L(0); PG8_MMA(0, 0, At, B0); PG8_BAR; PG8_SCHED;
;             PG8_LDB(B1, 0, 1); PG8_STAGE(PG8_SB(0, 0), b2, voffB);
;             PG8_BAR; PG8_WAIT_L(0); PG8_MMA(0, 1, At, B1); PG8_BAR;
;             PG8_LDA(At, 0, 1); PG8_STAGE(PG8_SA(0, 0), a2, voffA);
;             PG8_BAR; PG8_WAIT_L(0); PG8_MMA(1, 0, At, B0); PG8_BAR; PG8_SCHED;
;             PG8_STAGE(PG8_SB(0, 1), b2 + hstepB, voffB);
;             PG8_WAIT_V(6); PG8_BAR; PG8_MMA(1, 1, At, B1); PG8_BAR;
;             PG8_LDB(B0, 1, 0); PG8_SCHED; PG8_LDA(At, 1, 0); PG8_STAGE(PG8_SA(0, 1), a2 + hstepA, voffA);
;             PG8_WAIT_L(8); PG8_BAR; PG8_WAIT_L(0); PG8_MMA(0, 0, At, B0); PG8_BAR; PG8_SCHED;
;             PG8_LDB(B1, 1, 1); PG8_STAGE(PG8_SB(1, 0), b3, voffB);
;             PG8_BAR; PG8_WAIT_L(0); PG8_MMA(0, 1, At, B1); PG8_BAR;
;             PG8_LDA(At, 1, 1); PG8_STAGE(PG8_SA(1, 0), a3, voffA);
;             PG8_BAR; PG8_WAIT_L(0); PG8_MMA(1, 0, At, B0); PG8_BAR; PG8_SCHED;
;             PG8_STAGE(PG8_SB(1, 1), b3 + hstepB, voffB);
;             PG8_WAIT_V(6); PG8_BAR; PG8_MMA(1, 1, At, B1); PG8_BAR;
.LBB0_186:
	s_add_u32 s4, s24, 0x4000
	s_addc_u32 s5, s25, 0
	s_add_u32 s50, s22, 0x8000
	s_addc_u32 s51, s23, 0
	s_mov_b32 s22, 0
	s_add_i32 s54, s22, 2
	s_add_u32 s23, s4, 0x4000
	s_addc_u32 s24, s5, 0
	s_cmp_eq_u32 s40, s22
	s_cselect_b32 s26, s6, s23
	s_cselect_b32 s27, s7, s24
	s_cselect_b32 s24, s20, s50
	s_cselect_b32 s25, s21, s51
	s_add_u32 s22, s26, 0x4000
	s_addc_u32 s23, s27, 0
	s_add_i32 m0, s33, 0xc000
	v_lshl_add_u64 v[186:187], s[4:5], 0, v[158:159]
	global_load_lds_dwordx4 v[186:187], off nt
	s_add_i32 m0, s33, 0xe000
	v_lshl_add_u64 v[186:187], s[4:5], 0, v[160:161]
	global_load_lds_dwordx4 v[186:187], off nt
	s_mov_b32 s55, 0x10000
	v_add_u32_e32 v140, s55, v207
	ds_read_b128 v[128:131], v140
	ds_read_b128 v[136:139], v140 offset:2048
	ds_read_b128 v[132:135], v140 offset:1024
	ds_read_b128 v[140:143], v140 offset:3072
	ds_read_b128 v[144:147], v209
	ds_read_b128 v[162:165], v209 offset:2048
	ds_read_b128 v[170:173], v209 offset:4096
	ds_read_b128 v[178:181], v209 offset:6144
	ds_read_b128 v[148:151], v209 offset:1024
	ds_read_b128 v[166:169], v209 offset:3072
	ds_read_b128 v[174:177], v209 offset:5120
	ds_read_b128 v[182:185], v209 offset:7168
	s_mov_b32 s58, 0x14000
	s_add_i32 s55, s55, s31
	v_add_u32_e32 v198, s58, v207
	ds_read_b128 v[186:189], v198
	ds_read_b128 v[194:197], v198 offset:2048
	ds_read_b128 v[190:193], v198 offset:1024
	ds_read_b128 v[198:201], v198 offset:3072
	s_waitcnt lgkmcnt(0)
	s_barrier
	v_mfma_f32_16x16x32_bf16 v[124:127], v[128:131], v[144:147], 0
	s_setprio 1
	v_mfma_f32_16x16x32_bf16 v[120:123], v[136:139], v[144:147], 0
	v_mfma_f32_16x16x32_bf16 v[116:119], v[128:131], v[162:165], 0
	v_mfma_f32_16x16x32_bf16 v[112:115], v[136:139], v[162:165], 0
	v_mfma_f32_16x16x32_bf16 v[108:111], v[128:131], v[170:173], 0
	v_mfma_f32_16x16x32_bf16 v[104:107], v[136:139], v[170:173], 0
	v_mfma_f32_16x16x32_bf16 v[100:103], v[128:131], v[178:181], 0
	v_mfma_f32_16x16x32_bf16 v[96:99], v[136:139], v[178:181], 0
	v_mfma_f32_16x16x32_bf16 v[124:127], v[132:135], v[148:151], v[124:127]
	v_mfma_f32_16x16x32_bf16 v[120:123], v[140:143], v[148:151], v[120:123]
	v_mfma_f32_16x16x32_bf16 v[116:119], v[132:135], v[166:169], v[116:119]
	v_mfma_f32_16x16x32_bf16 v[112:115], v[140:143], v[166:169], v[112:115]
	v_mfma_f32_16x16x32_bf16 v[108:111], v[132:135], v[174:177], v[108:111]
	v_mfma_f32_16x16x32_bf16 v[104:107], v[140:143], v[174:177], v[104:107]
	v_mfma_f32_16x16x32_bf16 v[100:103], v[132:135], v[182:185], v[100:103]
	v_mfma_f32_16x16x32_bf16 v[96:99], v[140:143], v[182:185], v[96:99]
	v_mfma_f32_16x16x32_bf16 v[92:95], v[186:189], v[144:147], 0
	v_mfma_f32_16x16x32_bf16 v[88:91], v[194:197], v[144:147], 0
	v_mfma_f32_16x16x32_bf16 v[84:87], v[186:189], v[162:165], 0
	v_mfma_f32_16x16x32_bf16 v[80:83], v[194:197], v[162:165], 0
	v_mfma_f32_16x16x32_bf16 v[76:79], v[186:189], v[170:173], 0
	v_mfma_f32_16x16x32_bf16 v[72:75], v[194:197], v[170:173], 0
	v_mfma_f32_16x16x32_bf16 v[68:71], v[186:189], v[178:181], 0
	v_mfma_f32_16x16x32_bf16 v[64:67], v[194:197], v[178:181], 0
	v_mfma_f32_16x16x32_bf16 v[92:95], v[190:193], v[148:151], v[92:95]
	v_mfma_f32_16x16x32_bf16 v[88:91], v[198:201], v[148:151], v[88:91]
	v_mfma_f32_16x16x32_bf16 v[84:87], v[190:193], v[166:169], v[84:87]
	v_mfma_f32_16x16x32_bf16 v[80:83], v[198:201], v[166:169], v[80:83]
	v_mfma_f32_16x16x32_bf16 v[76:79], v[190:193], v[174:177], v[76:79]
	v_mfma_f32_16x16x32_bf16 v[72:75], v[198:201], v[174:177], v[72:75]
	v_mfma_f32_16x16x32_bf16 v[68:71], v[190:193], v[182:185], v[68:71]
	s_setprio 0
	v_mfma_f32_16x16x32_bf16 v[64:67], v[198:201], v[182:185], v[64:67]
	s_barrier
	s_mov_b32 m0, s55
	v_lshl_add_u64 v[202:203], s[24:25], 0, v[152:153]
	global_load_lds_dwordx4 v[202:203], off
	s_add_i32 m0, s55, 0x2000
	v_lshl_add_u64 v[202:203], s[24:25], 0, v[156:157]
	global_load_lds_dwordx4 v[202:203], off
	s_mov_b32 m0, s33
	v_lshl_add_u64 v[202:203], s[26:27], 0, v[152:153]
	global_load_lds_dwordx4 v[202:203], off nt
	s_mov_b32 m0, s34
	v_lshl_add_u64 v[202:203], s[26:27], 0, v[156:157]
	global_load_lds_dwordx4 v[202:203], off nt
	s_add_u32 s56, s24, s52
	s_addc_u32 s57, s25, 0
	s_add_i32 s55, s58, s31
	s_mov_b32 m0, s55
	v_lshl_add_u64 v[202:203], s[56:57], 0, v[152:153]
	global_load_lds_dwordx4 v[202:203], off
	s_add_i32 m0, s55, 0x2000
	v_lshl_add_u64 v[202:203], s[56:57], 0, v[156:157]
	global_load_lds_dwordx4 v[202:203], off
	ds_read_b128 v[144:147], v209 offset:16384
	ds_read_b128 v[162:165], v209 offset:18432
	ds_read_b128 v[170:173], v209 offset:20480
	ds_read_b128 v[178:181], v209 offset:22528
	ds_read_b128 v[148:151], v209 offset:17408
	ds_read_b128 v[166:169], v209 offset:19456
	ds_read_b128 v[174:177], v209 offset:21504
	ds_read_b128 v[182:185], v209 offset:23552
	s_waitcnt vmcnt(6)
	s_waitcnt lgkmcnt(0)
	s_barrier
; #define PG8_STAGE(bufoff, gbase, voff) do { _Pragma("unroll") for (int _i = 0; _i < 2; ++_i) \
;         __builtin_amdgcn_global_load_lds((const unsigned*)((const char*)(gbase) + (voff)[_i]), (LAS unsigned*)(lds + (bufoff) + ldsw + _i * 8192), 16, 0, 0); } while (0)
; #define PG8_LDA(dst, b, h) do { _Pragma("unroll") for (int m = 0; m < 4; ++m) _Pragma("unroll") for (int k = 0; k < 2; ++k) dst[m][k] = *(const LAS bf16x8*)(lds + PG8_SA(b, h) + aoff + m * 2048 + k * 1024); } while (0)
; #define PG8_WAIT_V(n) asm volatile("s_waitcnt vmcnt(" #n ")" ::: "memory")
; #define PG8_WAIT_L(n) asm volatile("s_waitcnt lgkmcnt(" #n ")" ::: "memory")
; template <class Epi>
; __device__ __forceinline__ void gemm_phase(LAS unsigned char* lds, const Gemm g, const StaticOrder& S, const Epi& E) {
;     ...
;         for (int t = 0; t < nt; t += 2) {
;             const bool last = (t == nt - 2);
;             const char* a1 = cA + (size_t)(t + 1) * kstep;
;             const char* a2 = last ? nA : cA + (size_t)(t + 2) * kstep; const char* b2 = last ? nB : cB + (size_t)(t + 2) * kstep;
;             const char* a3 = a2 + kstep; const char* b3 = b2 + kstep;
;             PG8_LDB(B0, 0, 0); PG8_SCHED; PG8_LDA(At, 0, 0); PG8_STAGE(PG8_SA(1, 1), a1 + hstepA, voffA);
;             PG8_WAIT_L(8); PG8_BAR; PG8_WAIT_L(0); PG8_MMA(0, 0, At, B0); PG8_BAR; PG8_SCHED;
;             PG8_LDB(B1, 0, 1); PG8_STAGE(PG8_SB(0, 0), b2, voffB);
;             PG8_BAR; PG8_WAIT_L(0); PG8_MMA(0, 1, At, B1); PG8_BAR;
;             PG8_LDA(At, 0, 1); PG8_STAGE(PG8_SA(0, 0), a2, voffA);
;             PG8_BAR; PG8_WAIT_L(0); PG8_MMA(1, 0, At, B0); PG8_BAR; PG8_SCHED;
;             PG8_STAGE(PG8_SB(0, 1), b2 + hstepB, voffB);
;             PG8_WAIT_V(6); PG8_BAR; PG8_MMA(1, 1, At, B1); PG8_BAR;
;             PG8_LDB(B0, 1, 0); PG8_SCHED; PG8_LDA(At, 1, 0); PG8_STAGE(PG8_SA(0, 1), a2 + hstepA, voffA);
;             PG8_WAIT_L(8); PG8_BAR; PG8_WAIT_L(0); PG8_MMA(0, 0, At, B0); PG8_BAR; PG8_SCHED;
;             PG8_LDB(B1, 1, 1); PG8_STAGE(PG8_SB(1, 0), b3, voffB);
;             PG8_BAR; PG8_WAIT_L(0); PG8_MMA(0, 1, At, B1); PG8_BAR;
;             PG8_LDA(At, 1, 1); PG8_STAGE(PG8_SA(1, 0), a3, voffA);
;             PG8_BAR; PG8_WAIT_L(0); PG8_MMA(1, 0, At, B0); PG8_BAR; PG8_SCHED;
;             PG8_STAGE(PG8_SB(1, 1), b3 + hstepB, voffB);
;             PG8_WAIT_V(6); PG8_BAR; PG8_MMA(1, 1, At, B1); PG8_BAR;
	v_mfma_f32_16x16x32_bf16 v[60:63], v[128:131], v[144:147], 0
	s_setprio 1
	v_mfma_f32_16x16x32_bf16 v[56:59], v[136:139], v[144:147], 0
	v_mfma_f32_16x16x32_bf16 v[52:55], v[128:131], v[162:165], 0
	v_mfma_f32_16x16x32_bf16 v[48:51], v[136:139], v[162:165], 0
	v_mfma_f32_16x16x32_bf16 v[44:47], v[128:131], v[170:173], 0
	v_mfma_f32_16x16x32_bf16 v[40:43], v[136:139], v[170:173], 0
	v_mfma_f32_16x16x32_bf16 v[36:39], v[128:131], v[178:181], 0
	v_mfma_f32_16x16x32_bf16 v[32:35], v[136:139], v[178:181], 0
	v_mfma_f32_16x16x32_bf16 v[60:63], v[132:135], v[148:151], v[60:63]
	v_mfma_f32_16x16x32_bf16 v[56:59], v[140:143], v[148:151], v[56:59]
	v_mfma_f32_16x16x32_bf16 v[52:55], v[132:135], v[166:169], v[52:55]
	v_mfma_f32_16x16x32_bf16 v[48:51], v[140:143], v[166:169], v[48:51]
	v_mfma_f32_16x16x32_bf16 v[44:47], v[132:135], v[174:177], v[44:47]
	v_mfma_f32_16x16x32_bf16 v[40:43], v[140:143], v[174:177], v[40:43]
	v_mfma_f32_16x16x32_bf16 v[36:39], v[132:135], v[182:185], v[36:39]
	v_mfma_f32_16x16x32_bf16 v[32:35], v[140:143], v[182:185], v[32:35]
	v_mfma_f32_16x16x32_bf16 v[28:31], v[186:189], v[144:147], 0
	v_mfma_f32_16x16x32_bf16 v[24:27], v[194:197], v[144:147], 0
	s_add_i32 s55, 0, 0x18000
	v_add_u32_e32 v140, s55, v207
	v_mfma_f32_16x16x32_bf16 v[20:23], v[186:189], v[162:165], 0
	v_mfma_f32_16x16x32_bf16 v[16:19], v[194:197], v[162:165], 0
	v_mfma_f32_16x16x32_bf16 v[12:15], v[186:189], v[170:173], 0
	v_mfma_f32_16x16x32_bf16 v[8:11], v[194:197], v[170:173], 0
	v_mfma_f32_16x16x32_bf16 v[4:7], v[186:189], v[178:181], 0
	v_mfma_f32_16x16x32_bf16 v[0:3], v[194:197], v[178:181], 0
	v_mfma_f32_16x16x32_bf16 v[28:31], v[190:193], v[148:151], v[28:31]
	v_mfma_f32_16x16x32_bf16 v[24:27], v[198:201], v[148:151], v[24:27]
	v_mfma_f32_16x16x32_bf16 v[20:23], v[190:193], v[166:169], v[20:23]
	v_mfma_f32_16x16x32_bf16 v[16:19], v[198:201], v[166:169], v[16:19]
	v_mfma_f32_16x16x32_bf16 v[12:15], v[190:193], v[174:177], v[12:15]
	v_mfma_f32_16x16x32_bf16 v[8:11], v[198:201], v[174:177], v[8:11]
	v_mfma_f32_16x16x32_bf16 v[4:7], v[190:193], v[182:185], v[4:7]
	s_setprio 0
	v_mfma_f32_16x16x32_bf16 v[0:3], v[198:201], v[182:185], v[0:3]
	s_barrier
	s_add_u32 s26, s26, s52
	s_addc_u32 s27, s27, 0
	s_mov_b32 m0, s35
	v_lshl_add_u64 v[186:187], s[26:27], 0, v[152:153]
	global_load_lds_dwordx4 v[186:187], off nt
	s_mov_b32 m0, s36
	v_lshl_add_u64 v[186:187], s[26:27], 0, v[156:157]
	global_load_lds_dwordx4 v[186:187], off nt
	ds_read_b128 v[128:131], v140
	ds_read_b128 v[136:139], v140 offset:2048
	ds_read_b128 v[132:135], v140 offset:1024
	ds_read_b128 v[140:143], v140 offset:3072
	ds_read_b128 v[144:147], v209 offset:32768
	ds_read_b128 v[162:165], v209 offset:34816
	ds_read_b128 v[170:173], v209 offset:36864
	ds_read_b128 v[178:181], v209 offset:38912
	ds_read_b128 v[148:151], v209 offset:33792
	ds_read_b128 v[166:169], v209 offset:35840
	ds_read_b128 v[174:177], v209 offset:37888
	ds_read_b128 v[182:185], v209 offset:39936
	s_mov_b32 s26, 0x1c000
	s_add_u32 s24, s24, 0x4000
	s_addc_u32 s25, s25, 0
	s_add_i32 s27, s55, s31
	v_add_u32_e32 v198, s26, v207
	ds_read_b128 v[186:189], v198
	ds_read_b128 v[194:197], v198 offset:2048
	ds_read_b128 v[190:193], v198 offset:1024
	ds_read_b128 v[198:201], v198 offset:3072
	s_waitcnt lgkmcnt(0)
	s_barrier
	v_mfma_f32_16x16x32_bf16 v[124:127], v[128:131], v[144:147], v[124:127]
	s_setprio 1
	v_mfma_f32_16x16x32_bf16 v[120:123], v[136:139], v[144:147], v[120:123]
	v_mfma_f32_16x16x32_bf16 v[116:119], v[128:131], v[162:165], v[116:119]
	v_mfma_f32_16x16x32_bf16 v[112:115], v[136:139], v[162:165], v[112:115]
	v_mfma_f32_16x16x32_bf16 v[108:111], v[128:131], v[170:173], v[108:111]
	v_mfma_f32_16x16x32_bf16 v[104:107], v[136:139], v[170:173], v[104:107]
	v_mfma_f32_16x16x32_bf16 v[100:103], v[128:131], v[178:181], v[100:103]
	v_mfma_f32_16x16x32_bf16 v[96:99], v[136:139], v[178:181], v[96:99]
	v_mfma_f32_16x16x32_bf16 v[124:127], v[132:135], v[148:151], v[124:127]
	v_mfma_f32_16x16x32_bf16 v[120:123], v[140:143], v[148:151], v[120:123]
	v_mfma_f32_16x16x32_bf16 v[116:119], v[132:135], v[166:169], v[116:119]
	v_mfma_f32_16x16x32_bf16 v[112:115], v[140:143], v[166:169], v[112:115]
	v_mfma_f32_16x16x32_bf16 v[108:111], v[132:135], v[174:177], v[108:111]
	v_mfma_f32_16x16x32_bf16 v[104:107], v[140:143], v[174:177], v[104:107]
	v_mfma_f32_16x16x32_bf16 v[100:103], v[132:135], v[182:185], v[100:103]
	v_mfma_f32_16x16x32_bf16 v[96:99], v[140:143], v[182:185], v[96:99]
	v_mfma_f32_16x16x32_bf16 v[92:95], v[186:189], v[144:147], v[92:95]
	v_mfma_f32_16x16x32_bf16 v[88:91], v[194:197], v[144:147], v[88:91]
	v_mfma_f32_16x16x32_bf16 v[84:87], v[186:189], v[162:165], v[84:87]
	v_mfma_f32_16x16x32_bf16 v[80:83], v[194:197], v[162:165], v[80:83]
	v_mfma_f32_16x16x32_bf16 v[76:79], v[186:189], v[170:173], v[76:79]
	v_mfma_f32_16x16x32_bf16 v[72:75], v[194:197], v[170:173], v[72:75]
	v_mfma_f32_16x16x32_bf16 v[68:71], v[186:189], v[178:181], v[68:71]
	v_mfma_f32_16x16x32_bf16 v[64:67], v[194:197], v[178:181], v[64:67]
	v_mfma_f32_16x16x32_bf16 v[92:95], v[190:193], v[148:151], v[92:95]
	v_mfma_f32_16x16x32_bf16 v[88:91], v[198:201], v[148:151], v[88:91]
	v_mfma_f32_16x16x32_bf16 v[84:87], v[190:193], v[166:169], v[84:87]
	v_mfma_f32_16x16x32_bf16 v[80:83], v[198:201], v[166:169], v[80:83]
	v_mfma_f32_16x16x32_bf16 v[76:79], v[190:193], v[174:177], v[76:79]
	v_mfma_f32_16x16x32_bf16 v[72:75], v[198:201], v[174:177], v[72:75]
	v_mfma_f32_16x16x32_bf16 v[68:71], v[190:193], v[182:185], v[68:71]
	s_setprio 0
	v_mfma_f32_16x16x32_bf16 v[64:67], v[198:201], v[182:185], v[64:67]
	s_barrier
; #define PG8_STAGE(bufoff, gbase, voff) do { _Pragma("unroll") for (int _i = 0; _i < 2; ++_i) \
;         __builtin_amdgcn_global_load_lds((const unsigned*)((const char*)(gbase) + (voff)[_i]), (LAS unsigned*)(lds + (bufoff) + ldsw + _i * 8192), 16, 0, 0); } while (0)
; #define PG8_LDA(dst, b, h) do { _Pragma("unroll") for (int m = 0; m < 4; ++m) _Pragma("unroll") for (int k = 0; k < 2; ++k) dst[m][k] = *(const LAS bf16x8*)(lds + PG8_SA(b, h) + aoff + m * 2048 + k * 1024); } while (0)
; #define PG8_WAIT_V(n) asm volatile("s_waitcnt vmcnt(" #n ")" ::: "memory")
; #define PG8_WAIT_L(n) asm volatile("s_waitcnt lgkmcnt(" #n ")" ::: "memory")
; template <class Epi>
; __device__ __forceinline__ void gemm_phase(LAS unsigned char* lds, const Gemm g, const StaticOrder& S, const Epi& E) {
;     ...
;         for (int t = 0; t < nt; t += 2) {
;             const bool last = (t == nt - 2);
;             const char* a1 = cA + (size_t)(t + 1) * kstep;
;             const char* a2 = last ? nA : cA + (size_t)(t + 2) * kstep; const char* b2 = last ? nB : cB + (size_t)(t + 2) * kstep;
;             const char* a3 = a2 + kstep; const char* b3 = b2 + kstep;
;             PG8_LDB(B0, 0, 0); PG8_SCHED; PG8_LDA(At, 0, 0); PG8_STAGE(PG8_SA(1, 1), a1 + hstepA, voffA);
;             PG8_WAIT_L(8); PG8_BAR; PG8_WAIT_L(0); PG8_MMA(0, 0, At, B0); PG8_BAR; PG8_SCHED;
;             PG8_LDB(B1, 0, 1); PG8_STAGE(PG8_SB(0, 0), b2, voffB);
;             PG8_BAR; PG8_WAIT_L(0); PG8_MMA(0, 1, At, B1); PG8_BAR;
;             PG8_LDA(At, 0, 1); PG8_STAGE(PG8_SA(0, 0), a2, voffA);
;             PG8_BAR; PG8_WAIT_L(0); PG8_MMA(1, 0, At, B0); PG8_BAR; PG8_SCHED;
;             PG8_STAGE(PG8_SB(0, 1), b2 + hstepB, voffB);
;             PG8_WAIT_V(6); PG8_BAR; PG8_MMA(1, 1, At, B1); PG8_BAR;
;             PG8_LDB(B0, 1, 0); PG8_SCHED; PG8_LDA(At, 1, 0); PG8_STAGE(PG8_SA(0, 1), a2 + hstepA, voffA);
;             PG8_WAIT_L(8); PG8_BAR; PG8_WAIT_L(0); PG8_MMA(0, 0, At, B0); PG8_BAR; PG8_SCHED;
;             PG8_LDB(B1, 1, 1); PG8_STAGE(PG8_SB(1, 0), b3, voffB);
;             PG8_BAR; PG8_WAIT_L(0); PG8_MMA(0, 1, At, B1); PG8_BAR;
;             PG8_LDA(At, 1, 1); PG8_STAGE(PG8_SA(1, 0), a3, voffA);
;             PG8_BAR; PG8_WAIT_L(0); PG8_MMA(1, 0, At, B0); PG8_BAR; PG8_SCHED;
;             PG8_STAGE(PG8_SB(1, 1), b3 + hstepB, voffB);
;             PG8_WAIT_V(6); PG8_BAR; PG8_MMA(1, 1, At, B1); PG8_BAR;
	s_mov_b32 m0, s27
	v_lshl_add_u64 v[202:203], s[24:25], 0, v[152:153]
	global_load_lds_dwordx4 v[202:203], off
	s_add_i32 m0, s27, 0x2000
	v_lshl_add_u64 v[202:203], s[24:25], 0, v[156:157]
	global_load_lds_dwordx4 v[202:203], off
	s_mov_b32 m0, s38
	v_lshl_add_u64 v[202:203], s[22:23], 0, v[152:153]
	global_load_lds_dwordx4 v[202:203], off nt
	s_mov_b32 m0, s39
	v_lshl_add_u64 v[202:203], s[22:23], 0, v[156:157]
	global_load_lds_dwordx4 v[202:203], off nt
	s_add_u32 s22, s24, s52
	s_addc_u32 s23, s25, 0
	s_add_i32 s24, s26, s31
	s_mov_b32 m0, s24
	v_lshl_add_u64 v[202:203], s[22:23], 0, v[152:153]
	global_load_lds_dwordx4 v[202:203], off
	s_add_i32 m0, s24, 0x2000
	v_lshl_add_u64 v[202:203], s[22:23], 0, v[156:157]
	global_load_lds_dwordx4 v[202:203], off
	ds_read_b128 v[144:147], v209 offset:49152
	ds_read_b128 v[162:165], v209 offset:51200
	ds_read_b128 v[170:173], v209 offset:53248
	ds_read_b128 v[178:181], v209 offset:55296
	ds_read_b128 v[148:151], v209 offset:50176
	ds_read_b128 v[166:169], v209 offset:52224
	ds_read_b128 v[174:177], v209 offset:54272
	ds_read_b128 v[182:185], v209 offset:56320
	s_waitcnt vmcnt(6)
	s_waitcnt lgkmcnt(0)
	s_barrier
	v_mfma_f32_16x16x32_bf16 v[60:63], v[128:131], v[144:147], v[60:63]
	s_setprio 1
	v_mfma_f32_16x16x32_bf16 v[56:59], v[136:139], v[144:147], v[56:59]
	v_mfma_f32_16x16x32_bf16 v[52:55], v[128:131], v[162:165], v[52:55]
	v_mfma_f32_16x16x32_bf16 v[48:51], v[136:139], v[162:165], v[48:51]
	v_mfma_f32_16x16x32_bf16 v[44:47], v[128:131], v[170:173], v[44:47]
	v_mfma_f32_16x16x32_bf16 v[40:43], v[136:139], v[170:173], v[40:43]
	v_mfma_f32_16x16x32_bf16 v[36:39], v[128:131], v[178:181], v[36:39]
	v_mfma_f32_16x16x32_bf16 v[32:35], v[136:139], v[178:181], v[32:35]
	v_mfma_f32_16x16x32_bf16 v[60:63], v[132:135], v[148:151], v[60:63]
	v_mfma_f32_16x16x32_bf16 v[56:59], v[140:143], v[148:151], v[56:59]
	v_mfma_f32_16x16x32_bf16 v[52:55], v[132:135], v[166:169], v[52:55]
	v_mfma_f32_16x16x32_bf16 v[48:51], v[140:143], v[166:169], v[48:51]
	v_mfma_f32_16x16x32_bf16 v[44:47], v[132:135], v[174:177], v[44:47]
	v_mfma_f32_16x16x32_bf16 v[40:43], v[140:143], v[174:177], v[40:43]
	v_mfma_f32_16x16x32_bf16 v[36:39], v[132:135], v[182:185], v[36:39]
	v_mfma_f32_16x16x32_bf16 v[32:35], v[140:143], v[182:185], v[32:35]
	v_mfma_f32_16x16x32_bf16 v[28:31], v[186:189], v[144:147], v[28:31]
	v_mfma_f32_16x16x32_bf16 v[24:27], v[194:197], v[144:147], v[24:27]
	s_add_u32 s4, s4, 0x8000
	s_addc_u32 s5, s5, 0
	s_add_u32 s50, s50, 0x8000
	s_addc_u32 s51, s51, 0
	v_mfma_f32_16x16x32_bf16 v[20:23], v[186:189], v[162:165], v[20:23]
	v_mfma_f32_16x16x32_bf16 v[16:19], v[194:197], v[162:165], v[16:19]
	v_mfma_f32_16x16x32_bf16 v[12:15], v[186:189], v[170:173], v[12:15]
	v_mfma_f32_16x16x32_bf16 v[8:11], v[194:197], v[170:173], v[8:11]
	v_mfma_f32_16x16x32_bf16 v[4:7], v[186:189], v[178:181], v[4:7]
	v_mfma_f32_16x16x32_bf16 v[0:3], v[194:197], v[178:181], v[0:3]
	v_mfma_f32_16x16x32_bf16 v[28:31], v[190:193], v[148:151], v[28:31]
	v_mfma_f32_16x16x32_bf16 v[24:27], v[198:201], v[148:151], v[24:27]
	v_mfma_f32_16x16x32_bf16 v[20:23], v[190:193], v[166:169], v[20:23]
	v_mfma_f32_16x16x32_bf16 v[16:19], v[198:201], v[166:169], v[16:19]
	v_mfma_f32_16x16x32_bf16 v[12:15], v[190:193], v[174:177], v[12:15]
	v_mfma_f32_16x16x32_bf16 v[8:11], v[198:201], v[174:177], v[8:11]
	v_mfma_f32_16x16x32_bf16 v[4:7], v[190:193], v[182:185], v[4:7]
	s_cmp_ge_u32 s54, s28
	s_mov_b32 s22, s54
	s_setprio 0
	v_mfma_f32_16x16x32_bf16 v[0:3], v[198:201], v[182:185], v[0:3]
	s_cbranch_scc1 .Lrot_exit_187
.LBB0_187:
	s_barrier
	s_add_i32 s54, s22, 2
	s_add_u32 s23, s4, 0x4000
	s_addc_u32 s24, s5, 0
	s_cmp_eq_u32 s40, s22
	s_cselect_b32 s26, s6, s23
	s_cselect_b32 s27, s7, s24
	s_cselect_b32 s24, s20, s50
	s_cselect_b32 s25, s21, s51
	s_add_u32 s22, s26, 0x4000
	s_addc_u32 s23, s27, 0
	s_add_i32 m0, s33, 0xc000
	v_lshl_add_u64 v[186:187], s[4:5], 0, v[158:159]
	global_load_lds_dwordx4 v[186:187], off nt
	s_add_i32 m0, s33, 0xe000
	v_lshl_add_u64 v[186:187], s[4:5], 0, v[160:161]
	global_load_lds_dwordx4 v[186:187], off nt
	s_mov_b32 s55, 0x10000
	v_add_u32_e32 v140, s55, v207
	ds_read_b128 v[128:131], v140
	ds_read_b128 v[136:139], v140 offset:2048
	ds_read_b128 v[132:135], v140 offset:1024
	ds_read_b128 v[140:143], v140 offset:3072
	ds_read_b128 v[144:147], v209
	ds_read_b128 v[162:165], v209 offset:2048
	ds_read_b128 v[170:173], v209 offset:4096
	ds_read_b128 v[178:181], v209 offset:6144
	ds_read_b128 v[148:151], v209 offset:1024
	ds_read_b128 v[166:169], v209 offset:3072
	ds_read_b128 v[174:177], v209 offset:5120
	ds_read_b128 v[182:185], v209 offset:7168
	s_mov_b32 s58, 0x14000
	s_add_i32 s55, s55, s31
	v_add_u32_e32 v198, s58, v207
	ds_read_b128 v[186:189], v198
	ds_read_b128 v[194:197], v198 offset:2048
	ds_read_b128 v[190:193], v198 offset:1024
	ds_read_b128 v[198:201], v198 offset:3072
	s_waitcnt lgkmcnt(0)
	s_barrier
; #define PG8_STAGE(bufoff, gbase, voff) do { _Pragma("unroll") for (int _i = 0; _i < 2; ++_i) \
;         __builtin_amdgcn_global_load_lds((const unsigned*)((const char*)(gbase) + (voff)[_i]), (LAS unsigned*)(lds + (bufoff) + ldsw + _i * 8192), 16, 0, 0); } while (0)
; #define PG8_LDA(dst, b, h) do { _Pragma("unroll") for (int m = 0; m < 4; ++m) _Pragma("unroll") for (int k = 0; k < 2; ++k) dst[m][k] = *(const LAS bf16x8*)(lds + PG8_SA(b, h) + aoff + m * 2048 + k * 1024); } while (0)
; #define PG8_WAIT_V(n) asm volatile("s_waitcnt vmcnt(" #n ")" ::: "memory")
; #define PG8_WAIT_L(n) asm volatile("s_waitcnt lgkmcnt(" #n ")" ::: "memory")
; template <class Epi>
; __device__ __forceinline__ void gemm_phase(LAS unsigned char* lds, const Gemm g, const StaticOrder& S, const Epi& E) {
;     ...
;         for (int t = 0; t < nt; t += 2) {
;             const bool last = (t == nt - 2);
;             const char* a1 = cA + (size_t)(t + 1) * kstep;
;             const char* a2 = last ? nA : cA + (size_t)(t + 2) * kstep; const char* b2 = last ? nB : cB + (size_t)(t + 2) * kstep;
;             const char* a3 = a2 + kstep; const char* b3 = b2 + kstep;
;             PG8_LDB(B0, 0, 0); PG8_SCHED; PG8_LDA(At, 0, 0); PG8_STAGE(PG8_SA(1, 1), a1 + hstepA, voffA);
;             PG8_WAIT_L(8); PG8_BAR; PG8_WAIT_L(0); PG8_MMA(0, 0, At, B0); PG8_BAR; PG8_SCHED;
;             PG8_LDB(B1, 0, 1); PG8_STAGE(PG8_SB(0, 0), b2, voffB);
;             PG8_BAR; PG8_WAIT_L(0); PG8_MMA(0, 1, At, B1); PG8_BAR;
;             PG8_LDA(At, 0, 1); PG8_STAGE(PG8_SA(0, 0), a2, voffA);
;             PG8_BAR; PG8_WAIT_L(0); PG8_MMA(1, 0, At, B0); PG8_BAR; PG8_SCHED;
;             PG8_STAGE(PG8_SB(0, 1), b2 + hstepB, voffB);
;             PG8_WAIT_V(6); PG8_BAR; PG8_MMA(1, 1, At, B1); PG8_BAR;
;             PG8_LDB(B0, 1, 0); PG8_SCHED; PG8_LDA(At, 1, 0); PG8_STAGE(PG8_SA(0, 1), a2 + hstepA, voffA);
;             PG8_WAIT_L(8); PG8_BAR; PG8_WAIT_L(0); PG8_MMA(0, 0, At, B0); PG8_BAR; PG8_SCHED;
;             PG8_LDB(B1, 1, 1); PG8_STAGE(PG8_SB(1, 0), b3, voffB);
;             PG8_BAR; PG8_WAIT_L(0); PG8_MMA(0, 1, At, B1); PG8_BAR;
;             PG8_LDA(At, 1, 1); PG8_STAGE(PG8_SA(1, 0), a3, voffA);
;             PG8_BAR; PG8_WAIT_L(0); PG8_MMA(1, 0, At, B0); PG8_BAR; PG8_SCHED;
;             PG8_STAGE(PG8_SB(1, 1), b3 + hstepB, voffB);
;             PG8_WAIT_V(6); PG8_BAR; PG8_MMA(1, 1, At, B1); PG8_BAR;
	v_mfma_f32_16x16x32_bf16 v[124:127], v[128:131], v[144:147], v[124:127]
	s_setprio 1
	v_mfma_f32_16x16x32_bf16 v[120:123], v[136:139], v[144:147], v[120:123]
	v_mfma_f32_16x16x32_bf16 v[116:119], v[128:131], v[162:165], v[116:119]
	v_mfma_f32_16x16x32_bf16 v[112:115], v[136:139], v[162:165], v[112:115]
	v_mfma_f32_16x16x32_bf16 v[108:111], v[128:131], v[170:173], v[108:111]
	v_mfma_f32_16x16x32_bf16 v[104:107], v[136:139], v[170:173], v[104:107]
	v_mfma_f32_16x16x32_bf16 v[100:103], v[128:131], v[178:181], v[100:103]
	v_mfma_f32_16x16x32_bf16 v[96:99], v[136:139], v[178:181], v[96:99]
	v_mfma_f32_16x16x32_bf16 v[124:127], v[132:135], v[148:151], v[124:127]
	v_mfma_f32_16x16x32_bf16 v[120:123], v[140:143], v[148:151], v[120:123]
	v_mfma_f32_16x16x32_bf16 v[116:119], v[132:135], v[166:169], v[116:119]
	v_mfma_f32_16x16x32_bf16 v[112:115], v[140:143], v[166:169], v[112:115]
	v_mfma_f32_16x16x32_bf16 v[108:111], v[132:135], v[174:177], v[108:111]
	v_mfma_f32_16x16x32_bf16 v[104:107], v[140:143], v[174:177], v[104:107]
	v_mfma_f32_16x16x32_bf16 v[100:103], v[132:135], v[182:185], v[100:103]
	v_mfma_f32_16x16x32_bf16 v[96:99], v[140:143], v[182:185], v[96:99]
	v_mfma_f32_16x16x32_bf16 v[92:95], v[186:189], v[144:147], v[92:95]
	v_mfma_f32_16x16x32_bf16 v[88:91], v[194:197], v[144:147], v[88:91]
	v_mfma_f32_16x16x32_bf16 v[84:87], v[186:189], v[162:165], v[84:87]
	v_mfma_f32_16x16x32_bf16 v[80:83], v[194:197], v[162:165], v[80:83]
	v_mfma_f32_16x16x32_bf16 v[76:79], v[186:189], v[170:173], v[76:79]
	v_mfma_f32_16x16x32_bf16 v[72:75], v[194:197], v[170:173], v[72:75]
	v_mfma_f32_16x16x32_bf16 v[68:71], v[186:189], v[178:181], v[68:71]
	v_mfma_f32_16x16x32_bf16 v[64:67], v[194:197], v[178:181], v[64:67]
	v_mfma_f32_16x16x32_bf16 v[92:95], v[190:193], v[148:151], v[92:95]
	v_mfma_f32_16x16x32_bf16 v[88:91], v[198:201], v[148:151], v[88:91]
	v_mfma_f32_16x16x32_bf16 v[84:87], v[190:193], v[166:169], v[84:87]
	v_mfma_f32_16x16x32_bf16 v[80:83], v[198:201], v[166:169], v[80:83]
	v_mfma_f32_16x16x32_bf16 v[76:79], v[190:193], v[174:177], v[76:79]
	v_mfma_f32_16x16x32_bf16 v[72:75], v[198:201], v[174:177], v[72:75]
	v_mfma_f32_16x16x32_bf16 v[68:71], v[190:193], v[182:185], v[68:71]
	s_setprio 0
	v_mfma_f32_16x16x32_bf16 v[64:67], v[198:201], v[182:185], v[64:67]
	s_barrier
	s_mov_b32 m0, s55
	v_lshl_add_u64 v[202:203], s[24:25], 0, v[152:153]
	global_load_lds_dwordx4 v[202:203], off
	s_add_i32 m0, s55, 0x2000
	v_lshl_add_u64 v[202:203], s[24:25], 0, v[156:157]
	global_load_lds_dwordx4 v[202:203], off
	s_mov_b32 m0, s33
	v_lshl_add_u64 v[202:203], s[26:27], 0, v[152:153]
	global_load_lds_dwordx4 v[202:203], off nt
	s_mov_b32 m0, s34
	v_lshl_add_u64 v[202:203], s[26:27], 0, v[156:157]
	global_load_lds_dwordx4 v[202:203], off nt
	s_add_u32 s56, s24, s52
	s_addc_u32 s57, s25, 0
	s_add_i32 s55, s58, s31
	s_mov_b32 m0, s55
	v_lshl_add_u64 v[202:203], s[56:57], 0, v[152:153]
	global_load_lds_dwordx4 v[202:203], off
	s_add_i32 m0, s55, 0x2000
	v_lshl_add_u64 v[202:203], s[56:57], 0, v[156:157]
	global_load_lds_dwordx4 v[202:203], off
	ds_read_b128 v[144:147], v209 offset:16384
	ds_read_b128 v[162:165], v209 offset:18432
	ds_read_b128 v[170:173], v209 offset:20480
	ds_read_b128 v[178:181], v209 offset:22528
	ds_read_b128 v[148:151], v209 offset:17408
	ds_read_b128 v[166:169], v209 offset:19456
	ds_read_b128 v[174:177], v209 offset:21504
	ds_read_b128 v[182:185], v209 offset:23552
	s_waitcnt vmcnt(6)
	s_waitcnt lgkmcnt(0)
	s_barrier
	v_mfma_f32_16x16x32_bf16 v[60:63], v[128:131], v[144:147], v[60:63]
	s_setprio 1
	v_mfma_f32_16x16x32_bf16 v[56:59], v[136:139], v[144:147], v[56:59]
	v_mfma_f32_16x16x32_bf16 v[52:55], v[128:131], v[162:165], v[52:55]
	v_mfma_f32_16x16x32_bf16 v[48:51], v[136:139], v[162:165], v[48:51]
	v_mfma_f32_16x16x32_bf16 v[44:47], v[128:131], v[170:173], v[44:47]
	v_mfma_f32_16x16x32_bf16 v[40:43], v[136:139], v[170:173], v[40:43]
	v_mfma_f32_16x16x32_bf16 v[36:39], v[128:131], v[178:181], v[36:39]
	v_mfma_f32_16x16x32_bf16 v[32:35], v[136:139], v[178:181], v[32:35]
	v_mfma_f32_16x16x32_bf16 v[60:63], v[132:135], v[148:151], v[60:63]
	v_mfma_f32_16x16x32_bf16 v[56:59], v[140:143], v[148:151], v[56:59]
	v_mfma_f32_16x16x32_bf16 v[52:55], v[132:135], v[166:169], v[52:55]
	v_mfma_f32_16x16x32_bf16 v[48:51], v[140:143], v[166:169], v[48:51]
	v_mfma_f32_16x16x32_bf16 v[44:47], v[132:135], v[174:177], v[44:47]
	v_mfma_f32_16x16x32_bf16 v[40:43], v[140:143], v[174:177], v[40:43]
	v_mfma_f32_16x16x32_bf16 v[36:39], v[132:135], v[182:185], v[36:39]
	v_mfma_f32_16x16x32_bf16 v[32:35], v[140:143], v[182:185], v[32:35]
	v_mfma_f32_16x16x32_bf16 v[28:31], v[186:189], v[144:147], v[28:31]
	v_mfma_f32_16x16x32_bf16 v[24:27], v[194:197], v[144:147], v[24:27]
	s_add_i32 s55, 0, 0x18000
	v_add_u32_e32 v140, s55, v207
	v_mfma_f32_16x16x32_bf16 v[20:23], v[186:189], v[162:165], v[20:23]
	v_mfma_f32_16x16x32_bf16 v[16:19], v[194:197], v[162:165], v[16:19]
	v_mfma_f32_16x16x32_bf16 v[12:15], v[186:189], v[170:173], v[12:15]
	v_mfma_f32_16x16x32_bf16 v[8:11], v[194:197], v[170:173], v[8:11]
	v_mfma_f32_16x16x32_bf16 v[4:7], v[186:189], v[178:181], v[4:7]
	v_mfma_f32_16x16x32_bf16 v[0:3], v[194:197], v[178:181], v[0:3]
	v_mfma_f32_16x16x32_bf16 v[28:31], v[190:193], v[148:151], v[28:31]
	v_mfma_f32_16x16x32_bf16 v[24:27], v[198:201], v[148:151], v[24:27]
	v_mfma_f32_16x16x32_bf16 v[20:23], v[190:193], v[166:169], v[20:23]
	v_mfma_f32_16x16x32_bf16 v[16:19], v[198:201], v[166:169], v[16:19]
	v_mfma_f32_16x16x32_bf16 v[12:15], v[190:193], v[174:177], v[12:15]
	v_mfma_f32_16x16x32_bf16 v[8:11], v[198:201], v[174:177], v[8:11]
	v_mfma_f32_16x16x32_bf16 v[4:7], v[190:193], v[182:185], v[4:7]
	s_setprio 0
	v_mfma_f32_16x16x32_bf16 v[0:3], v[198:201], v[182:185], v[0:3]
	s_barrier
; #define PG8_STAGE(bufoff, gbase, voff) do { _Pragma("unroll") for (int _i = 0; _i < 2; ++_i) \
;         __builtin_amdgcn_global_load_lds((const unsigned*)((const char*)(gbase) + (voff)[_i]), (LAS unsigned*)(lds + (bufoff) + ldsw + _i * 8192), 16, 0, 0); } while (0)
; #define PG8_LDA(dst, b, h) do { _Pragma("unroll") for (int m = 0; m < 4; ++m) _Pragma("unroll") for (int k = 0; k < 2; ++k) dst[m][k] = *(const LAS bf16x8*)(lds + PG8_SA(b, h) + aoff + m * 2048 + k * 1024); } while (0)
; #define PG8_WAIT_V(n) asm volatile("s_waitcnt vmcnt(" #n ")" ::: "memory")
; #define PG8_WAIT_L(n) asm volatile("s_waitcnt lgkmcnt(" #n ")" ::: "memory")
; template <class Epi>
; __device__ __forceinline__ void gemm_phase(LAS unsigned char* lds, const Gemm g, const StaticOrder& S, const Epi& E) {
;     ...
;         for (int t = 0; t < nt; t += 2) {
;             const bool last = (t == nt - 2);
;             const char* a1 = cA + (size_t)(t + 1) * kstep;
;             const char* a2 = last ? nA : cA + (size_t)(t + 2) * kstep; const char* b2 = last ? nB : cB + (size_t)(t + 2) * kstep;
;             const char* a3 = a2 + kstep; const char* b3 = b2 + kstep;
;             PG8_LDB(B0, 0, 0); PG8_SCHED; PG8_LDA(At, 0, 0); PG8_STAGE(PG8_SA(1, 1), a1 + hstepA, voffA);
;             PG8_WAIT_L(8); PG8_BAR; PG8_WAIT_L(0); PG8_MMA(0, 0, At, B0); PG8_BAR; PG8_SCHED;
;             PG8_LDB(B1, 0, 1); PG8_STAGE(PG8_SB(0, 0), b2, voffB);
;             PG8_BAR; PG8_WAIT_L(0); PG8_MMA(0, 1, At, B1); PG8_BAR;
;             PG8_LDA(At, 0, 1); PG8_STAGE(PG8_SA(0, 0), a2, voffA);
;             PG8_BAR; PG8_WAIT_L(0); PG8_MMA(1, 0, At, B0); PG8_BAR; PG8_SCHED;
;             PG8_STAGE(PG8_SB(0, 1), b2 + hstepB, voffB);
;             PG8_WAIT_V(6); PG8_BAR; PG8_MMA(1, 1, At, B1); PG8_BAR;
;             PG8_LDB(B0, 1, 0); PG8_SCHED; PG8_LDA(At, 1, 0); PG8_STAGE(PG8_SA(0, 1), a2 + hstepA, voffA);
;             PG8_WAIT_L(8); PG8_BAR; PG8_WAIT_L(0); PG8_MMA(0, 0, At, B0); PG8_BAR; PG8_SCHED;
;             PG8_LDB(B1, 1, 1); PG8_STAGE(PG8_SB(1, 0), b3, voffB);
;             PG8_BAR; PG8_WAIT_L(0); PG8_MMA(0, 1, At, B1); PG8_BAR;
;             PG8_LDA(At, 1, 1); PG8_STAGE(PG8_SA(1, 0), a3, voffA);
;             PG8_BAR; PG8_WAIT_L(0); PG8_MMA(1, 0, At, B0); PG8_BAR; PG8_SCHED;
;             PG8_STAGE(PG8_SB(1, 1), b3 + hstepB, voffB);
;             PG8_WAIT_V(6); PG8_BAR; PG8_MMA(1, 1, At, B1); PG8_BAR;
	s_add_u32 s26, s26, s52
	s_addc_u32 s27, s27, 0
	s_mov_b32 m0, s35
	v_lshl_add_u64 v[186:187], s[26:27], 0, v[152:153]
	global_load_lds_dwordx4 v[186:187], off nt
	s_mov_b32 m0, s36
	v_lshl_add_u64 v[186:187], s[26:27], 0, v[156:157]
	global_load_lds_dwordx4 v[186:187], off nt
	ds_read_b128 v[128:131], v140
	ds_read_b128 v[136:139], v140 offset:2048
	ds_read_b128 v[132:135], v140 offset:1024
	ds_read_b128 v[140:143], v140 offset:3072
	ds_read_b128 v[144:147], v209 offset:32768
	ds_read_b128 v[162:165], v209 offset:34816
	ds_read_b128 v[170:173], v209 offset:36864
	ds_read_b128 v[178:181], v209 offset:38912
	ds_read_b128 v[148:151], v209 offset:33792
	ds_read_b128 v[166:169], v209 offset:35840
	ds_read_b128 v[174:177], v209 offset:37888
	ds_read_b128 v[182:185], v209 offset:39936
	s_mov_b32 s26, 0x1c000
	s_add_u32 s24, s24, 0x4000
	s_addc_u32 s25, s25, 0
	s_add_i32 s27, s55, s31
	v_add_u32_e32 v198, s26, v207
	ds_read_b128 v[186:189], v198
	ds_read_b128 v[194:197], v198 offset:2048
	ds_read_b128 v[190:193], v198 offset:1024
	ds_read_b128 v[198:201], v198 offset:3072
	s_waitcnt lgkmcnt(0)
	s_barrier
	v_mfma_f32_16x16x32_bf16 v[124:127], v[128:131], v[144:147], v[124:127]
	s_setprio 1
	v_mfma_f32_16x16x32_bf16 v[120:123], v[136:139], v[144:147], v[120:123]
	v_mfma_f32_16x16x32_bf16 v[116:119], v[128:131], v[162:165], v[116:119]
	v_mfma_f32_16x16x32_bf16 v[112:115], v[136:139], v[162:165], v[112:115]
	v_mfma_f32_16x16x32_bf16 v[108:111], v[128:131], v[170:173], v[108:111]
	v_mfma_f32_16x16x32_bf16 v[104:107], v[136:139], v[170:173], v[104:107]
	v_mfma_f32_16x16x32_bf16 v[100:103], v[128:131], v[178:181], v[100:103]
	v_mfma_f32_16x16x32_bf16 v[96:99], v[136:139], v[178:181], v[96:99]
	v_mfma_f32_16x16x32_bf16 v[124:127], v[132:135], v[148:151], v[124:127]
	v_mfma_f32_16x16x32_bf16 v[120:123], v[140:143], v[148:151], v[120:123]
	v_mfma_f32_16x16x32_bf16 v[116:119], v[132:135], v[166:169], v[116:119]
	v_mfma_f32_16x16x32_bf16 v[112:115], v[140:143], v[166:169], v[112:115]
	v_mfma_f32_16x16x32_bf16 v[108:111], v[132:135], v[174:177], v[108:111]
	v_mfma_f32_16x16x32_bf16 v[104:107], v[140:143], v[174:177], v[104:107]
	v_mfma_f32_16x16x32_bf16 v[100:103], v[132:135], v[182:185], v[100:103]
	v_mfma_f32_16x16x32_bf16 v[96:99], v[140:143], v[182:185], v[96:99]
	v_mfma_f32_16x16x32_bf16 v[92:95], v[186:189], v[144:147], v[92:95]
	v_mfma_f32_16x16x32_bf16 v[88:91], v[194:197], v[144:147], v[88:91]
	v_mfma_f32_16x16x32_bf16 v[84:87], v[186:189], v[162:165], v[84:87]
	v_mfma_f32_16x16x32_bf16 v[80:83], v[194:197], v[162:165], v[80:83]
	v_mfma_f32_16x16x32_bf16 v[76:79], v[186:189], v[170:173], v[76:79]
	v_mfma_f32_16x16x32_bf16 v[72:75], v[194:197], v[170:173], v[72:75]
	v_mfma_f32_16x16x32_bf16 v[68:71], v[186:189], v[178:181], v[68:71]
	v_mfma_f32_16x16x32_bf16 v[64:67], v[194:197], v[178:181], v[64:67]
	v_mfma_f32_16x16x32_bf16 v[92:95], v[190:193], v[148:151], v[92:95]
	v_mfma_f32_16x16x32_bf16 v[88:91], v[198:201], v[148:151], v[88:91]
	v_mfma_f32_16x16x32_bf16 v[84:87], v[190:193], v[166:169], v[84:87]
	v_mfma_f32_16x16x32_bf16 v[80:83], v[198:201], v[166:169], v[80:83]
	v_mfma_f32_16x16x32_bf16 v[76:79], v[190:193], v[174:177], v[76:79]
	v_mfma_f32_16x16x32_bf16 v[72:75], v[198:201], v[174:177], v[72:75]
	v_mfma_f32_16x16x32_bf16 v[68:71], v[190:193], v[182:185], v[68:71]
	s_setprio 0
	v_mfma_f32_16x16x32_bf16 v[64:67], v[198:201], v[182:185], v[64:67]
	s_barrier
	s_mov_b32 m0, s27
	v_lshl_add_u64 v[202:203], s[24:25], 0, v[152:153]
	global_load_lds_dwordx4 v[202:203], off
	s_add_i32 m0, s27, 0x2000
	v_lshl_add_u64 v[202:203], s[24:25], 0, v[156:157]
	global_load_lds_dwordx4 v[202:203], off
	s_mov_b32 m0, s38
	v_lshl_add_u64 v[202:203], s[22:23], 0, v[152:153]
	global_load_lds_dwordx4 v[202:203], off nt
	s_mov_b32 m0, s39
	v_lshl_add_u64 v[202:203], s[22:23], 0, v[156:157]
	global_load_lds_dwordx4 v[202:203], off nt
	s_add_u32 s22, s24, s52
	s_addc_u32 s23, s25, 0
	s_add_i32 s24, s26, s31
	s_mov_b32 m0, s24
	v_lshl_add_u64 v[202:203], s[22:23], 0, v[152:153]
	global_load_lds_dwordx4 v[202:203], off
	s_add_i32 m0, s24, 0x2000
	v_lshl_add_u64 v[202:203], s[22:23], 0, v[156:157]
	global_load_lds_dwordx4 v[202:203], off
	ds_read_b128 v[144:147], v209 offset:49152
	ds_read_b128 v[162:165], v209 offset:51200
	ds_read_b128 v[170:173], v209 offset:53248
	ds_read_b128 v[178:181], v209 offset:55296
	ds_read_b128 v[148:151], v209 offset:50176
	ds_read_b128 v[166:169], v209 offset:52224
	ds_read_b128 v[174:177], v209 offset:54272
	ds_read_b128 v[182:185], v209 offset:56320
	s_waitcnt vmcnt(6)
	s_waitcnt lgkmcnt(0)
	s_barrier
	v_mfma_f32_16x16x32_bf16 v[60:63], v[128:131], v[144:147], v[60:63]
	s_setprio 1
	v_mfma_f32_16x16x32_bf16 v[56:59], v[136:139], v[144:147], v[56:59]
	v_mfma_f32_16x16x32_bf16 v[52:55], v[128:131], v[162:165], v[52:55]
	v_mfma_f32_16x16x32_bf16 v[48:51], v[136:139], v[162:165], v[48:51]
	v_mfma_f32_16x16x32_bf16 v[44:47], v[128:131], v[170:173], v[44:47]
	v_mfma_f32_16x16x32_bf16 v[40:43], v[136:139], v[170:173], v[40:43]
	v_mfma_f32_16x16x32_bf16 v[36:39], v[128:131], v[178:181], v[36:39]
	v_mfma_f32_16x16x32_bf16 v[32:35], v[136:139], v[178:181], v[32:35]
	v_mfma_f32_16x16x32_bf16 v[60:63], v[132:135], v[148:151], v[60:63]
	v_mfma_f32_16x16x32_bf16 v[56:59], v[140:143], v[148:151], v[56:59]
	v_mfma_f32_16x16x32_bf16 v[52:55], v[132:135], v[166:169], v[52:55]
	v_mfma_f32_16x16x32_bf16 v[48:51], v[140:143], v[166:169], v[48:51]
	v_mfma_f32_16x16x32_bf16 v[44:47], v[132:135], v[174:177], v[44:47]
	v_mfma_f32_16x16x32_bf16 v[40:43], v[140:143], v[174:177], v[40:43]
	v_mfma_f32_16x16x32_bf16 v[36:39], v[132:135], v[182:185], v[36:39]
	v_mfma_f32_16x16x32_bf16 v[32:35], v[140:143], v[182:185], v[32:35]
	v_mfma_f32_16x16x32_bf16 v[28:31], v[186:189], v[144:147], v[28:31]
	v_mfma_f32_16x16x32_bf16 v[24:27], v[194:197], v[144:147], v[24:27]
	s_add_u32 s4, s4, 0x8000
	s_addc_u32 s5, s5, 0
	s_add_u32 s50, s50, 0x8000
	s_addc_u32 s51, s51, 0
	v_mfma_f32_16x16x32_bf16 v[20:23], v[186:189], v[162:165], v[20:23]
	v_mfma_f32_16x16x32_bf16 v[16:19], v[194:197], v[162:165], v[16:19]
	v_mfma_f32_16x16x32_bf16 v[12:15], v[186:189], v[170:173], v[12:15]
	v_mfma_f32_16x16x32_bf16 v[8:11], v[194:197], v[170:173], v[8:11]
	v_mfma_f32_16x16x32_bf16 v[4:7], v[186:189], v[178:181], v[4:7]
	v_mfma_f32_16x16x32_bf16 v[0:3], v[194:197], v[178:181], v[0:3]
	v_mfma_f32_16x16x32_bf16 v[28:31], v[190:193], v[148:151], v[28:31]
	v_mfma_f32_16x16x32_bf16 v[24:27], v[198:201], v[148:151], v[24:27]
	v_mfma_f32_16x16x32_bf16 v[20:23], v[190:193], v[166:169], v[20:23]
	v_mfma_f32_16x16x32_bf16 v[16:19], v[198:201], v[166:169], v[16:19]
	v_mfma_f32_16x16x32_bf16 v[12:15], v[190:193], v[174:177], v[12:15]
	v_mfma_f32_16x16x32_bf16 v[8:11], v[198:201], v[174:177], v[8:11]
	v_mfma_f32_16x16x32_bf16 v[4:7], v[190:193], v[182:185], v[4:7]
	s_cmp_ge_u32 s54, s28
	s_mov_b32 s22, s54
	s_setprio 0
	v_mfma_f32_16x16x32_bf16 v[0:3], v[198:201], v[182:185], v[0:3]
	s_cbranch_scc0 .LBB0_187
;     __device__ __forceinline__ void operator()(const f32x4 (&acc)[2][2][4][2], const Unit& u, int wr, int wc, int fr, int fq) const {
;         const int row0 = u.pm * BM + wr * 64 + fr, col0 = u.pn * BM + wc * 32 + 8 * fq;
;         const float* gb = gate + (size_t)(row0 >> 12) * (6 * DM);
;         const bool ln = stats != nullptr;
;         constexpr int GB[4] = {0, 4, 8, 16};
;         f32x2 st[4];
; #pragma unroll
;         for (int grp = 0; grp < 3; ++grp) {
;             u32x4 xv[8]; f32x4 cg[2][2], cl[2][2], cb[2][2];
;             if (grp == 0 || grp == 2) {
; #pragma unroll
;                 for (int m = 0; m < 4; ++m) st[m] = ln ? *(const f32x2*)(stats + 2 * (row0 + (grp ? HALF : 0) + m * 16)) : (f32x2){0.f, 1.f};
;             }
; #pragma unroll
;             for (int j = GB[grp]; j < GB[grp + 1]; ++j) {
;                 const int k = j >> 2, m = j & 3, ai = k >> 1, col = col0 + (k & 1) * HALF, kk = k - (GB[grp] >> 2);
;                 if (m == 0) {
; #pragma unroll
;                     for (int n = 0; n < 2; ++n) { cg[kk][n] = *(const f32x4*)(gb + col + 4 * n) + 1.0f; cl[kk][n] = (f32x4){1.f, 1.f, 1.f, 1.f}; cb[kk][n] = (f32x4){0.f, 0.f, 0.f, 0.f};
;                         if (ln) { cl[kk][n] = *(const f32x4*)(lng + col + 4 * n); cb[kk][n] = *(const f32x4*)(lnb + col + 4 * n); } }
;                 }
;                 xv[j - GB[grp]] = *(const u32x4*)(z + (size_t)(row0 + ai * HALF + m * 16) * DM + col);
.Lrot_exit_187:
	s_barrier
.Lpeel_done_187:
	s_lshl_b32 s22, s49, 8
	s_add_i32 s22, s22, s37
	v_or_b32_e32 v162, s22, v206
	v_lshlrev_b32_e32 v170, 1, v162
	v_cndmask_b32_e64 v128, 0, 1, s[12:13]
	v_mov_b32_e32 v182, 1.0
	v_mov_b32_e32 v184, 0
	v_cmp_ne_u32_e64 s[4:5], 1, v128
	s_andn2_b64 vcc, exec, s[12:13]
	v_ashrrev_i32_e32 v171, 31, v170
	v_mov_b32_e32 v192, 0
	v_mov_b32_e32 v194, 1.0
	v_mov_b32_e32 v176, 1.0
	v_mov_b32_e32 v174, 0
	v_mov_b32_e32 v178, 0
	v_mov_b32_e32 v180, 1.0
	s_mov_b32 s54, 0xd00ab22c
	s_mov_b32 s55, 0x3febb5fa
	s_cbranch_vccnz .Lres_st1_skip
	v_lshl_add_u64 v[128:129], v[170:171], 2, s[14:15]
	global_load_dwordx2 v[192:193], v[128:129], off
	global_load_dwordx2 v[184:185], v[128:129], off offset:128
	global_load_dwordx2 v[178:179], v[128:129], off offset:256
	global_load_dwordx2 v[174:175], v[128:129], off offset:384

; #define PG8_STAGE(bufoff, gbase, voff) do { _Pragma("unroll") for (int _i = 0; _i < 2; ++_i) \
;         __builtin_amdgcn_global_load_lds((const unsigned*)((const char*)(gbase) + (voff)[_i]), (LAS unsigned*)(lds + (bufoff) + ldsw + _i * 8192), 16, 0, 0); } while (0)
; #define PG8_WAIT_V(n) asm volatile("s_waitcnt vmcnt(" #n ")" ::: "memory")
; #define PG8_WAIT_L(n) asm volatile("s_waitcnt lgkmcnt(" #n ")" ::: "memory")
; template <class Epi>
; __device__ __forceinline__ void gemm_phase(LAS unsigned char* lds, const Gemm g, const StaticOrder& S, const Epi& E) {
;     ...
;         const bool has_next = S.next(ui + 1, nxt);
;         const char* nA = has_next ? (const char*)g.A + (size_t)nxt.pm * tstepA : cA; const char* nB = has_next ? (const char*)g.Bt + (size_t)nxt.pn * tstepB : cB;
;         for (int t = 0; t < nt; t += 2) {
;             const bool last = (t == nt - 2);
;             const char* a1 = cA + (size_t)(t + 1) * kstep;
;             const char* a2 = last ? nA : cA + (size_t)(t + 2) * kstep; const char* b2 = last ? nB : cB + (size_t)(t + 2) * kstep;
;             const char* a3 = a2 + kstep; const char* b3 = b2 + kstep;
;             PG8_LDB(B0, 0, 0); PG8_SCHED; PG8_LDA(At, 0, 0); PG8_STAGE(PG8_SA(1, 1), a1 + hstepA, voffA);
;             PG8_WAIT_L(8); PG8_BAR; PG8_WAIT_L(0); PG8_MMA(0, 0, At, B0); PG8_BAR; PG8_SCHED;
;             PG8_LDB(B1, 0, 1); PG8_STAGE(PG8_SB(0, 0), b2, voffB);
;             PG8_BAR; PG8_WAIT_L(0); PG8_MMA(0, 1, At, B1); PG8_BAR;
;             PG8_LDA(At, 0, 1); PG8_STAGE(PG8_SA(0, 0), a2, voffA);
;             PG8_BAR; PG8_WAIT_L(0); PG8_MMA(1, 0, At, B0); PG8_BAR; PG8_SCHED;
;             PG8_STAGE(PG8_SB(0, 1), b2 + hstepB, voffB);
;             PG8_WAIT_V(6); PG8_BAR; PG8_MMA(1, 1, At, B1); PG8_BAR;
;             PG8_LDB(B0, 1, 0); PG8_SCHED; PG8_LDA(At, 1, 0); PG8_STAGE(PG8_SA(0, 1), a2 + hstepA, voffA);
;             PG8_WAIT_L(8); PG8_BAR; PG8_WAIT_L(0); PG8_MMA(0, 0, At, B0); PG8_BAR; PG8_SCHED;
;             PG8_LDB(B1, 1, 1); PG8_STAGE(PG8_SB(1, 0), b3, voffB);
;             PG8_BAR; PG8_WAIT_L(0); PG8_MMA(0, 1, At, B1); PG8_BAR;
;             PG8_LDA(At, 1, 1); PG8_STAGE(PG8_SA(1, 0), a3, voffA);
;             PG8_BAR; PG8_WAIT_L(0); PG8_MMA(1, 0, At, B0); PG8_BAR; PG8_SCHED;
;             PG8_STAGE(PG8_SB(1, 1), b3 + hstepB, voffB);
;             PG8_WAIT_V(6); PG8_BAR; PG8_MMA(1, 1, At, B1); PG8_BAR;
.LBB0_246:
	s_ashr_i32 s5, s4, 31
	v_cmp_lt_i64_e32 vcc, s[6:7], v[154:155]
	s_lshl_b64 s[6:7], s[4:5], 20
	v_readlane_b32 s8, v252, 53
	v_readlane_b32 s9, v252, 54
	s_add_u32 s6, s8, s6
	s_addc_u32 s7, s9, s7
	s_and_b64 s[8:9], vcc, exec
	s_cselect_b32 s5, s7, s13
	s_cselect_b32 s11, s6, s12
	s_ashr_i32 s3, s2, 31
	s_lshl_b64 s[8:9], s[2:3], 20
	s_add_u32 s8, s21, s8
	s_addc_u32 s9, s22, s9
	s_and_b64 s[16:17], vcc, exec
	s_cselect_b32 s3, s9, s15
	s_cselect_b32 s35, s8, s14
	s_add_u32 s12, s12, 0x84000
	s_addc_u32 s13, s13, 0
	s_add_u32 s36, s14, 0x8000
	s_addc_u32 s37, s15, 0
	s_mov_b32 s38, -2
	s_add_u32 s14, s12, 0xfff84000
	s_addc_u32 s15, s13, -1
	s_cmp_eq_u32 s38, 28
	s_cselect_b32 s18, s11, s14
	s_cselect_b32 s19, s5, s15
	s_cselect_b32 s14, s35, s36
	s_cselect_b32 s15, s3, s37
	s_add_u32 s16, s18, 0x4000
	s_addc_u32 s17, s19, 0
	s_add_i32 m0, s25, 0xc000
	v_lshl_add_u64 v[194:195], s[12:13], 0, v[156:157]
	global_load_lds_dwordx4 v[194:195], off
	s_add_i32 m0, s25, 0xe000
	v_lshl_add_u64 v[194:195], s[12:13], 0, v[158:159]
	global_load_lds_dwordx4 v[194:195], off
	s_mov_b32 s39, 0x10000
	v_add_u32_e32 v140, s39, v170
	ds_read_b128 v[128:131], v140
	ds_read_b128 v[136:139], v140 offset:2048
	ds_read_b128 v[132:135], v140 offset:1024
	ds_read_b128 v[140:143], v140 offset:3072
	ds_read_b128 v[144:147], v172
	ds_read_b128 v[166:169], v172 offset:2048
	ds_read_b128 v[178:181], v172 offset:4096
	ds_read_b128 v[186:189], v172 offset:6144
	ds_read_b128 v[148:151], v172 offset:1024
	ds_read_b128 v[174:177], v172 offset:3072
	ds_read_b128 v[182:185], v172 offset:5120
	ds_read_b128 v[190:193], v172 offset:7168
	s_mov_b32 s42, 0x14000
	s_add_i32 s39, s39, s23
	v_add_u32_e32 v152, s42, v170
	ds_read_b128 v[194:197], v152
	ds_read_b128 v[202:205], v152 offset:2048
	ds_read_b128 v[198:201], v152 offset:1024
	ds_read_b128 v[206:209], v152 offset:3072
	s_waitcnt lgkmcnt(0)
	s_barrier
	v_mfma_f32_16x16x32_bf16 v[124:127], v[128:131], v[144:147], 0
	s_setprio 1
	v_mfma_f32_16x16x32_bf16 v[120:123], v[136:139], v[144:147], 0
	v_mfma_f32_16x16x32_bf16 v[108:111], v[128:131], v[166:169], 0
	v_mfma_f32_16x16x32_bf16 v[104:107], v[136:139], v[166:169], 0
	v_mfma_f32_16x16x32_bf16 v[92:95], v[128:131], v[178:181], 0
	v_mfma_f32_16x16x32_bf16 v[88:91], v[136:139], v[178:181], 0
	v_mfma_f32_16x16x32_bf16 v[76:79], v[128:131], v[186:189], 0
	v_mfma_f32_16x16x32_bf16 v[72:75], v[136:139], v[186:189], 0
	v_mfma_f32_16x16x32_bf16 v[124:127], v[132:135], v[148:151], v[124:127]
	v_mfma_f32_16x16x32_bf16 v[120:123], v[140:143], v[148:151], v[120:123]
	v_mfma_f32_16x16x32_bf16 v[108:111], v[132:135], v[174:177], v[108:111]
	v_mfma_f32_16x16x32_bf16 v[104:107], v[140:143], v[174:177], v[104:107]
	v_mfma_f32_16x16x32_bf16 v[92:95], v[132:135], v[182:185], v[92:95]
	v_mfma_f32_16x16x32_bf16 v[88:91], v[140:143], v[182:185], v[88:91]
	v_mfma_f32_16x16x32_bf16 v[76:79], v[132:135], v[190:193], v[76:79]
	v_mfma_f32_16x16x32_bf16 v[72:75], v[140:143], v[190:193], v[72:75]
	v_mfma_f32_16x16x32_bf16 v[116:119], v[194:197], v[144:147], 0
	v_mfma_f32_16x16x32_bf16 v[112:115], v[202:205], v[144:147], 0
	v_mfma_f32_16x16x32_bf16 v[100:103], v[194:197], v[166:169], 0
	v_mfma_f32_16x16x32_bf16 v[96:99], v[202:205], v[166:169], 0
	v_mfma_f32_16x16x32_bf16 v[84:87], v[194:197], v[178:181], 0
	v_mfma_f32_16x16x32_bf16 v[80:83], v[202:205], v[178:181], 0
	v_mfma_f32_16x16x32_bf16 v[68:71], v[194:197], v[186:189], 0
	v_mfma_f32_16x16x32_bf16 v[64:67], v[202:205], v[186:189], 0
	v_mfma_f32_16x16x32_bf16 v[116:119], v[198:201], v[148:151], v[116:119]
	v_mfma_f32_16x16x32_bf16 v[112:115], v[206:209], v[148:151], v[112:115]
	v_mfma_f32_16x16x32_bf16 v[100:103], v[198:201], v[174:177], v[100:103]
	v_mfma_f32_16x16x32_bf16 v[96:99], v[206:209], v[174:177], v[96:99]
	v_mfma_f32_16x16x32_bf16 v[84:87], v[198:201], v[182:185], v[84:87]
	v_mfma_f32_16x16x32_bf16 v[80:83], v[206:209], v[182:185], v[80:83]
	v_mfma_f32_16x16x32_bf16 v[68:71], v[198:201], v[190:193], v[68:71]
	s_setprio 0
	v_mfma_f32_16x16x32_bf16 v[64:67], v[206:209], v[190:193], v[64:67]
	s_barrier
	s_mov_b32 m0, s39
	v_lshl_add_u64 v[210:211], s[14:15], 0, v[156:157]
	global_load_lds_dwordx4 v[210:211], off
	s_add_i32 m0, s39, 0x2000
	v_lshl_add_u64 v[210:211], s[14:15], 0, v[158:159]
	global_load_lds_dwordx4 v[210:211], off
	s_mov_b32 m0, s25
	v_lshl_add_u64 v[210:211], s[18:19], 0, v[156:157]
	global_load_lds_dwordx4 v[210:211], off
	s_mov_b32 m0, s26
	v_lshl_add_u64 v[210:211], s[18:19], 0, v[158:159]
	global_load_lds_dwordx4 v[210:211], off
	s_add_u32 s40, s14, 0x80000
	s_addc_u32 s41, s15, 0
	s_add_i32 s39, s42, s23
	s_mov_b32 m0, s39
	v_lshl_add_u64 v[210:211], s[40:41], 0, v[156:157]
	global_load_lds_dwordx4 v[210:211], off
	s_add_i32 m0, s39, 0x2000
	v_lshl_add_u64 v[210:211], s[40:41], 0, v[158:159]
	global_load_lds_dwordx4 v[210:211], off
	ds_read_b128 v[144:147], v172 offset:16384
	ds_read_b128 v[166:169], v172 offset:18432
	ds_read_b128 v[178:181], v172 offset:20480
	ds_read_b128 v[186:189], v172 offset:22528
	ds_read_b128 v[148:151], v172 offset:17408
	ds_read_b128 v[174:177], v172 offset:19456
	ds_read_b128 v[182:185], v172 offset:21504
	ds_read_b128 v[190:193], v172 offset:23552
	s_waitcnt vmcnt(6)
	s_waitcnt lgkmcnt(0)
	s_barrier
; #define PG8_STAGE(bufoff, gbase, voff) do { _Pragma("unroll") for (int _i = 0; _i < 2; ++_i) \
;         __builtin_amdgcn_global_load_lds((const unsigned*)((const char*)(gbase) + (voff)[_i]), (LAS unsigned*)(lds + (bufoff) + ldsw + _i * 8192), 16, 0, 0); } while (0)
; #define PG8_LDA(dst, b, h) do { _Pragma("unroll") for (int m = 0; m < 4; ++m) _Pragma("unroll") for (int k = 0; k < 2; ++k) dst[m][k] = *(const LAS bf16x8*)(lds + PG8_SA(b, h) + aoff + m * 2048 + k * 1024); } while (0)
; #define PG8_WAIT_V(n) asm volatile("s_waitcnt vmcnt(" #n ")" ::: "memory")
; #define PG8_WAIT_L(n) asm volatile("s_waitcnt lgkmcnt(" #n ")" ::: "memory")
; template <class Epi>
; __device__ __forceinline__ void gemm_phase(LAS unsigned char* lds, const Gemm g, const StaticOrder& S, const Epi& E) {
;     ...
;         for (int t = 0; t < nt; t += 2) {
;             const bool last = (t == nt - 2);
;             const char* a1 = cA + (size_t)(t + 1) * kstep;
;             const char* a2 = last ? nA : cA + (size_t)(t + 2) * kstep; const char* b2 = last ? nB : cB + (size_t)(t + 2) * kstep;
;             const char* a3 = a2 + kstep; const char* b3 = b2 + kstep;
;             PG8_LDB(B0, 0, 0); PG8_SCHED; PG8_LDA(At, 0, 0); PG8_STAGE(PG8_SA(1, 1), a1 + hstepA, voffA);
;             PG8_WAIT_L(8); PG8_BAR; PG8_WAIT_L(0); PG8_MMA(0, 0, At, B0); PG8_BAR; PG8_SCHED;
;             PG8_LDB(B1, 0, 1); PG8_STAGE(PG8_SB(0, 0), b2, voffB);
;             PG8_BAR; PG8_WAIT_L(0); PG8_MMA(0, 1, At, B1); PG8_BAR;
;             PG8_LDA(At, 0, 1); PG8_STAGE(PG8_SA(0, 0), a2, voffA);
;             PG8_BAR; PG8_WAIT_L(0); PG8_MMA(1, 0, At, B0); PG8_BAR; PG8_SCHED;
;             PG8_STAGE(PG8_SB(0, 1), b2 + hstepB, voffB);
;             PG8_WAIT_V(6); PG8_BAR; PG8_MMA(1, 1, At, B1); PG8_BAR;
;             PG8_LDB(B0, 1, 0); PG8_SCHED; PG8_LDA(At, 1, 0); PG8_STAGE(PG8_SA(0, 1), a2 + hstepA, voffA);
;             PG8_WAIT_L(8); PG8_BAR; PG8_WAIT_L(0); PG8_MMA(0, 0, At, B0); PG8_BAR; PG8_SCHED;
;             PG8_LDB(B1, 1, 1); PG8_STAGE(PG8_SB(1, 0), b3, voffB);
;             PG8_BAR; PG8_WAIT_L(0); PG8_MMA(0, 1, At, B1); PG8_BAR;
;             PG8_LDA(At, 1, 1); PG8_STAGE(PG8_SA(1, 0), a3, voffA);
;             PG8_BAR; PG8_WAIT_L(0); PG8_MMA(1, 0, At, B0); PG8_BAR; PG8_SCHED;
;             PG8_STAGE(PG8_SB(1, 1), b3 + hstepB, voffB);
;             PG8_WAIT_V(6); PG8_BAR; PG8_MMA(1, 1, At, B1); PG8_BAR;
	v_mfma_f32_16x16x32_bf16 v[60:63], v[128:131], v[144:147], 0
	s_setprio 1
	v_mfma_f32_16x16x32_bf16 v[56:59], v[136:139], v[144:147], 0
	v_mfma_f32_16x16x32_bf16 v[44:47], v[128:131], v[166:169], 0
	v_mfma_f32_16x16x32_bf16 v[40:43], v[136:139], v[166:169], 0
	v_mfma_f32_16x16x32_bf16 v[28:31], v[128:131], v[178:181], 0
	v_mfma_f32_16x16x32_bf16 v[24:27], v[136:139], v[178:181], 0
	v_mfma_f32_16x16x32_bf16 v[12:15], v[128:131], v[186:189], 0
	v_mfma_f32_16x16x32_bf16 v[8:11], v[136:139], v[186:189], 0
	v_mfma_f32_16x16x32_bf16 v[60:63], v[132:135], v[148:151], v[60:63]
	v_mfma_f32_16x16x32_bf16 v[56:59], v[140:143], v[148:151], v[56:59]
	v_mfma_f32_16x16x32_bf16 v[44:47], v[132:135], v[174:177], v[44:47]
	v_mfma_f32_16x16x32_bf16 v[40:43], v[140:143], v[174:177], v[40:43]
	v_mfma_f32_16x16x32_bf16 v[28:31], v[132:135], v[182:185], v[28:31]
	v_mfma_f32_16x16x32_bf16 v[24:27], v[140:143], v[182:185], v[24:27]
	v_mfma_f32_16x16x32_bf16 v[12:15], v[132:135], v[190:193], v[12:15]
	v_mfma_f32_16x16x32_bf16 v[8:11], v[140:143], v[190:193], v[8:11]
	v_mfma_f32_16x16x32_bf16 v[52:55], v[194:197], v[144:147], 0
	v_mfma_f32_16x16x32_bf16 v[48:51], v[202:205], v[144:147], 0
	s_add_i32 s39, 0, 0x18000
	v_add_u32_e32 v140, s39, v170
	v_mfma_f32_16x16x32_bf16 v[36:39], v[194:197], v[166:169], 0
	v_mfma_f32_16x16x32_bf16 v[32:35], v[202:205], v[166:169], 0
	v_mfma_f32_16x16x32_bf16 v[20:23], v[194:197], v[178:181], 0
	v_mfma_f32_16x16x32_bf16 v[16:19], v[202:205], v[178:181], 0
	v_mfma_f32_16x16x32_bf16 v[4:7], v[194:197], v[186:189], 0
	v_mfma_f32_16x16x32_bf16 v[0:3], v[202:205], v[186:189], 0
	v_mfma_f32_16x16x32_bf16 v[52:55], v[198:201], v[148:151], v[52:55]
	v_mfma_f32_16x16x32_bf16 v[48:51], v[206:209], v[148:151], v[48:51]
	v_mfma_f32_16x16x32_bf16 v[36:39], v[198:201], v[174:177], v[36:39]
	v_mfma_f32_16x16x32_bf16 v[32:35], v[206:209], v[174:177], v[32:35]
	v_mfma_f32_16x16x32_bf16 v[20:23], v[198:201], v[182:185], v[20:23]
	v_mfma_f32_16x16x32_bf16 v[16:19], v[206:209], v[182:185], v[16:19]
	v_mfma_f32_16x16x32_bf16 v[4:7], v[198:201], v[190:193], v[4:7]
	s_setprio 0
	v_mfma_f32_16x16x32_bf16 v[0:3], v[206:209], v[190:193], v[0:3]
	s_barrier
	s_add_u32 s18, s18, 0x80000
	s_addc_u32 s19, s19, 0
	s_mov_b32 m0, s27
	v_lshl_add_u64 v[194:195], s[18:19], 0, v[156:157]
	global_load_lds_dwordx4 v[194:195], off
	s_mov_b32 m0, s28
	v_lshl_add_u64 v[194:195], s[18:19], 0, v[158:159]
	global_load_lds_dwordx4 v[194:195], off
	ds_read_b128 v[128:131], v140
	ds_read_b128 v[136:139], v140 offset:2048
	ds_read_b128 v[132:135], v140 offset:1024
	ds_read_b128 v[140:143], v140 offset:3072
	ds_read_b128 v[144:147], v172 offset:32768
	ds_read_b128 v[166:169], v172 offset:34816
	ds_read_b128 v[178:181], v172 offset:36864
	ds_read_b128 v[186:189], v172 offset:38912
	ds_read_b128 v[148:151], v172 offset:33792
	ds_read_b128 v[174:177], v172 offset:35840
	ds_read_b128 v[182:185], v172 offset:37888
	ds_read_b128 v[190:193], v172 offset:39936
	s_mov_b32 s40, 0x1c000
	s_add_u32 s18, s14, 0x4000
	s_addc_u32 s19, s15, 0
	s_add_i32 s39, s39, s23
	v_add_u32_e32 v152, s40, v170
	ds_read_b128 v[194:197], v152
	ds_read_b128 v[202:205], v152 offset:2048
	ds_read_b128 v[198:201], v152 offset:1024
	ds_read_b128 v[206:209], v152 offset:3072
	s_waitcnt lgkmcnt(0)
	s_barrier
	v_mfma_f32_16x16x32_bf16 v[124:127], v[128:131], v[144:147], v[124:127]
	s_setprio 1
	v_mfma_f32_16x16x32_bf16 v[120:123], v[136:139], v[144:147], v[120:123]
	v_mfma_f32_16x16x32_bf16 v[108:111], v[128:131], v[166:169], v[108:111]
	v_mfma_f32_16x16x32_bf16 v[104:107], v[136:139], v[166:169], v[104:107]
	v_mfma_f32_16x16x32_bf16 v[92:95], v[128:131], v[178:181], v[92:95]
	v_mfma_f32_16x16x32_bf16 v[88:91], v[136:139], v[178:181], v[88:91]
	v_mfma_f32_16x16x32_bf16 v[76:79], v[128:131], v[186:189], v[76:79]
	v_mfma_f32_16x16x32_bf16 v[72:75], v[136:139], v[186:189], v[72:75]
	v_mfma_f32_16x16x32_bf16 v[124:127], v[132:135], v[148:151], v[124:127]
	v_mfma_f32_16x16x32_bf16 v[120:123], v[140:143], v[148:151], v[120:123]
	v_mfma_f32_16x16x32_bf16 v[108:111], v[132:135], v[174:177], v[108:111]
	v_mfma_f32_16x16x32_bf16 v[104:107], v[140:143], v[174:177], v[104:107]
	v_mfma_f32_16x16x32_bf16 v[92:95], v[132:135], v[182:185], v[92:95]
	v_mfma_f32_16x16x32_bf16 v[88:91], v[140:143], v[182:185], v[88:91]
	v_mfma_f32_16x16x32_bf16 v[76:79], v[132:135], v[190:193], v[76:79]
	v_mfma_f32_16x16x32_bf16 v[72:75], v[140:143], v[190:193], v[72:75]
	v_mfma_f32_16x16x32_bf16 v[116:119], v[194:197], v[144:147], v[116:119]
	v_mfma_f32_16x16x32_bf16 v[112:115], v[202:205], v[144:147], v[112:115]
	v_mfma_f32_16x16x32_bf16 v[100:103], v[194:197], v[166:169], v[100:103]
	v_mfma_f32_16x16x32_bf16 v[96:99], v[202:205], v[166:169], v[96:99]
	v_mfma_f32_16x16x32_bf16 v[84:87], v[194:197], v[178:181], v[84:87]
	v_mfma_f32_16x16x32_bf16 v[80:83], v[202:205], v[178:181], v[80:83]
	v_mfma_f32_16x16x32_bf16 v[68:71], v[194:197], v[186:189], v[68:71]
	v_mfma_f32_16x16x32_bf16 v[64:67], v[202:205], v[186:189], v[64:67]
	v_mfma_f32_16x16x32_bf16 v[116:119], v[198:201], v[148:151], v[116:119]
	v_mfma_f32_16x16x32_bf16 v[112:115], v[206:209], v[148:151], v[112:115]
	v_mfma_f32_16x16x32_bf16 v[100:103], v[198:201], v[174:177], v[100:103]
	v_mfma_f32_16x16x32_bf16 v[96:99], v[206:209], v[174:177], v[96:99]
	v_mfma_f32_16x16x32_bf16 v[84:87], v[198:201], v[182:185], v[84:87]
	v_mfma_f32_16x16x32_bf16 v[80:83], v[206:209], v[182:185], v[80:83]
	v_mfma_f32_16x16x32_bf16 v[68:71], v[198:201], v[190:193], v[68:71]
	s_setprio 0
	v_mfma_f32_16x16x32_bf16 v[64:67], v[206:209], v[190:193], v[64:67]
	s_barrier
; #define PG8_STAGE(bufoff, gbase, voff) do { _Pragma("unroll") for (int _i = 0; _i < 2; ++_i) \
;         __builtin_amdgcn_global_load_lds((const unsigned*)((const char*)(gbase) + (voff)[_i]), (LAS unsigned*)(lds + (bufoff) + ldsw + _i * 8192), 16, 0, 0); } while (0)
; #define PG8_LDA(dst, b, h) do { _Pragma("unroll") for (int m = 0; m < 4; ++m) _Pragma("unroll") for (int k = 0; k < 2; ++k) dst[m][k] = *(const LAS bf16x8*)(lds + PG8_SA(b, h) + aoff + m * 2048 + k * 1024); } while (0)
; #define PG8_WAIT_V(n) asm volatile("s_waitcnt vmcnt(" #n ")" ::: "memory")
; #define PG8_WAIT_L(n) asm volatile("s_waitcnt lgkmcnt(" #n ")" ::: "memory")
; template <class Epi>
; __device__ __forceinline__ void gemm_phase(LAS unsigned char* lds, const Gemm g, const StaticOrder& S, const Epi& E) {
;     ...
;         for (int t = 0; t < nt; t += 2) {
;             const bool last = (t == nt - 2);
;             const char* a1 = cA + (size_t)(t + 1) * kstep;
;             const char* a2 = last ? nA : cA + (size_t)(t + 2) * kstep; const char* b2 = last ? nB : cB + (size_t)(t + 2) * kstep;
;             const char* a3 = a2 + kstep; const char* b3 = b2 + kstep;
;             PG8_LDB(B0, 0, 0); PG8_SCHED; PG8_LDA(At, 0, 0); PG8_STAGE(PG8_SA(1, 1), a1 + hstepA, voffA);
;             PG8_WAIT_L(8); PG8_BAR; PG8_WAIT_L(0); PG8_MMA(0, 0, At, B0); PG8_BAR; PG8_SCHED;
;             PG8_LDB(B1, 0, 1); PG8_STAGE(PG8_SB(0, 0), b2, voffB);
;             PG8_BAR; PG8_WAIT_L(0); PG8_MMA(0, 1, At, B1); PG8_BAR;
;             PG8_LDA(At, 0, 1); PG8_STAGE(PG8_SA(0, 0), a2, voffA);
;             PG8_BAR; PG8_WAIT_L(0); PG8_MMA(1, 0, At, B0); PG8_BAR; PG8_SCHED;
;             PG8_STAGE(PG8_SB(0, 1), b2 + hstepB, voffB);
;             PG8_WAIT_V(6); PG8_BAR; PG8_MMA(1, 1, At, B1); PG8_BAR;
;             PG8_LDB(B0, 1, 0); PG8_SCHED; PG8_LDA(At, 1, 0); PG8_STAGE(PG8_SA(0, 1), a2 + hstepA, voffA);
;             PG8_WAIT_L(8); PG8_BAR; PG8_WAIT_L(0); PG8_MMA(0, 0, At, B0); PG8_BAR; PG8_SCHED;
;             PG8_LDB(B1, 1, 1); PG8_STAGE(PG8_SB(1, 0), b3, voffB);
;             PG8_BAR; PG8_WAIT_L(0); PG8_MMA(0, 1, At, B1); PG8_BAR;
;             PG8_LDA(At, 1, 1); PG8_STAGE(PG8_SA(1, 0), a3, voffA);
;             PG8_BAR; PG8_WAIT_L(0); PG8_MMA(1, 0, At, B0); PG8_BAR; PG8_SCHED;
;             PG8_STAGE(PG8_SB(1, 1), b3 + hstepB, voffB);
;             PG8_WAIT_V(6); PG8_BAR; PG8_MMA(1, 1, At, B1); PG8_BAR;
	s_mov_b32 m0, s39
	v_lshl_add_u64 v[210:211], s[18:19], 0, v[156:157]
	global_load_lds_dwordx4 v[210:211], off
	s_add_i32 m0, s39, 0x2000
	v_lshl_add_u64 v[210:211], s[18:19], 0, v[158:159]
	global_load_lds_dwordx4 v[210:211], off
	s_mov_b32 m0, s29
	v_lshl_add_u64 v[210:211], s[16:17], 0, v[156:157]
	global_load_lds_dwordx4 v[210:211], off
	s_mov_b32 m0, s30
	v_lshl_add_u64 v[210:211], s[16:17], 0, v[158:159]
	global_load_lds_dwordx4 v[210:211], off
	s_add_u32 s14, s14, 0x84000
	s_addc_u32 s15, s15, 0
	s_add_i32 s16, s40, s23
	s_mov_b32 m0, s16
	v_lshl_add_u64 v[210:211], s[14:15], 0, v[156:157]
	global_load_lds_dwordx4 v[210:211], off
	s_add_i32 m0, s16, 0x2000
	v_lshl_add_u64 v[210:211], s[14:15], 0, v[158:159]
	global_load_lds_dwordx4 v[210:211], off
	ds_read_b128 v[144:147], v172 offset:49152
	ds_read_b128 v[166:169], v172 offset:51200
	ds_read_b128 v[178:181], v172 offset:53248
	ds_read_b128 v[186:189], v172 offset:55296
	ds_read_b128 v[148:151], v172 offset:50176
	ds_read_b128 v[174:177], v172 offset:52224
	ds_read_b128 v[182:185], v172 offset:54272
	ds_read_b128 v[190:193], v172 offset:56320
	s_waitcnt vmcnt(6)
	s_waitcnt lgkmcnt(0)
	s_barrier
	v_mfma_f32_16x16x32_bf16 v[60:63], v[128:131], v[144:147], v[60:63]
	s_setprio 1
	v_mfma_f32_16x16x32_bf16 v[56:59], v[136:139], v[144:147], v[56:59]
	v_mfma_f32_16x16x32_bf16 v[44:47], v[128:131], v[166:169], v[44:47]
	v_mfma_f32_16x16x32_bf16 v[40:43], v[136:139], v[166:169], v[40:43]
	v_mfma_f32_16x16x32_bf16 v[28:31], v[128:131], v[178:181], v[28:31]
	v_mfma_f32_16x16x32_bf16 v[24:27], v[136:139], v[178:181], v[24:27]
	v_mfma_f32_16x16x32_bf16 v[12:15], v[128:131], v[186:189], v[12:15]
	v_mfma_f32_16x16x32_bf16 v[8:11], v[136:139], v[186:189], v[8:11]
	v_mfma_f32_16x16x32_bf16 v[60:63], v[132:135], v[148:151], v[60:63]
	v_mfma_f32_16x16x32_bf16 v[56:59], v[140:143], v[148:151], v[56:59]
	v_mfma_f32_16x16x32_bf16 v[44:47], v[132:135], v[174:177], v[44:47]
	v_mfma_f32_16x16x32_bf16 v[40:43], v[140:143], v[174:177], v[40:43]
	v_mfma_f32_16x16x32_bf16 v[28:31], v[132:135], v[182:185], v[28:31]
	v_mfma_f32_16x16x32_bf16 v[24:27], v[140:143], v[182:185], v[24:27]
	v_mfma_f32_16x16x32_bf16 v[12:15], v[132:135], v[190:193], v[12:15]
	v_mfma_f32_16x16x32_bf16 v[8:11], v[140:143], v[190:193], v[8:11]
	v_mfma_f32_16x16x32_bf16 v[52:55], v[194:197], v[144:147], v[52:55]
	v_mfma_f32_16x16x32_bf16 v[48:51], v[202:205], v[144:147], v[48:51]
	s_add_i32 s38, s38, 2
	s_add_u32 s12, s12, 0x8000
	s_addc_u32 s13, s13, 0
	s_add_u32 s36, s36, 0x8000
	s_addc_u32 s37, s37, 0
	v_mfma_f32_16x16x32_bf16 v[36:39], v[194:197], v[166:169], v[36:39]
	v_mfma_f32_16x16x32_bf16 v[32:35], v[202:205], v[166:169], v[32:35]
	v_mfma_f32_16x16x32_bf16 v[20:23], v[194:197], v[178:181], v[20:23]
	v_mfma_f32_16x16x32_bf16 v[16:19], v[202:205], v[178:181], v[16:19]
	v_mfma_f32_16x16x32_bf16 v[4:7], v[194:197], v[186:189], v[4:7]
	v_mfma_f32_16x16x32_bf16 v[0:3], v[202:205], v[186:189], v[0:3]
	v_mfma_f32_16x16x32_bf16 v[52:55], v[198:201], v[148:151], v[52:55]
	v_mfma_f32_16x16x32_bf16 v[48:51], v[206:209], v[148:151], v[48:51]
	v_mfma_f32_16x16x32_bf16 v[36:39], v[198:201], v[174:177], v[36:39]
	v_mfma_f32_16x16x32_bf16 v[32:35], v[206:209], v[174:177], v[32:35]
	v_mfma_f32_16x16x32_bf16 v[20:23], v[198:201], v[182:185], v[20:23]
	v_mfma_f32_16x16x32_bf16 v[16:19], v[206:209], v[182:185], v[16:19]
	v_mfma_f32_16x16x32_bf16 v[4:7], v[198:201], v[190:193], v[4:7]
	s_cmp_gt_u32 s38, 29
	s_setprio 0
	v_mfma_f32_16x16x32_bf16 v[0:3], v[206:209], v[190:193], v[0:3]
	s_cbranch_scc1 .Lrot_exit_247
.LBB0_247:
	s_barrier
	s_add_u32 s14, s12, 0xfff84000
	s_addc_u32 s15, s13, -1
	s_cmp_eq_u32 s38, 28
	s_cselect_b32 s18, s11, s14
	s_cselect_b32 s19, s5, s15
	s_cselect_b32 s14, s35, s36
	s_cselect_b32 s15, s3, s37
	s_add_u32 s16, s18, 0x4000
	s_addc_u32 s17, s19, 0
	s_add_i32 m0, s25, 0xc000
	v_lshl_add_u64 v[194:195], s[12:13], 0, v[156:157]
	global_load_lds_dwordx4 v[194:195], off
	s_add_i32 m0, s25, 0xe000
	v_lshl_add_u64 v[194:195], s[12:13], 0, v[158:159]
	global_load_lds_dwordx4 v[194:195], off
	s_mov_b32 s39, 0x10000
	v_add_u32_e32 v140, s39, v170
	ds_read_b128 v[128:131], v140
	ds_read_b128 v[136:139], v140 offset:2048
	ds_read_b128 v[132:135], v140 offset:1024
	ds_read_b128 v[140:143], v140 offset:3072
	ds_read_b128 v[144:147], v172
	ds_read_b128 v[166:169], v172 offset:2048
	ds_read_b128 v[178:181], v172 offset:4096
	ds_read_b128 v[186:189], v172 offset:6144
	ds_read_b128 v[148:151], v172 offset:1024
	ds_read_b128 v[174:177], v172 offset:3072
	ds_read_b128 v[182:185], v172 offset:5120
	ds_read_b128 v[190:193], v172 offset:7168
	s_mov_b32 s42, 0x14000
	s_add_i32 s39, s39, s23
	v_add_u32_e32 v152, s42, v170
	ds_read_b128 v[194:197], v152
	ds_read_b128 v[202:205], v152 offset:2048
	ds_read_b128 v[198:201], v152 offset:1024
	ds_read_b128 v[206:209], v152 offset:3072
	s_waitcnt lgkmcnt(0)
	s_barrier
; #define PG8_STAGE(bufoff, gbase, voff) do { _Pragma("unroll") for (int _i = 0; _i < 2; ++_i) \
;         __builtin_amdgcn_global_load_lds((const unsigned*)((const char*)(gbase) + (voff)[_i]), (LAS unsigned*)(lds + (bufoff) + ldsw + _i * 8192), 16, 0, 0); } while (0)
; #define PG8_LDA(dst, b, h) do { _Pragma("unroll") for (int m = 0; m < 4; ++m) _Pragma("unroll") for (int k = 0; k < 2; ++k) dst[m][k] = *(const LAS bf16x8*)(lds + PG8_SA(b, h) + aoff + m * 2048 + k * 1024); } while (0)
; #define PG8_WAIT_V(n) asm volatile("s_waitcnt vmcnt(" #n ")" ::: "memory")
; #define PG8_WAIT_L(n) asm volatile("s_waitcnt lgkmcnt(" #n ")" ::: "memory")
; template <class Epi>
; __device__ __forceinline__ void gemm_phase(LAS unsigned char* lds, const Gemm g, const StaticOrder& S, const Epi& E) {
;     ...
;         for (int t = 0; t < nt; t += 2) {
;             const bool last = (t == nt - 2);
;             const char* a1 = cA + (size_t)(t + 1) * kstep;
;             const char* a2 = last ? nA : cA + (size_t)(t + 2) * kstep; const char* b2 = last ? nB : cB + (size_t)(t + 2) * kstep;
;             const char* a3 = a2 + kstep; const char* b3 = b2 + kstep;
;             PG8_LDB(B0, 0, 0); PG8_SCHED; PG8_LDA(At, 0, 0); PG8_STAGE(PG8_SA(1, 1), a1 + hstepA, voffA);
;             PG8_WAIT_L(8); PG8_BAR; PG8_WAIT_L(0); PG8_MMA(0, 0, At, B0); PG8_BAR; PG8_SCHED;
;             PG8_LDB(B1, 0, 1); PG8_STAGE(PG8_SB(0, 0), b2, voffB);
;             PG8_BAR; PG8_WAIT_L(0); PG8_MMA(0, 1, At, B1); PG8_BAR;
;             PG8_LDA(At, 0, 1); PG8_STAGE(PG8_SA(0, 0), a2, voffA);
;             PG8_BAR; PG8_WAIT_L(0); PG8_MMA(1, 0, At, B0); PG8_BAR; PG8_SCHED;
;             PG8_STAGE(PG8_SB(0, 1), b2 + hstepB, voffB);
;             PG8_WAIT_V(6); PG8_BAR; PG8_MMA(1, 1, At, B1); PG8_BAR;
;             PG8_LDB(B0, 1, 0); PG8_SCHED; PG8_LDA(At, 1, 0); PG8_STAGE(PG8_SA(0, 1), a2 + hstepA, voffA);
;             PG8_WAIT_L(8); PG8_BAR; PG8_WAIT_L(0); PG8_MMA(0, 0, At, B0); PG8_BAR; PG8_SCHED;
;             PG8_LDB(B1, 1, 1); PG8_STAGE(PG8_SB(1, 0), b3, voffB);
;             PG8_BAR; PG8_WAIT_L(0); PG8_MMA(0, 1, At, B1); PG8_BAR;
;             PG8_LDA(At, 1, 1); PG8_STAGE(PG8_SA(1, 0), a3, voffA);
;             PG8_BAR; PG8_WAIT_L(0); PG8_MMA(1, 0, At, B0); PG8_BAR; PG8_SCHED;
;             PG8_STAGE(PG8_SB(1, 1), b3 + hstepB, voffB);
;             PG8_WAIT_V(6); PG8_BAR; PG8_MMA(1, 1, At, B1); PG8_BAR;
	v_mfma_f32_16x16x32_bf16 v[124:127], v[128:131], v[144:147], v[124:127]
	s_setprio 1
	v_mfma_f32_16x16x32_bf16 v[120:123], v[136:139], v[144:147], v[120:123]
	v_mfma_f32_16x16x32_bf16 v[108:111], v[128:131], v[166:169], v[108:111]
	v_mfma_f32_16x16x32_bf16 v[104:107], v[136:139], v[166:169], v[104:107]
	v_mfma_f32_16x16x32_bf16 v[92:95], v[128:131], v[178:181], v[92:95]
	v_mfma_f32_16x16x32_bf16 v[88:91], v[136:139], v[178:181], v[88:91]
	v_mfma_f32_16x16x32_bf16 v[76:79], v[128:131], v[186:189], v[76:79]
	v_mfma_f32_16x16x32_bf16 v[72:75], v[136:139], v[186:189], v[72:75]
	v_mfma_f32_16x16x32_bf16 v[124:127], v[132:135], v[148:151], v[124:127]
	v_mfma_f32_16x16x32_bf16 v[120:123], v[140:143], v[148:151], v[120:123]
	v_mfma_f32_16x16x32_bf16 v[108:111], v[132:135], v[174:177], v[108:111]
	v_mfma_f32_16x16x32_bf16 v[104:107], v[140:143], v[174:177], v[104:107]
	v_mfma_f32_16x16x32_bf16 v[92:95], v[132:135], v[182:185], v[92:95]
	v_mfma_f32_16x16x32_bf16 v[88:91], v[140:143], v[182:185], v[88:91]
	v_mfma_f32_16x16x32_bf16 v[76:79], v[132:135], v[190:193], v[76:79]
	v_mfma_f32_16x16x32_bf16 v[72:75], v[140:143], v[190:193], v[72:75]
	v_mfma_f32_16x16x32_bf16 v[116:119], v[194:197], v[144:147], v[116:119]
	v_mfma_f32_16x16x32_bf16 v[112:115], v[202:205], v[144:147], v[112:115]
	v_mfma_f32_16x16x32_bf16 v[100:103], v[194:197], v[166:169], v[100:103]
	v_mfma_f32_16x16x32_bf16 v[96:99], v[202:205], v[166:169], v[96:99]
	v_mfma_f32_16x16x32_bf16 v[84:87], v[194:197], v[178:181], v[84:87]
	v_mfma_f32_16x16x32_bf16 v[80:83], v[202:205], v[178:181], v[80:83]
	v_mfma_f32_16x16x32_bf16 v[68:71], v[194:197], v[186:189], v[68:71]
	v_mfma_f32_16x16x32_bf16 v[64:67], v[202:205], v[186:189], v[64:67]
	v_mfma_f32_16x16x32_bf16 v[116:119], v[198:201], v[148:151], v[116:119]
	v_mfma_f32_16x16x32_bf16 v[112:115], v[206:209], v[148:151], v[112:115]
	v_mfma_f32_16x16x32_bf16 v[100:103], v[198:201], v[174:177], v[100:103]
	v_mfma_f32_16x16x32_bf16 v[96:99], v[206:209], v[174:177], v[96:99]
	v_mfma_f32_16x16x32_bf16 v[84:87], v[198:201], v[182:185], v[84:87]
	v_mfma_f32_16x16x32_bf16 v[80:83], v[206:209], v[182:185], v[80:83]
	v_mfma_f32_16x16x32_bf16 v[68:71], v[198:201], v[190:193], v[68:71]
	s_setprio 0
	v_mfma_f32_16x16x32_bf16 v[64:67], v[206:209], v[190:193], v[64:67]
	s_barrier
	s_mov_b32 m0, s39
	v_lshl_add_u64 v[210:211], s[14:15], 0, v[156:157]
	global_load_lds_dwordx4 v[210:211], off
	s_add_i32 m0, s39, 0x2000
	v_lshl_add_u64 v[210:211], s[14:15], 0, v[158:159]
	global_load_lds_dwordx4 v[210:211], off
	s_mov_b32 m0, s25
	v_lshl_add_u64 v[210:211], s[18:19], 0, v[156:157]
	global_load_lds_dwordx4 v[210:211], off
	s_mov_b32 m0, s26
	v_lshl_add_u64 v[210:211], s[18:19], 0, v[158:159]
	global_load_lds_dwordx4 v[210:211], off
	s_add_u32 s40, s14, 0x80000
	s_addc_u32 s41, s15, 0
	s_add_i32 s39, s42, s23
	s_mov_b32 m0, s39
	v_lshl_add_u64 v[210:211], s[40:41], 0, v[156:157]
	global_load_lds_dwordx4 v[210:211], off
	s_add_i32 m0, s39, 0x2000
	v_lshl_add_u64 v[210:211], s[40:41], 0, v[158:159]
	global_load_lds_dwordx4 v[210:211], off
	ds_read_b128 v[144:147], v172 offset:16384
	ds_read_b128 v[166:169], v172 offset:18432
	ds_read_b128 v[178:181], v172 offset:20480
	ds_read_b128 v[186:189], v172 offset:22528
	ds_read_b128 v[148:151], v172 offset:17408
	ds_read_b128 v[174:177], v172 offset:19456
	ds_read_b128 v[182:185], v172 offset:21504
	ds_read_b128 v[190:193], v172 offset:23552
	s_waitcnt vmcnt(6)
	s_waitcnt lgkmcnt(0)
	s_barrier
	v_mfma_f32_16x16x32_bf16 v[60:63], v[128:131], v[144:147], v[60:63]
	s_setprio 1
	v_mfma_f32_16x16x32_bf16 v[56:59], v[136:139], v[144:147], v[56:59]
	v_mfma_f32_16x16x32_bf16 v[44:47], v[128:131], v[166:169], v[44:47]
	v_mfma_f32_16x16x32_bf16 v[40:43], v[136:139], v[166:169], v[40:43]
	v_mfma_f32_16x16x32_bf16 v[28:31], v[128:131], v[178:181], v[28:31]
	v_mfma_f32_16x16x32_bf16 v[24:27], v[136:139], v[178:181], v[24:27]
	v_mfma_f32_16x16x32_bf16 v[12:15], v[128:131], v[186:189], v[12:15]
	v_mfma_f32_16x16x32_bf16 v[8:11], v[136:139], v[186:189], v[8:11]
	v_mfma_f32_16x16x32_bf16 v[60:63], v[132:135], v[148:151], v[60:63]
	v_mfma_f32_16x16x32_bf16 v[56:59], v[140:143], v[148:151], v[56:59]
	v_mfma_f32_16x16x32_bf16 v[44:47], v[132:135], v[174:177], v[44:47]
	v_mfma_f32_16x16x32_bf16 v[40:43], v[140:143], v[174:177], v[40:43]
	v_mfma_f32_16x16x32_bf16 v[28:31], v[132:135], v[182:185], v[28:31]
	v_mfma_f32_16x16x32_bf16 v[24:27], v[140:143], v[182:185], v[24:27]
	v_mfma_f32_16x16x32_bf16 v[12:15], v[132:135], v[190:193], v[12:15]
	v_mfma_f32_16x16x32_bf16 v[8:11], v[140:143], v[190:193], v[8:11]
	v_mfma_f32_16x16x32_bf16 v[52:55], v[194:197], v[144:147], v[52:55]
	v_mfma_f32_16x16x32_bf16 v[48:51], v[202:205], v[144:147], v[48:51]
	s_add_i32 s39, 0, 0x18000
	v_add_u32_e32 v140, s39, v170
	v_mfma_f32_16x16x32_bf16 v[36:39], v[194:197], v[166:169], v[36:39]
	v_mfma_f32_16x16x32_bf16 v[32:35], v[202:205], v[166:169], v[32:35]
	v_mfma_f32_16x16x32_bf16 v[20:23], v[194:197], v[178:181], v[20:23]
	v_mfma_f32_16x16x32_bf16 v[16:19], v[202:205], v[178:181], v[16:19]
	v_mfma_f32_16x16x32_bf16 v[4:7], v[194:197], v[186:189], v[4:7]
	v_mfma_f32_16x16x32_bf16 v[0:3], v[202:205], v[186:189], v[0:3]
	v_mfma_f32_16x16x32_bf16 v[52:55], v[198:201], v[148:151], v[52:55]
	v_mfma_f32_16x16x32_bf16 v[48:51], v[206:209], v[148:151], v[48:51]
	v_mfma_f32_16x16x32_bf16 v[36:39], v[198:201], v[174:177], v[36:39]
	v_mfma_f32_16x16x32_bf16 v[32:35], v[206:209], v[174:177], v[32:35]
	v_mfma_f32_16x16x32_bf16 v[20:23], v[198:201], v[182:185], v[20:23]
	v_mfma_f32_16x16x32_bf16 v[16:19], v[206:209], v[182:185], v[16:19]
	v_mfma_f32_16x16x32_bf16 v[4:7], v[198:201], v[190:193], v[4:7]
	s_setprio 0
	v_mfma_f32_16x16x32_bf16 v[0:3], v[206:209], v[190:193], v[0:3]
	s_barrier
; #define PG8_STAGE(bufoff, gbase, voff) do { _Pragma("unroll") for (int _i = 0; _i < 2; ++_i) \
;         __builtin_amdgcn_global_load_lds((const unsigned*)((const char*)(gbase) + (voff)[_i]), (LAS unsigned*)(lds + (bufoff) + ldsw + _i * 8192), 16, 0, 0); } while (0)
; #define PG8_LDA(dst, b, h) do { _Pragma("unroll") for (int m = 0; m < 4; ++m) _Pragma("unroll") for (int k = 0; k < 2; ++k) dst[m][k] = *(const LAS bf16x8*)(lds + PG8_SA(b, h) + aoff + m * 2048 + k * 1024); } while (0)
; #define PG8_WAIT_V(n) asm volatile("s_waitcnt vmcnt(" #n ")" ::: "memory")
; #define PG8_WAIT_L(n) asm volatile("s_waitcnt lgkmcnt(" #n ")" ::: "memory")
; template <class Epi>
; __device__ __forceinline__ void gemm_phase(LAS unsigned char* lds, const Gemm g, const StaticOrder& S, const Epi& E) {
;     ...
;         for (int t = 0; t < nt; t += 2) {
;             const bool last = (t == nt - 2);
;             const char* a1 = cA + (size_t)(t + 1) * kstep;
;             const char* a2 = last ? nA : cA + (size_t)(t + 2) * kstep; const char* b2 = last ? nB : cB + (size_t)(t + 2) * kstep;
;             const char* a3 = a2 + kstep; const char* b3 = b2 + kstep;
;             PG8_LDB(B0, 0, 0); PG8_SCHED; PG8_LDA(At, 0, 0); PG8_STAGE(PG8_SA(1, 1), a1 + hstepA, voffA);
;             PG8_WAIT_L(8); PG8_BAR; PG8_WAIT_L(0); PG8_MMA(0, 0, At, B0); PG8_BAR; PG8_SCHED;
;             PG8_LDB(B1, 0, 1); PG8_STAGE(PG8_SB(0, 0), b2, voffB);
;             PG8_BAR; PG8_WAIT_L(0); PG8_MMA(0, 1, At, B1); PG8_BAR;
;             PG8_LDA(At, 0, 1); PG8_STAGE(PG8_SA(0, 0), a2, voffA);
;             PG8_BAR; PG8_WAIT_L(0); PG8_MMA(1, 0, At, B0); PG8_BAR; PG8_SCHED;
;             PG8_STAGE(PG8_SB(0, 1), b2 + hstepB, voffB);
;             PG8_WAIT_V(6); PG8_BAR; PG8_MMA(1, 1, At, B1); PG8_BAR;
;             PG8_LDB(B0, 1, 0); PG8_SCHED; PG8_LDA(At, 1, 0); PG8_STAGE(PG8_SA(0, 1), a2 + hstepA, voffA);
;             PG8_WAIT_L(8); PG8_BAR; PG8_WAIT_L(0); PG8_MMA(0, 0, At, B0); PG8_BAR; PG8_SCHED;
;             PG8_LDB(B1, 1, 1); PG8_STAGE(PG8_SB(1, 0), b3, voffB);
;             PG8_BAR; PG8_WAIT_L(0); PG8_MMA(0, 1, At, B1); PG8_BAR;
;             PG8_LDA(At, 1, 1); PG8_STAGE(PG8_SA(1, 0), a3, voffA);
;             PG8_BAR; PG8_WAIT_L(0); PG8_MMA(1, 0, At, B0); PG8_BAR; PG8_SCHED;
;             PG8_STAGE(PG8_SB(1, 1), b3 + hstepB, voffB);
;             PG8_WAIT_V(6); PG8_BAR; PG8_MMA(1, 1, At, B1); PG8_BAR;
	s_add_u32 s18, s18, 0x80000
	s_addc_u32 s19, s19, 0
	s_mov_b32 m0, s27
	v_lshl_add_u64 v[194:195], s[18:19], 0, v[156:157]
	global_load_lds_dwordx4 v[194:195], off
	s_mov_b32 m0, s28
	v_lshl_add_u64 v[194:195], s[18:19], 0, v[158:159]
	global_load_lds_dwordx4 v[194:195], off
	ds_read_b128 v[128:131], v140
	ds_read_b128 v[136:139], v140 offset:2048
	ds_read_b128 v[132:135], v140 offset:1024
	ds_read_b128 v[140:143], v140 offset:3072
	ds_read_b128 v[144:147], v172 offset:32768
	ds_read_b128 v[166:169], v172 offset:34816
	ds_read_b128 v[178:181], v172 offset:36864
	ds_read_b128 v[186:189], v172 offset:38912
	ds_read_b128 v[148:151], v172 offset:33792
	ds_read_b128 v[174:177], v172 offset:35840
	ds_read_b128 v[182:185], v172 offset:37888
	ds_read_b128 v[190:193], v172 offset:39936
	s_mov_b32 s40, 0x1c000
	s_add_u32 s18, s14, 0x4000
	s_addc_u32 s19, s15, 0
	s_add_i32 s39, s39, s23
	v_add_u32_e32 v152, s40, v170
	ds_read_b128 v[194:197], v152
	ds_read_b128 v[202:205], v152 offset:2048
	ds_read_b128 v[198:201], v152 offset:1024
	ds_read_b128 v[206:209], v152 offset:3072
	s_waitcnt lgkmcnt(0)
	s_barrier
	v_mfma_f32_16x16x32_bf16 v[124:127], v[128:131], v[144:147], v[124:127]
	s_setprio 1
	v_mfma_f32_16x16x32_bf16 v[120:123], v[136:139], v[144:147], v[120:123]
	v_mfma_f32_16x16x32_bf16 v[108:111], v[128:131], v[166:169], v[108:111]
	v_mfma_f32_16x16x32_bf16 v[104:107], v[136:139], v[166:169], v[104:107]
	v_mfma_f32_16x16x32_bf16 v[92:95], v[128:131], v[178:181], v[92:95]
	v_mfma_f32_16x16x32_bf16 v[88:91], v[136:139], v[178:181], v[88:91]
	v_mfma_f32_16x16x32_bf16 v[76:79], v[128:131], v[186:189], v[76:79]
	v_mfma_f32_16x16x32_bf16 v[72:75], v[136:139], v[186:189], v[72:75]
	v_mfma_f32_16x16x32_bf16 v[124:127], v[132:135], v[148:151], v[124:127]
	v_mfma_f32_16x16x32_bf16 v[120:123], v[140:143], v[148:151], v[120:123]
	v_mfma_f32_16x16x32_bf16 v[108:111], v[132:135], v[174:177], v[108:111]
	v_mfma_f32_16x16x32_bf16 v[104:107], v[140:143], v[174:177], v[104:107]
	v_mfma_f32_16x16x32_bf16 v[92:95], v[132:135], v[182:185], v[92:95]
	v_mfma_f32_16x16x32_bf16 v[88:91], v[140:143], v[182:185], v[88:91]
	v_mfma_f32_16x16x32_bf16 v[76:79], v[132:135], v[190:193], v[76:79]
	v_mfma_f32_16x16x32_bf16 v[72:75], v[140:143], v[190:193], v[72:75]
	v_mfma_f32_16x16x32_bf16 v[116:119], v[194:197], v[144:147], v[116:119]
	v_mfma_f32_16x16x32_bf16 v[112:115], v[202:205], v[144:147], v[112:115]
	v_mfma_f32_16x16x32_bf16 v[100:103], v[194:197], v[166:169], v[100:103]
	v_mfma_f32_16x16x32_bf16 v[96:99], v[202:205], v[166:169], v[96:99]
	v_mfma_f32_16x16x32_bf16 v[84:87], v[194:197], v[178:181], v[84:87]
	v_mfma_f32_16x16x32_bf16 v[80:83], v[202:205], v[178:181], v[80:83]
	v_mfma_f32_16x16x32_bf16 v[68:71], v[194:197], v[186:189], v[68:71]
	v_mfma_f32_16x16x32_bf16 v[64:67], v[202:205], v[186:189], v[64:67]
	v_mfma_f32_16x16x32_bf16 v[116:119], v[198:201], v[148:151], v[116:119]
	v_mfma_f32_16x16x32_bf16 v[112:115], v[206:209], v[148:151], v[112:115]
	v_mfma_f32_16x16x32_bf16 v[100:103], v[198:201], v[174:177], v[100:103]
	v_mfma_f32_16x16x32_bf16 v[96:99], v[206:209], v[174:177], v[96:99]
	v_mfma_f32_16x16x32_bf16 v[84:87], v[198:201], v[182:185], v[84:87]
	v_mfma_f32_16x16x32_bf16 v[80:83], v[206:209], v[182:185], v[80:83]
	v_mfma_f32_16x16x32_bf16 v[68:71], v[198:201], v[190:193], v[68:71]
	s_setprio 0
	v_mfma_f32_16x16x32_bf16 v[64:67], v[206:209], v[190:193], v[64:67]
	s_barrier
	s_mov_b32 m0, s39
	v_lshl_add_u64 v[210:211], s[18:19], 0, v[156:157]
	global_load_lds_dwordx4 v[210:211], off
	s_add_i32 m0, s39, 0x2000
	v_lshl_add_u64 v[210:211], s[18:19], 0, v[158:159]
	global_load_lds_dwordx4 v[210:211], off
	s_mov_b32 m0, s29
	v_lshl_add_u64 v[210:211], s[16:17], 0, v[156:157]
	global_load_lds_dwordx4 v[210:211], off
	s_mov_b32 m0, s30
	v_lshl_add_u64 v[210:211], s[16:17], 0, v[158:159]
	global_load_lds_dwordx4 v[210:211], off
	s_add_u32 s14, s14, 0x84000
	s_addc_u32 s15, s15, 0
	s_add_i32 s16, s40, s23
	s_mov_b32 m0, s16
	v_lshl_add_u64 v[210:211], s[14:15], 0, v[156:157]
	global_load_lds_dwordx4 v[210:211], off
	s_add_i32 m0, s16, 0x2000
	v_lshl_add_u64 v[210:211], s[14:15], 0, v[158:159]
	global_load_lds_dwordx4 v[210:211], off
	ds_read_b128 v[144:147], v172 offset:49152
	ds_read_b128 v[166:169], v172 offset:51200
	ds_read_b128 v[178:181], v172 offset:53248
	ds_read_b128 v[186:189], v172 offset:55296
	ds_read_b128 v[148:151], v172 offset:50176
	ds_read_b128 v[174:177], v172 offset:52224
	ds_read_b128 v[182:185], v172 offset:54272
	ds_read_b128 v[190:193], v172 offset:56320
	s_waitcnt vmcnt(6)
	s_waitcnt lgkmcnt(0)
	s_barrier
	v_mfma_f32_16x16x32_bf16 v[60:63], v[128:131], v[144:147], v[60:63]
	s_setprio 1
	v_mfma_f32_16x16x32_bf16 v[56:59], v[136:139], v[144:147], v[56:59]
	v_mfma_f32_16x16x32_bf16 v[44:47], v[128:131], v[166:169], v[44:47]
	v_mfma_f32_16x16x32_bf16 v[40:43], v[136:139], v[166:169], v[40:43]
	v_mfma_f32_16x16x32_bf16 v[28:31], v[128:131], v[178:181], v[28:31]
	v_mfma_f32_16x16x32_bf16 v[24:27], v[136:139], v[178:181], v[24:27]
	v_mfma_f32_16x16x32_bf16 v[12:15], v[128:131], v[186:189], v[12:15]
	v_mfma_f32_16x16x32_bf16 v[8:11], v[136:139], v[186:189], v[8:11]
	v_mfma_f32_16x16x32_bf16 v[60:63], v[132:135], v[148:151], v[60:63]
	v_mfma_f32_16x16x32_bf16 v[56:59], v[140:143], v[148:151], v[56:59]
	v_mfma_f32_16x16x32_bf16 v[44:47], v[132:135], v[174:177], v[44:47]
	v_mfma_f32_16x16x32_bf16 v[40:43], v[140:143], v[174:177], v[40:43]
	v_mfma_f32_16x16x32_bf16 v[28:31], v[132:135], v[182:185], v[28:31]
	v_mfma_f32_16x16x32_bf16 v[24:27], v[140:143], v[182:185], v[24:27]
	v_mfma_f32_16x16x32_bf16 v[12:15], v[132:135], v[190:193], v[12:15]
	v_mfma_f32_16x16x32_bf16 v[8:11], v[140:143], v[190:193], v[8:11]
	v_mfma_f32_16x16x32_bf16 v[52:55], v[194:197], v[144:147], v[52:55]
	v_mfma_f32_16x16x32_bf16 v[48:51], v[202:205], v[144:147], v[48:51]
	s_add_i32 s38, s38, 2
	s_add_u32 s12, s12, 0x8000
	s_addc_u32 s13, s13, 0
	s_add_u32 s36, s36, 0x8000
	s_addc_u32 s37, s37, 0
	v_mfma_f32_16x16x32_bf16 v[36:39], v[194:197], v[166:169], v[36:39]
	v_mfma_f32_16x16x32_bf16 v[32:35], v[202:205], v[166:169], v[32:35]
	v_mfma_f32_16x16x32_bf16 v[20:23], v[194:197], v[178:181], v[20:23]
	v_mfma_f32_16x16x32_bf16 v[16:19], v[202:205], v[178:181], v[16:19]
	v_mfma_f32_16x16x32_bf16 v[4:7], v[194:197], v[186:189], v[4:7]
	v_mfma_f32_16x16x32_bf16 v[0:3], v[202:205], v[186:189], v[0:3]
	v_mfma_f32_16x16x32_bf16 v[52:55], v[198:201], v[148:151], v[52:55]
	v_mfma_f32_16x16x32_bf16 v[48:51], v[206:209], v[148:151], v[48:51]
	v_mfma_f32_16x16x32_bf16 v[36:39], v[198:201], v[174:177], v[36:39]
	v_mfma_f32_16x16x32_bf16 v[32:35], v[206:209], v[174:177], v[32:35]
	v_mfma_f32_16x16x32_bf16 v[20:23], v[198:201], v[182:185], v[20:23]
	v_mfma_f32_16x16x32_bf16 v[16:19], v[206:209], v[182:185], v[16:19]
	v_mfma_f32_16x16x32_bf16 v[4:7], v[198:201], v[190:193], v[4:7]
	s_cmp_gt_u32 s38, 29
	s_setprio 0
	v_mfma_f32_16x16x32_bf16 v[0:3], v[206:209], v[190:193], v[0:3]
	s_cbranch_scc0 .LBB0_247
; __device__ __forceinline__ unsigned cvt_pk_bf16(float lo, float hi) { unsigned r; asm volatile("v_cvt_pk_bf16_f32 %0, %1, %2" : "=v"(r) : "v"(lo), "v"(hi)); return r; }
;     __device__ __forceinline__ void operator()(const f32x4 (&acc)[2][2][4][2], const Unit& u, int wr, int wc, int fr, int fq) const {
;         const int row0 = u.pm * BM + wr * 64 + fr, j0 = wc * 16 + 4 * fq, colb = u.pn * BM + j0;
;         if (u.pn < 8) {
;     ...
;         } else {
; #pragma unroll
;             for (int ai = 0; ai < 2; ++ai)
; #pragma unroll
;                 for (int m = 0; m < 4; ++m) {
;                     const int row = row0 + ai * HALF + m * 16;
;                     bf16_t* rowp = O + (size_t)row * DIN + colb;
; #pragma unroll
;                     for (int bj = 0; bj < 2; ++bj) {
;                         const f32x4 o1 = acc[ai][bj][m][0], o2 = acc[ai][bj][m][1];
;                         u32x2 w1, w2; w1.x = cvt_pk_bf16(o1[0], o1[1]); w1.y = cvt_pk_bf16(o1[2], o1[3]); w2.x = cvt_pk_bf16(o2[0], o2[1]); w2.y = cvt_pk_bf16(o2[2], o2[3]);
;                         *(u32x2*)(rowp + bj * HALF) = w1; *(u32x2*)(rowp + bj * HALF + 64) = w2;
;                     }
;                 }
.Lrot_exit_247:
	s_barrier
.Lpeel_done_247:
	v_lshl_add_u32 v177, s10, 8, v165
	v_lshl_or_b32 v152, s34, 8, v171
	s_mov_b64 s[10:11], -1
	s_cmp_lt_i32 s34, 8
	v_or_b32_e32 v180, 16, v177
	v_or_b32_e32 v179, 32, v177
	v_or_b32_e32 v178, 48, v177
	v_add_u32_e32 v176, 0x80, v177
	v_add_u32_e32 v175, 0x90, v177
	v_add_u32_e32 v174, 0xa0, v177
	v_add_u32_e32 v173, 0xb0, v177
	s_cbranch_scc1 .LBB0_250
	v_readlane_b32 s10, v252, 57
	v_readlane_b32 s11, v252, 58
	s_movk_i32 s3, 0x3000
	v_lshlrev_b64 v[130:131], 1, v[152:153]
	v_mov_b64_e32 v[128:129], s[10:11]
	v_mad_i64_i32 v[132:133], s[10:11], v177, s3, v[128:129]
	v_lshl_add_u64 v[132:133], v[132:133], 0, v[130:131]
	v_cvt_pk_bf16_f32 v134, v124, v125
	v_cvt_pk_bf16_f32 v135, v126, v127
	v_cvt_pk_bf16_f32 v136, v120, v121
	v_cvt_pk_bf16_f32 v137, v122, v123
	global_store_dwordx2 v[132:133], v[134:135], off
	global_store_dwordx2 v[132:133], v[136:137], off offset:128
	v_cvt_pk_bf16_f32 v134, v116, v117
	v_cvt_pk_bf16_f32 v135, v118, v119
	v_cvt_pk_bf16_f32 v136, v112, v113
	v_cvt_pk_bf16_f32 v137, v114, v115
	global_store_dwordx2 v[132:133], v[134:135], off offset:256
	global_store_dwordx2 v[132:133], v[136:137], off offset:384
	v_mad_i64_i32 v[132:133], s[10:11], v180, s3, v[128:129]
	v_lshl_add_u64 v[132:133], v[132:133], 0, v[130:131]
	v_cvt_pk_bf16_f32 v134, v108, v109
	v_cvt_pk_bf16_f32 v135, v110, v111
	v_cvt_pk_bf16_f32 v136, v104, v105
	v_cvt_pk_bf16_f32 v137, v106, v107
	global_store_dwordx2 v[132:133], v[134:135], off
	global_store_dwordx2 v[132:133], v[136:137], off offset:128
	v_cvt_pk_bf16_f32 v134, v100, v101
	v_cvt_pk_bf16_f32 v135, v102, v103
	v_cvt_pk_bf16_f32 v136, v96, v97
	v_cvt_pk_bf16_f32 v137, v98, v99
	global_store_dwordx2 v[132:133], v[134:135], off offset:256
	global_store_dwordx2 v[132:133], v[136:137], off offset:384
	v_mad_i64_i32 v[132:133], s[10:11], v179, s3, v[128:129]
	v_lshl_add_u64 v[132:133], v[132:133], 0, v[130:131]
	v_cvt_pk_bf16_f32 v134, v92, v93
	v_cvt_pk_bf16_f32 v135, v94, v95
	v_cvt_pk_bf16_f32 v136, v88, v89
	v_cvt_pk_bf16_f32 v137, v90, v91
	global_store_dwordx2 v[132:133], v[134:135], off
	global_store_dwordx2 v[132:133], v[136:137], off offset:128
	v_cvt_pk_bf16_f32 v134, v84, v85
	v_cvt_pk_bf16_f32 v135, v86, v87
	v_cvt_pk_bf16_f32 v136, v80, v81
	v_cvt_pk_bf16_f32 v137, v82, v83
	global_store_dwordx2 v[132:133], v[134:135], off offset:256
	global_store_dwordx2 v[132:133], v[136:137], off offset:384
	v_mad_i64_i32 v[132:133], s[10:11], v178, s3, v[128:129]
	v_lshl_add_u64 v[132:133], v[132:133], 0, v[130:131]
	v_cvt_pk_bf16_f32 v134, v76, v77
	v_cvt_pk_bf16_f32 v135, v78, v79
	v_cvt_pk_bf16_f32 v136, v72, v73
	v_cvt_pk_bf16_f32 v137, v74, v75
	global_store_dwordx2 v[132:133], v[134:135], off
	global_store_dwordx2 v[132:133], v[136:137], off offset:128
	v_cvt_pk_bf16_f32 v134, v68, v69
	v_cvt_pk_bf16_f32 v135, v70, v71
	v_cvt_pk_bf16_f32 v136, v64, v65
	v_cvt_pk_bf16_f32 v137, v66, v67
	global_store_dwordx2 v[132:133], v[134:135], off offset:256
	global_store_dwordx2 v[132:133], v[136:137], off offset:384
	v_mad_i64_i32 v[132:133], s[10:11], v176, s3, v[128:129]
	v_lshl_add_u64 v[132:133], v[132:133], 0, v[130:131]
	v_cvt_pk_bf16_f32 v134, v60, v61
	v_cvt_pk_bf16_f32 v135, v62, v63
	v_cvt_pk_bf16_f32 v136, v56, v57
	v_cvt_pk_bf16_f32 v137, v58, v59
	global_store_dwordx2 v[132:133], v[134:135], off
	global_store_dwordx2 v[132:133], v[136:137], off offset:128
	v_cvt_pk_bf16_f32 v134, v52, v53
	v_cvt_pk_bf16_f32 v135, v54, v55
	v_cvt_pk_bf16_f32 v136, v48, v49
	v_cvt_pk_bf16_f32 v137, v50, v51
	global_store_dwordx2 v[132:133], v[134:135], off offset:256
	global_store_dwordx2 v[132:133], v[136:137], off offset:384
	v_mad_i64_i32 v[132:133], s[10:11], v175, s3, v[128:129]
	v_lshl_add_u64 v[132:133], v[132:133], 0, v[130:131]
	v_cvt_pk_bf16_f32 v134, v44, v45
	v_cvt_pk_bf16_f32 v135, v46, v47
	v_cvt_pk_bf16_f32 v136, v40, v41
	v_cvt_pk_bf16_f32 v137, v42, v43
	global_store_dwordx2 v[132:133], v[134:135], off
	global_store_dwordx2 v[132:133], v[136:137], off offset:128
	v_cvt_pk_bf16_f32 v134, v36, v37
	v_cvt_pk_bf16_f32 v135, v38, v39
	v_cvt_pk_bf16_f32 v136, v32, v33
	v_cvt_pk_bf16_f32 v137, v34, v35
	global_store_dwordx2 v[132:133], v[134:135], off offset:256
	global_store_dwordx2 v[132:133], v[136:137], off offset:384
	v_mad_i64_i32 v[132:133], s[10:11], v174, s3, v[128:129]
	v_lshl_add_u64 v[132:133], v[132:133], 0, v[130:131]
	v_cvt_pk_bf16_f32 v134, v28, v29
	v_cvt_pk_bf16_f32 v135, v30, v31
	v_cvt_pk_bf16_f32 v136, v24, v25
	v_cvt_pk_bf16_f32 v137, v26, v27
	global_store_dwordx2 v[132:133], v[134:135], off
	global_store_dwordx2 v[132:133], v[136:137], off offset:128
	v_cvt_pk_bf16_f32 v134, v20, v21
	v_cvt_pk_bf16_f32 v135, v22, v23
	v_mad_i64_i32 v[128:129], s[10:11], v173, s3, v[128:129]
	v_cvt_pk_bf16_f32 v136, v16, v17
	v_cvt_pk_bf16_f32 v137, v18, v19
	global_store_dwordx2 v[132:133], v[134:135], off offset:256
	global_store_dwordx2 v[132:133], v[136:137], off offset:384
	v_lshl_add_u64 v[128:129], v[128:129], 0, v[130:131]
	v_cvt_pk_bf16_f32 v130, v12, v13
	v_cvt_pk_bf16_f32 v131, v14, v15
	v_cvt_pk_bf16_f32 v132, v8, v9
	v_cvt_pk_bf16_f32 v133, v10, v11
	s_mov_b64 s[10:11], 0
	global_store_dwordx2 v[128:129], v[130:131], off
	global_store_dwordx2 v[128:129], v[132:133], off offset:128
	v_cvt_pk_bf16_f32 v130, v4, v5
	v_cvt_pk_bf16_f32 v131, v6, v7
	v_cvt_pk_bf16_f32 v132, v0, v1
	v_cvt_pk_bf16_f32 v133, v2, v3
